# 31 xor-32 shuffles in GEMM epilogues use v_permlane32_swap instead of ds_bpermute + LDS wait
# speedup vs baseline: 1.0099x; 1.0003x over previous
; __device__ __forceinline__ float xor16(float v) { return __int_as_float(__builtin_amdgcn_ds_swizzle(__float_as_int(v), 0x401F)); }
;   __device__ __forceinline__ void operator()(const f32x4 (&acc)[2][2][4][2], const g8::Unit& u, int ui, int wr, int wc, int fr, int fq) const {
;     ...
;         const int rl = 128 * ai + 64 * wr + 16 * m + fr;
;         float r = rsl[ui * 256 + rl];
;         if (gi >= 0) {
;           float ss = 0.f;
; #pragma unroll
;           for (int bj = 0; bj < 2; ++bj)
; #pragma unroll
;             for (int n = 0; n < 2; ++n)
; #pragma unroll
;               for (int j = 0; j < 4; ++j) ss += acc[ai][bj][m][n][j] * acc[ai][bj][m][n][j];
;           ss += xor16(ss);
;           ss += __shfl_xor(ss, 32);
;           r *= rsqrtf(ss * r * r * (1.f / 64.f) + EPS);
;         }
;         h16* rowp = P + (size_t)(u.pm * 256 + rl) * IWP + 64 * hs + 8 * fq;
.Lg1_nopre:
	s_waitcnt vmcnt(0)
	ds_read_b32 v140, v177
	s_xor_b64 s[14:15], s[26:27], -1
	s_and_b64 vcc, exec, s[14:15]
	s_cbranch_vccnz .LBB0_212
	v_mul_f32_e32 v141, v127, v127
	v_fmac_f32_e32 v141, v126, v126
	v_fmac_f32_e32 v141, v128, v128
	v_fmac_f32_e32 v141, v129, v129
	v_fmac_f32_e32 v141, v122, v122
	v_fmac_f32_e32 v141, v123, v123
	v_fmac_f32_e32 v141, v124, v124
	v_fmac_f32_e32 v141, v125, v125
	v_fmac_f32_e32 v141, v118, v118
	v_fmac_f32_e32 v141, v119, v119
	v_pk_mul_f32 v[152:153], v[120:121], v[120:121]
	v_pk_mul_f32 v[154:155], v[114:115], v[114:115]
	v_add_f32_e32 v141, v152, v141
	v_add_f32_e32 v141, v153, v141
	v_add_f32_e32 v141, v154, v141
	v_pk_mul_f32 v[152:153], v[116:117], v[116:117]
	v_add_f32_e32 v141, v155, v141
	v_add_f32_e32 v141, v152, v141
	v_add_f32_e32 v141, v153, v141
	v_mov_b32_e32 v152, v141
	s_nop 1
	v_permlane16_swap_b32_e32 v152, v141
	v_xor_b32_e32 v153, 32, v199
	s_waitcnt lgkmcnt(0)
	v_add_f32_e32 v141, v141, v152
	v_and_b32_e32 v152, 64, v199
	v_add_u32_e32 v152, 64, v152
	v_cmp_lt_i32_e32 vcc, v153, v152
	s_nop 1
	v_cndmask_b32_e32 v152, v199, v153, vcc
	v_lshlrev_b32_e32 v152, 2, v152
	v_mov_b32_e32 v152, v141
	s_nop 1
	v_permlane32_swap_b32_e32 v152, v141
	s_waitcnt lgkmcnt(0)
	v_add_f32_e32 v141, v141, v152
	v_mul_f32_e32 v141, v140, v141
	v_mul_f32_e32 v141, v140, v141
	v_fmamk_f32 v141, v141, 0x3c800000, v144
	v_mul_f32_e32 v152, 0x4b800000, v141
	v_cmp_gt_f32_e32 vcc, s75, v141
	s_nop 1
	v_cndmask_b32_e32 v141, v141, v152, vcc
	v_rsq_f32_e32 v141, v141
	s_nop 0
	v_mul_f32_e32 v152, 0x45800000, v141
	v_cndmask_b32_e32 v141, v141, v152, vcc
	v_mul_f32_e32 v140, v140, v141

; __device__ __forceinline__ float xor16(float v) { return __int_as_float(__builtin_amdgcn_ds_swizzle(__float_as_int(v), 0x401F)); }
; __device__ __forceinline__ float sigmoidf(float x) { return 1.f / (1.f + __expf(-x)); }
;   __device__ __forceinline__ void operator()(const f32x4 (&acc)[2][2][4][2], const g8::Unit& u, int ui, int wr, int wc, int fr, int fq) const {
;     ...
;         const int rl = 128 * ai + 64 * wr + 16 * m + fr;
;         float r = rsl[ui * 256 + rl];
;         if (gi >= 0) {
;           float ss = 0.f;
; #pragma unroll
;           for (int bj = 0; bj < 2; ++bj)
; #pragma unroll
;             for (int n = 0; n < 2; ++n)
; #pragma unroll
;               for (int j = 0; j < 4; ++j) ss += acc[ai][bj][m][n][j] * acc[ai][bj][m][n][j];
;           ss += xor16(ss);
;           ss += __shfl_xor(ss, 32);
;           r *= rsqrtf(ss * r * r * (1.f / 64.f) + EPS);
;         }
;         h16* rowp = P + (size_t)(u.pm * 256 + rl) * IWP + 64 * hs + 8 * fq;
; #pragma unroll
;         for (int bj = 0; bj < 2; ++bj) {
;           f32x4 v[2];
; #pragma unroll
;           for (int n = 0; n < 2; ++n) {
;             v[n] = acc[ai][bj][m][n] * r;
;             if (gi >= 0) {
;               const float4 g4 = *(const float4*)(qkg + gi * 64 + 32 * bj + 8 * fq + 4 * n);
;               v[n][0] *= g4.x; v[n][1] *= g4.y; v[n][2] *= g4.z; v[n][3] *= g4.w;
;             } else if (gate) {
; #pragma unroll
;               for (int j = 0; j < 4; ++j) v[n][j] = (32 * bj + 8 * fq + 4 * n + j) < 12 ? sigmoidf(v[n][j]) : 0.f;
;             }
;           }
;           *(h16x8*)(rowp + 32 * bj) = pack8(v[0], v[1]);
.LBB0_251:
	ds_read_b32 v114, v177 offset:64
	v_cndmask_b32_e64 v115, 0, 1, s[26:27]
	v_cvt_pk_f16_f32 v155, v124, v125
	v_cvt_pk_f16_f32 v154, v128, v129
	v_cvt_pk_f16_f32 v153, v118, v119
	v_cvt_pk_f16_f32 v152, v120, v121
	v_cmp_ne_u32_e64 s[14:15], 1, v115
	s_andn2_b64 vcc, exec, s[26:27]
	global_store_dwordx4 v[122:123], v[152:155], off offset:64
	s_cbranch_vccnz .LBB0_253
	v_mul_f32_e32 v115, v111, v111
	v_fmac_f32_e32 v115, v110, v110
	v_fmac_f32_e32 v115, v112, v112
	v_fmac_f32_e32 v115, v113, v113
	v_fmac_f32_e32 v115, v106, v106
	v_fmac_f32_e32 v115, v107, v107
	v_fmac_f32_e32 v115, v108, v108
	v_fmac_f32_e32 v115, v109, v109
	v_fmac_f32_e32 v115, v102, v102
	v_fmac_f32_e32 v115, v103, v103
	v_pk_mul_f32 v[116:117], v[104:105], v[104:105]
	v_pk_mul_f32 v[118:119], v[98:99], v[98:99]
	v_add_f32_e32 v115, v116, v115
	v_add_f32_e32 v115, v117, v115
	v_add_f32_e32 v115, v118, v115
	v_pk_mul_f32 v[116:117], v[100:101], v[100:101]
	v_add_f32_e32 v115, v119, v115
	v_add_f32_e32 v115, v116, v115
	v_add_f32_e32 v115, v117, v115
	v_mov_b32_e32 v116, v115
	s_nop 1
	v_permlane16_swap_b32_e32 v116, v115
	v_xor_b32_e32 v117, 32, v199
	s_waitcnt lgkmcnt(0)
	v_add_f32_e32 v115, v115, v116
	v_and_b32_e32 v116, 64, v199
	v_add_u32_e32 v116, 64, v116
	v_cmp_lt_i32_e32 vcc, v117, v116
	s_nop 1
	v_cndmask_b32_e32 v116, v199, v117, vcc
	v_lshlrev_b32_e32 v116, 2, v116
	v_mov_b32_e32 v116, v115
	s_nop 1
	v_permlane32_swap_b32_e32 v116, v115
	s_waitcnt lgkmcnt(0)
	v_add_f32_e32 v115, v115, v116
	v_mul_f32_e32 v115, v114, v115
	v_mul_f32_e32 v115, v114, v115
	v_fmamk_f32 v115, v115, 0x3c800000, v144
	v_mul_f32_e32 v116, 0x4b800000, v115
	v_cmp_gt_f32_e32 vcc, s75, v115
	s_nop 1
	v_cndmask_b32_e32 v115, v115, v116, vcc
	v_rsq_f32_e32 v115, v115
	s_nop 0
	v_mul_f32_e32 v116, 0x45800000, v115
	v_cndmask_b32_e32 v115, v115, v116, vcc
	v_mul_f32_e32 v114, v114, v115

; __device__ __forceinline__ float xor16(float v) { return __int_as_float(__builtin_amdgcn_ds_swizzle(__float_as_int(v), 0x401F)); }
; __device__ __forceinline__ float sigmoidf(float x) { return 1.f / (1.f + __expf(-x)); }
;   __device__ __forceinline__ void operator()(const f32x4 (&acc)[2][2][4][2], const g8::Unit& u, int ui, int wr, int wc, int fr, int fq) const {
;     ...
;         const int rl = 128 * ai + 64 * wr + 16 * m + fr;
;         float r = rsl[ui * 256 + rl];
;         if (gi >= 0) {
;           float ss = 0.f;
; #pragma unroll
;           for (int bj = 0; bj < 2; ++bj)
; #pragma unroll
;             for (int n = 0; n < 2; ++n)
; #pragma unroll
;               for (int j = 0; j < 4; ++j) ss += acc[ai][bj][m][n][j] * acc[ai][bj][m][n][j];
;           ss += xor16(ss);
;           ss += __shfl_xor(ss, 32);
;           r *= rsqrtf(ss * r * r * (1.f / 64.f) + EPS);
;         }
;         h16* rowp = P + (size_t)(u.pm * 256 + rl) * IWP + 64 * hs + 8 * fq;
; #pragma unroll
;         for (int bj = 0; bj < 2; ++bj) {
;           f32x4 v[2];
; #pragma unroll
;           for (int n = 0; n < 2; ++n) {
;             v[n] = acc[ai][bj][m][n] * r;
;             if (gi >= 0) {
;               const float4 g4 = *(const float4*)(qkg + gi * 64 + 32 * bj + 8 * fq + 4 * n);
;               v[n][0] *= g4.x; v[n][1] *= g4.y; v[n][2] *= g4.z; v[n][3] *= g4.w;
;             } else if (gate) {
; #pragma unroll
;               for (int j = 0; j < 4; ++j) v[n][j] = (32 * bj + 8 * fq + 4 * n + j) < 12 ? sigmoidf(v[n][j]) : 0.f;
;             }
;           }
;           *(h16x8*)(rowp + 32 * bj) = pack8(v[0], v[1]);
.LBB0_295:
	ds_read_b32 v98, v177 offset:128
	v_cvt_pk_f16_f32 v113, v108, v109
	v_cvt_pk_f16_f32 v112, v110, v111
	v_cvt_pk_f16_f32 v111, v102, v103
	v_cvt_pk_f16_f32 v110, v104, v105
	s_and_b64 vcc, exec, s[14:15]
	global_store_dwordx4 v[106:107], v[110:113], off offset:64
	s_cbranch_vccnz .LBB0_297
	v_mul_f32_e32 v99, v95, v95
	v_fmac_f32_e32 v99, v94, v94
	v_fmac_f32_e32 v99, v96, v96
	v_fmac_f32_e32 v99, v97, v97
	v_fmac_f32_e32 v99, v90, v90
	v_fmac_f32_e32 v99, v91, v91
	v_fmac_f32_e32 v99, v92, v92
	v_fmac_f32_e32 v99, v93, v93
	v_fmac_f32_e32 v99, v86, v86
	v_fmac_f32_e32 v99, v87, v87
	v_pk_mul_f32 v[100:101], v[88:89], v[88:89]
	v_pk_mul_f32 v[102:103], v[82:83], v[82:83]
	v_add_f32_e32 v99, v100, v99
	v_add_f32_e32 v99, v101, v99
	v_add_f32_e32 v99, v102, v99
	v_pk_mul_f32 v[100:101], v[84:85], v[84:85]
	v_add_f32_e32 v99, v103, v99
	v_add_f32_e32 v99, v100, v99
	v_add_f32_e32 v99, v101, v99
	v_mov_b32_e32 v100, v99
	s_nop 1
	v_permlane16_swap_b32_e32 v100, v99
	v_xor_b32_e32 v101, 32, v199
	s_waitcnt lgkmcnt(0)
	v_add_f32_e32 v99, v99, v100
	v_and_b32_e32 v100, 64, v199
	v_add_u32_e32 v100, 64, v100
	v_cmp_lt_i32_e32 vcc, v101, v100
	s_nop 1
	v_cndmask_b32_e32 v100, v199, v101, vcc
	v_lshlrev_b32_e32 v100, 2, v100
	v_mov_b32_e32 v100, v99
	s_nop 1
	v_permlane32_swap_b32_e32 v100, v99
	s_waitcnt lgkmcnt(0)
	v_add_f32_e32 v99, v99, v100
	v_mul_f32_e32 v99, v98, v99
	v_mul_f32_e32 v99, v98, v99
	v_fmamk_f32 v99, v99, 0x3c800000, v144
	v_mul_f32_e32 v100, 0x4b800000, v99
	v_cmp_gt_f32_e32 vcc, s75, v99
	s_nop 1
	v_cndmask_b32_e32 v99, v99, v100, vcc
	v_rsq_f32_e32 v99, v99
	s_nop 0
	v_mul_f32_e32 v100, 0x45800000, v99
	v_cndmask_b32_e32 v99, v99, v100, vcc
	v_mul_f32_e32 v98, v98, v99

; __device__ __forceinline__ float xor16(float v) { return __int_as_float(__builtin_amdgcn_ds_swizzle(__float_as_int(v), 0x401F)); }
; __device__ __forceinline__ float sigmoidf(float x) { return 1.f / (1.f + __expf(-x)); }
;   __device__ __forceinline__ void operator()(const f32x4 (&acc)[2][2][4][2], const g8::Unit& u, int ui, int wr, int wc, int fr, int fq) const {
;     ...
;         const int rl = 128 * ai + 64 * wr + 16 * m + fr;
;         float r = rsl[ui * 256 + rl];
;         if (gi >= 0) {
;           float ss = 0.f;
; #pragma unroll
;           for (int bj = 0; bj < 2; ++bj)
; #pragma unroll
;             for (int n = 0; n < 2; ++n)
; #pragma unroll
;               for (int j = 0; j < 4; ++j) ss += acc[ai][bj][m][n][j] * acc[ai][bj][m][n][j];
;           ss += xor16(ss);
;           ss += __shfl_xor(ss, 32);
;           r *= rsqrtf(ss * r * r * (1.f / 64.f) + EPS);
;         }
;         h16* rowp = P + (size_t)(u.pm * 256 + rl) * IWP + 64 * hs + 8 * fq;
; #pragma unroll
;         for (int bj = 0; bj < 2; ++bj) {
;           f32x4 v[2];
; #pragma unroll
;           for (int n = 0; n < 2; ++n) {
;             v[n] = acc[ai][bj][m][n] * r;
;             if (gi >= 0) {
;               const float4 g4 = *(const float4*)(qkg + gi * 64 + 32 * bj + 8 * fq + 4 * n);
;               v[n][0] *= g4.x; v[n][1] *= g4.y; v[n][2] *= g4.z; v[n][3] *= g4.w;
;             } else if (gate) {
; #pragma unroll
;               for (int j = 0; j < 4; ++j) v[n][j] = (32 * bj + 8 * fq + 4 * n + j) < 12 ? sigmoidf(v[n][j]) : 0.f;
;             }
;           }
;           *(h16x8*)(rowp + 32 * bj) = pack8(v[0], v[1]);
.LBB0_339:
	ds_read_b32 v82, v177 offset:192
	v_cvt_pk_f16_f32 v97, v92, v93
	v_cvt_pk_f16_f32 v96, v94, v95
	v_cvt_pk_f16_f32 v95, v86, v87
	v_cvt_pk_f16_f32 v94, v88, v89
	s_and_b64 vcc, exec, s[14:15]
	global_store_dwordx4 v[90:91], v[94:97], off offset:64
	s_cbranch_vccnz .LBB0_341
	v_mul_f32_e32 v83, v79, v79
	v_fmac_f32_e32 v83, v78, v78
	v_fmac_f32_e32 v83, v80, v80
	v_fmac_f32_e32 v83, v81, v81
	v_fmac_f32_e32 v83, v74, v74
	v_fmac_f32_e32 v83, v75, v75
	v_fmac_f32_e32 v83, v76, v76
	v_fmac_f32_e32 v83, v77, v77
	v_fmac_f32_e32 v83, v70, v70
	v_fmac_f32_e32 v83, v71, v71
	v_pk_mul_f32 v[84:85], v[72:73], v[72:73]
	v_pk_mul_f32 v[86:87], v[66:67], v[66:67]
	v_add_f32_e32 v83, v84, v83
	v_add_f32_e32 v83, v85, v83
	v_add_f32_e32 v83, v86, v83
	v_pk_mul_f32 v[84:85], v[68:69], v[68:69]
	v_add_f32_e32 v83, v87, v83
	v_add_f32_e32 v83, v84, v83
	v_add_f32_e32 v83, v85, v83
	v_mov_b32_e32 v84, v83
	s_nop 1
	v_permlane16_swap_b32_e32 v84, v83
	v_xor_b32_e32 v85, 32, v199
	s_waitcnt lgkmcnt(0)
	v_add_f32_e32 v83, v83, v84
	v_and_b32_e32 v84, 64, v199
	v_add_u32_e32 v84, 64, v84
	v_cmp_lt_i32_e32 vcc, v85, v84
	s_nop 1
	v_cndmask_b32_e32 v84, v199, v85, vcc
	v_lshlrev_b32_e32 v84, 2, v84
	v_mov_b32_e32 v84, v83
	s_nop 1
	v_permlane32_swap_b32_e32 v84, v83
	s_waitcnt lgkmcnt(0)
	v_add_f32_e32 v83, v83, v84
	v_mul_f32_e32 v83, v82, v83
	v_mul_f32_e32 v83, v82, v83
	v_fmamk_f32 v83, v83, 0x3c800000, v144
	v_mul_f32_e32 v84, 0x4b800000, v83
	v_cmp_gt_f32_e32 vcc, s75, v83
	s_nop 1
	v_cndmask_b32_e32 v83, v83, v84, vcc
	v_rsq_f32_e32 v83, v83
	s_nop 0
	v_mul_f32_e32 v84, 0x45800000, v83
	v_cndmask_b32_e32 v83, v83, v84, vcc
	v_mul_f32_e32 v82, v82, v83

; __device__ __forceinline__ float xor16(float v) { return __int_as_float(__builtin_amdgcn_ds_swizzle(__float_as_int(v), 0x401F)); }
; __device__ __forceinline__ float sigmoidf(float x) { return 1.f / (1.f + __expf(-x)); }
;   __device__ __forceinline__ void operator()(const f32x4 (&acc)[2][2][4][2], const g8::Unit& u, int ui, int wr, int wc, int fr, int fq) const {
;     ...
;         const int rl = 128 * ai + 64 * wr + 16 * m + fr;
;         float r = rsl[ui * 256 + rl];
;         if (gi >= 0) {
;           float ss = 0.f;
; #pragma unroll
;           for (int bj = 0; bj < 2; ++bj)
; #pragma unroll
;             for (int n = 0; n < 2; ++n)
; #pragma unroll
;               for (int j = 0; j < 4; ++j) ss += acc[ai][bj][m][n][j] * acc[ai][bj][m][n][j];
;           ss += xor16(ss);
;           ss += __shfl_xor(ss, 32);
;           r *= rsqrtf(ss * r * r * (1.f / 64.f) + EPS);
;         }
;         h16* rowp = P + (size_t)(u.pm * 256 + rl) * IWP + 64 * hs + 8 * fq;
; #pragma unroll
;         for (int bj = 0; bj < 2; ++bj) {
;           f32x4 v[2];
; #pragma unroll
;           for (int n = 0; n < 2; ++n) {
;             v[n] = acc[ai][bj][m][n] * r;
;             if (gi >= 0) {
;               const float4 g4 = *(const float4*)(qkg + gi * 64 + 32 * bj + 8 * fq + 4 * n);
;               v[n][0] *= g4.x; v[n][1] *= g4.y; v[n][2] *= g4.z; v[n][3] *= g4.w;
;             } else if (gate) {
; #pragma unroll
;               for (int j = 0; j < 4; ++j) v[n][j] = (32 * bj + 8 * fq + 4 * n + j) < 12 ? sigmoidf(v[n][j]) : 0.f;
;             }
;           }
;           *(h16x8*)(rowp + 32 * bj) = pack8(v[0], v[1]);
.LBB0_383:
	ds_read_b32 v66, v177 offset:512
	v_cvt_pk_f16_f32 v81, v76, v77
	v_cvt_pk_f16_f32 v80, v78, v79
	v_cvt_pk_f16_f32 v79, v70, v71
	v_cvt_pk_f16_f32 v78, v72, v73
	s_and_b64 vcc, exec, s[14:15]
	global_store_dwordx4 v[74:75], v[78:81], off offset:64
	s_cbranch_vccnz .LBB0_385
	v_mul_f32_e32 v67, v63, v63
	v_fmac_f32_e32 v67, v62, v62
	v_fmac_f32_e32 v67, v64, v64
	v_fmac_f32_e32 v67, v65, v65
	v_fmac_f32_e32 v67, v58, v58
	v_fmac_f32_e32 v67, v59, v59
	v_fmac_f32_e32 v67, v60, v60
	v_fmac_f32_e32 v67, v61, v61
	v_fmac_f32_e32 v67, v54, v54
	v_fmac_f32_e32 v67, v55, v55
	v_pk_mul_f32 v[68:69], v[56:57], v[56:57]
	v_pk_mul_f32 v[70:71], v[50:51], v[50:51]
	v_add_f32_e32 v67, v68, v67
	v_add_f32_e32 v67, v69, v67
	v_add_f32_e32 v67, v70, v67
	v_pk_mul_f32 v[68:69], v[52:53], v[52:53]
	v_add_f32_e32 v67, v71, v67
	v_add_f32_e32 v67, v68, v67
	v_add_f32_e32 v67, v69, v67
	v_mov_b32_e32 v68, v67
	s_nop 1
	v_permlane16_swap_b32_e32 v68, v67
	v_xor_b32_e32 v69, 32, v199
	s_waitcnt lgkmcnt(0)
	v_add_f32_e32 v67, v67, v68
	v_and_b32_e32 v68, 64, v199
	v_add_u32_e32 v68, 64, v68
	v_cmp_lt_i32_e32 vcc, v69, v68
	s_nop 1
	v_cndmask_b32_e32 v68, v199, v69, vcc
	v_lshlrev_b32_e32 v68, 2, v68
	v_mov_b32_e32 v68, v67
	s_nop 1
	v_permlane32_swap_b32_e32 v68, v67
	s_waitcnt lgkmcnt(0)
	v_add_f32_e32 v67, v67, v68
	v_mul_f32_e32 v67, v66, v67
	v_mul_f32_e32 v67, v66, v67
	v_fmamk_f32 v67, v67, 0x3c800000, v144
	v_mul_f32_e32 v68, 0x4b800000, v67
	v_cmp_gt_f32_e32 vcc, s75, v67
	s_nop 1
	v_cndmask_b32_e32 v67, v67, v68, vcc
	v_rsq_f32_e32 v67, v67
	s_nop 0
	v_mul_f32_e32 v68, 0x45800000, v67
	v_cndmask_b32_e32 v67, v67, v68, vcc
	v_mul_f32_e32 v66, v66, v67

; __device__ __forceinline__ float xor16(float v) { return __int_as_float(__builtin_amdgcn_ds_swizzle(__float_as_int(v), 0x401F)); }
; __device__ __forceinline__ float sigmoidf(float x) { return 1.f / (1.f + __expf(-x)); }
;   __device__ __forceinline__ void operator()(const f32x4 (&acc)[2][2][4][2], const g8::Unit& u, int ui, int wr, int wc, int fr, int fq) const {
;     ...
;         const int rl = 128 * ai + 64 * wr + 16 * m + fr;
;         float r = rsl[ui * 256 + rl];
;         if (gi >= 0) {
;           float ss = 0.f;
; #pragma unroll
;           for (int bj = 0; bj < 2; ++bj)
; #pragma unroll
;             for (int n = 0; n < 2; ++n)
; #pragma unroll
;               for (int j = 0; j < 4; ++j) ss += acc[ai][bj][m][n][j] * acc[ai][bj][m][n][j];
;           ss += xor16(ss);
;           ss += __shfl_xor(ss, 32);
;           r *= rsqrtf(ss * r * r * (1.f / 64.f) + EPS);
;         }
;         h16* rowp = P + (size_t)(u.pm * 256 + rl) * IWP + 64 * hs + 8 * fq;
; #pragma unroll
;         for (int bj = 0; bj < 2; ++bj) {
;           f32x4 v[2];
; #pragma unroll
;           for (int n = 0; n < 2; ++n) {
;             v[n] = acc[ai][bj][m][n] * r;
;             if (gi >= 0) {
;               const float4 g4 = *(const float4*)(qkg + gi * 64 + 32 * bj + 8 * fq + 4 * n);
;               v[n][0] *= g4.x; v[n][1] *= g4.y; v[n][2] *= g4.z; v[n][3] *= g4.w;
;             } else if (gate) {
; #pragma unroll
;               for (int j = 0; j < 4; ++j) v[n][j] = (32 * bj + 8 * fq + 4 * n + j) < 12 ? sigmoidf(v[n][j]) : 0.f;
;             }
;           }
;           *(h16x8*)(rowp + 32 * bj) = pack8(v[0], v[1]);
.LBB0_427:
	ds_read_b32 v50, v177 offset:576
	v_cvt_pk_f16_f32 v65, v60, v61
	v_cvt_pk_f16_f32 v64, v62, v63
	v_cvt_pk_f16_f32 v63, v54, v55
	v_cvt_pk_f16_f32 v62, v56, v57
	s_and_b64 vcc, exec, s[14:15]
	global_store_dwordx4 v[58:59], v[62:65], off offset:64
	s_cbranch_vccnz .LBB0_429
	v_mul_f32_e32 v51, v47, v47
	v_fmac_f32_e32 v51, v46, v46
	v_fmac_f32_e32 v51, v48, v48
	v_fmac_f32_e32 v51, v49, v49
	v_fmac_f32_e32 v51, v42, v42
	v_fmac_f32_e32 v51, v43, v43
	v_fmac_f32_e32 v51, v44, v44
	v_fmac_f32_e32 v51, v45, v45
	v_fmac_f32_e32 v51, v38, v38
	v_fmac_f32_e32 v51, v39, v39
	v_pk_mul_f32 v[52:53], v[40:41], v[40:41]
	v_pk_mul_f32 v[54:55], v[34:35], v[34:35]
	v_add_f32_e32 v51, v52, v51
	v_add_f32_e32 v51, v53, v51
	v_add_f32_e32 v51, v54, v51
	v_pk_mul_f32 v[52:53], v[36:37], v[36:37]
	v_add_f32_e32 v51, v55, v51
	v_add_f32_e32 v51, v52, v51
	v_add_f32_e32 v51, v53, v51
	v_mov_b32_e32 v52, v51
	s_nop 1
	v_permlane16_swap_b32_e32 v52, v51
	v_xor_b32_e32 v53, 32, v199
	s_waitcnt lgkmcnt(0)
	v_add_f32_e32 v51, v51, v52
	v_and_b32_e32 v52, 64, v199
	v_add_u32_e32 v52, 64, v52
	v_cmp_lt_i32_e32 vcc, v53, v52
	s_nop 1
	v_cndmask_b32_e32 v52, v199, v53, vcc
	v_lshlrev_b32_e32 v52, 2, v52
	v_mov_b32_e32 v52, v51
	s_nop 1
	v_permlane32_swap_b32_e32 v52, v51
	s_waitcnt lgkmcnt(0)
	v_add_f32_e32 v51, v51, v52
	v_mul_f32_e32 v51, v50, v51
	v_mul_f32_e32 v51, v50, v51
	v_fmamk_f32 v51, v51, 0x3c800000, v144
	v_mul_f32_e32 v52, 0x4b800000, v51
	v_cmp_gt_f32_e32 vcc, s75, v51
	s_nop 1
	v_cndmask_b32_e32 v51, v51, v52, vcc
	v_rsq_f32_e32 v51, v51
	s_nop 0
	v_mul_f32_e32 v52, 0x45800000, v51
	v_cndmask_b32_e32 v51, v51, v52, vcc
	v_mul_f32_e32 v50, v50, v51

; __device__ __forceinline__ float xor16(float v) { return __int_as_float(__builtin_amdgcn_ds_swizzle(__float_as_int(v), 0x401F)); }
; __device__ __forceinline__ float sigmoidf(float x) { return 1.f / (1.f + __expf(-x)); }
;   __device__ __forceinline__ void operator()(const f32x4 (&acc)[2][2][4][2], const g8::Unit& u, int ui, int wr, int wc, int fr, int fq) const {
;     ...
;         const int rl = 128 * ai + 64 * wr + 16 * m + fr;
;         float r = rsl[ui * 256 + rl];
;         if (gi >= 0) {
;           float ss = 0.f;
; #pragma unroll
;           for (int bj = 0; bj < 2; ++bj)
; #pragma unroll
;             for (int n = 0; n < 2; ++n)
; #pragma unroll
;               for (int j = 0; j < 4; ++j) ss += acc[ai][bj][m][n][j] * acc[ai][bj][m][n][j];
;           ss += xor16(ss);
;           ss += __shfl_xor(ss, 32);
;           r *= rsqrtf(ss * r * r * (1.f / 64.f) + EPS);
;         }
;         h16* rowp = P + (size_t)(u.pm * 256 + rl) * IWP + 64 * hs + 8 * fq;
; #pragma unroll
;         for (int bj = 0; bj < 2; ++bj) {
;           f32x4 v[2];
; #pragma unroll
;           for (int n = 0; n < 2; ++n) {
;             v[n] = acc[ai][bj][m][n] * r;
;             if (gi >= 0) {
;               const float4 g4 = *(const float4*)(qkg + gi * 64 + 32 * bj + 8 * fq + 4 * n);
;               v[n][0] *= g4.x; v[n][1] *= g4.y; v[n][2] *= g4.z; v[n][3] *= g4.w;
;             } else if (gate) {
; #pragma unroll
;               for (int j = 0; j < 4; ++j) v[n][j] = (32 * bj + 8 * fq + 4 * n + j) < 12 ? sigmoidf(v[n][j]) : 0.f;
;             }
;           }
;           *(h16x8*)(rowp + 32 * bj) = pack8(v[0], v[1]);
.LBB0_471:
	ds_read_b32 v34, v177 offset:640
	v_cvt_pk_f16_f32 v49, v44, v45
	v_cvt_pk_f16_f32 v48, v46, v47
	v_cvt_pk_f16_f32 v47, v38, v39
	v_cvt_pk_f16_f32 v46, v40, v41
	s_and_b64 vcc, exec, s[14:15]
	global_store_dwordx4 v[42:43], v[46:49], off offset:64
	s_cbranch_vccnz .LBB0_473
	v_mul_f32_e32 v35, v31, v31
	v_fmac_f32_e32 v35, v30, v30
	v_fmac_f32_e32 v35, v32, v32
	v_fmac_f32_e32 v35, v33, v33
	v_fmac_f32_e32 v35, v26, v26
	v_fmac_f32_e32 v35, v27, v27
	v_fmac_f32_e32 v35, v28, v28
	v_fmac_f32_e32 v35, v29, v29
	v_fmac_f32_e32 v35, v22, v22
	v_fmac_f32_e32 v35, v23, v23
	v_pk_mul_f32 v[36:37], v[24:25], v[24:25]
	v_pk_mul_f32 v[38:39], v[18:19], v[18:19]
	v_add_f32_e32 v35, v36, v35
	v_add_f32_e32 v35, v37, v35
	v_add_f32_e32 v35, v38, v35
	v_pk_mul_f32 v[36:37], v[20:21], v[20:21]
	v_add_f32_e32 v35, v39, v35
	v_add_f32_e32 v35, v36, v35
	v_add_f32_e32 v35, v37, v35
	v_mov_b32_e32 v36, v35
	s_nop 1
	v_permlane16_swap_b32_e32 v36, v35
	v_xor_b32_e32 v37, 32, v199
	s_waitcnt lgkmcnt(0)
	v_add_f32_e32 v35, v35, v36
	v_and_b32_e32 v36, 64, v199
	v_add_u32_e32 v36, 64, v36
	v_cmp_lt_i32_e32 vcc, v37, v36
	s_nop 1
	v_cndmask_b32_e32 v36, v199, v37, vcc
	v_lshlrev_b32_e32 v36, 2, v36
	v_mov_b32_e32 v36, v35
	s_nop 1
	v_permlane32_swap_b32_e32 v36, v35
	s_waitcnt lgkmcnt(0)
	v_add_f32_e32 v35, v35, v36
	v_mul_f32_e32 v35, v34, v35
	v_mul_f32_e32 v35, v34, v35
	v_fmamk_f32 v35, v35, 0x3c800000, v144
	v_mul_f32_e32 v36, 0x4b800000, v35
	v_cmp_gt_f32_e32 vcc, s75, v35
	s_nop 1
	v_cndmask_b32_e32 v35, v35, v36, vcc
	v_rsq_f32_e32 v35, v35
	s_nop 0
	v_mul_f32_e32 v36, 0x45800000, v35
	v_cndmask_b32_e32 v35, v35, v36, vcc
	v_mul_f32_e32 v34, v34, v35

; __device__ __forceinline__ float xor16(float v) { return __int_as_float(__builtin_amdgcn_ds_swizzle(__float_as_int(v), 0x401F)); }
; __device__ __forceinline__ float sigmoidf(float x) { return 1.f / (1.f + __expf(-x)); }
;   __device__ __forceinline__ void operator()(const f32x4 (&acc)[2][2][4][2], const g8::Unit& u, int ui, int wr, int wc, int fr, int fq) const {
;     ...
;         const int rl = 128 * ai + 64 * wr + 16 * m + fr;
;         float r = rsl[ui * 256 + rl];
;         if (gi >= 0) {
;           float ss = 0.f;
; #pragma unroll
;           for (int bj = 0; bj < 2; ++bj)
; #pragma unroll
;             for (int n = 0; n < 2; ++n)
; #pragma unroll
;               for (int j = 0; j < 4; ++j) ss += acc[ai][bj][m][n][j] * acc[ai][bj][m][n][j];
;           ss += xor16(ss);
;           ss += __shfl_xor(ss, 32);
;           r *= rsqrtf(ss * r * r * (1.f / 64.f) + EPS);
;         }
;         h16* rowp = P + (size_t)(u.pm * 256 + rl) * IWP + 64 * hs + 8 * fq;
; #pragma unroll
;         for (int bj = 0; bj < 2; ++bj) {
;           f32x4 v[2];
; #pragma unroll
;           for (int n = 0; n < 2; ++n) {
;             v[n] = acc[ai][bj][m][n] * r;
;             if (gi >= 0) {
;               const float4 g4 = *(const float4*)(qkg + gi * 64 + 32 * bj + 8 * fq + 4 * n);
;               v[n][0] *= g4.x; v[n][1] *= g4.y; v[n][2] *= g4.z; v[n][3] *= g4.w;
;             } else if (gate) {
; #pragma unroll
;               for (int j = 0; j < 4; ++j) v[n][j] = (32 * bj + 8 * fq + 4 * n + j) < 12 ? sigmoidf(v[n][j]) : 0.f;
;             }
;           }
;           *(h16x8*)(rowp + 32 * bj) = pack8(v[0], v[1]);
.LBB0_515:
	ds_read_b32 v18, v177 offset:704
	v_cvt_pk_f16_f32 v33, v28, v29
	v_cvt_pk_f16_f32 v32, v30, v31
	v_cvt_pk_f16_f32 v31, v22, v23
	v_cvt_pk_f16_f32 v30, v24, v25
	s_and_b64 vcc, exec, s[14:15]
	global_store_dwordx4 v[26:27], v[30:33], off offset:64
	s_cbranch_vccnz .LBB0_517
	v_mul_f32_e32 v19, v15, v15
	v_fmac_f32_e32 v19, v14, v14
	v_fmac_f32_e32 v19, v16, v16
	v_fmac_f32_e32 v19, v17, v17
	v_fmac_f32_e32 v19, v10, v10
	v_fmac_f32_e32 v19, v11, v11
	v_fmac_f32_e32 v19, v12, v12
	v_fmac_f32_e32 v19, v13, v13
	v_fmac_f32_e32 v19, v6, v6
	v_fmac_f32_e32 v19, v7, v7
	v_pk_mul_f32 v[20:21], v[8:9], v[8:9]
	v_pk_mul_f32 v[22:23], v[2:3], v[2:3]
	v_add_f32_e32 v19, v20, v19
	v_add_f32_e32 v19, v21, v19
	v_add_f32_e32 v19, v22, v19
	v_pk_mul_f32 v[20:21], v[4:5], v[4:5]
	v_add_f32_e32 v19, v23, v19
	v_add_f32_e32 v19, v20, v19
	v_add_f32_e32 v19, v21, v19
	v_mov_b32_e32 v20, v19
	s_nop 1
	v_permlane16_swap_b32_e32 v20, v19
	v_xor_b32_e32 v21, 32, v199
	s_waitcnt lgkmcnt(0)
	v_add_f32_e32 v19, v19, v20
	v_and_b32_e32 v20, 64, v199
	v_add_u32_e32 v20, 64, v20
	v_cmp_lt_i32_e32 vcc, v21, v20
	s_nop 1
	v_cndmask_b32_e32 v20, v199, v21, vcc
	v_lshlrev_b32_e32 v20, 2, v20
	v_mov_b32_e32 v20, v19
	s_nop 1
	v_permlane32_swap_b32_e32 v20, v19
	s_waitcnt lgkmcnt(0)
	v_add_f32_e32 v19, v19, v20
	v_mul_f32_e32 v19, v18, v19
	v_mul_f32_e32 v19, v18, v19
	v_fmamk_f32 v19, v19, 0x3c800000, v144
	v_mul_f32_e32 v20, 0x4b800000, v19
	v_cmp_gt_f32_e32 vcc, s75, v19
	s_nop 1
	v_cndmask_b32_e32 v19, v19, v20, vcc
	v_rsq_f32_e32 v19, v19
	s_nop 0
	v_mul_f32_e32 v20, 0x45800000, v19
	v_cndmask_b32_e32 v19, v19, v20, vcc
	v_mul_f32_e32 v18, v18, v19

; #define G8_STAGE(bufoff, gbase) do { _Pragma("unroll") for (int _i = 0; _i < 2; ++_i) \
;     __builtin_amdgcn_global_load_lds((const unsigned*)((const char*)(gbase) + voffA[_i]), (LAS unsigned*)(lds + (bufoff) + ldsw + _i * 8192), 16, 0, 0); } while (0)
; #define G8_LDA(dst, b, h) do { _Pragma("unroll") for (int m = 0; m < 4; ++m) _Pragma("unroll") for (int k = 0; k < 2; ++k) dst[m][k] = *(const LAS h16x8*)(lds + G8_SA(b, h) + aoff + m * 2048 + k * 1024); } while (0)
; #define G8_LDB(dst, b, h) do { _Pragma("unroll") for (int n = 0; n < 2; ++n) _Pragma("unroll") for (int k = 0; k < 2; ++k) dst[n][k] = *(const LAS h16x8*)(lds + G8_SB(b, h) + boff + n * 2048 + k * 1024); } while (0)
; #define G8_MMA(ai, bj, At, Bt_) do { __builtin_amdgcn_s_setprio(1); _Pragma("unroll") for (int m = 0; m < 4; ++m) _Pragma("unroll") for (int n = 0; n < 2; ++n) _Pragma("unroll") for (int k = 0; k < 2; ++k) \
;     acc[ai][bj][m][n] = __builtin_amdgcn_mfma_f32_16x16x32_f16(Bt_[n][k], At[m][k], acc[ai][bj][m][n], 0, 0, 0); __builtin_amdgcn_s_setprio(0); } while (0)
; #define G8_WAIT_L(n) asm volatile("s_waitcnt lgkmcnt(" #n ")" ::: "memory")
; #define G8_BAR __builtin_amdgcn_s_barrier()
; #define G8_SCHED __builtin_amdgcn_sched_barrier(0)
; template <class Epi>
; __device__ __forceinline__ void gemm_phase(LAS unsigned char* lds, const h16* A, const h16* Bt, int K, const Order& S, const Epi& E) {
;     ...
;     for (int t = 0; t < nt; t += 2) {
;       const bool last = (t == nt - 2);
;       const char* a1 = cA + (size_t)(t + 1) * kstep;
;       const char* a2 = last ? nA : cA + (size_t)(t + 2) * kstep;
;       const char* b2 = last ? nB : cB + (size_t)(t + 2) * kstep;
;       const char* a3 = a2 + kstep;
;       const char* b3 = b2 + kstep;
;       if (Epi::MID_T >= 0 && t == Epi::MID_T) E.mid(acc, ui, wr, fr);
;       G8_LDB(B0, 0, 0); G8_SCHED; G8_LDA(At, 0, 0); G8_STAGE(G8_SA(1, 1), a1 + hstep);
;       G8_WAIT_L(8); G8_BAR; G8_WAIT_L(0); G8_MMA(0, 0, At, B0); G8_BAR; G8_SCHED;
;       G8_LDB(B1, 0, 1); G8_STAGE(G8_SB(0, 0), b2);
;       G8_BAR; G8_WAIT_L(0); G8_MMA(0, 1, At, B1); G8_BAR;
;       G8_LDA(At, 0, 1); G8_STAGE(G8_SA(0, 0), a2);
;       G8_BAR; G8_WAIT_L(0); G8_MMA(1, 0, At, B0); G8_BAR; G8_SCHED;
.LBB0_2284:
	v_or_b32_e32 v34, 0x10000, v171
	v_add_u32_e32 v46, 0x10400, v171
	v_add_u32_e32 v50, 0x10800, v171
	v_add_u32_e32 v160, 0x10c00, v171
	ds_read_b128 v[34:37], v34
	ds_read_b128 v[46:49], v46
	ds_read_b128 v[50:53], v50
	ds_read_b128 v[160:163], v160
	s_add_u32 s26, s24, 0xfffe0080
	s_addc_u32 s27, s25, -1
	s_cmp_eq_u32 s55, 4
	s_cselect_b32 s29, s3, s27
	s_cselect_b32 s28, s17, s26
	s_cselect_b32 s27, s15, s54
	s_cselect_b32 s26, s23, s53
	v_lshl_add_u64 v[168:169], s[24:25], 0, v[156:157]
	s_add_i32 m0, s37, 0xc000
	ds_read_b128 v[164:167], v170
	ds_read_b128 v[174:177], v170 offset:1024
	ds_read_b128 v[178:181], v170 offset:2048
	ds_read_b128 v[182:185], v170 offset:3072
	ds_read_b128 v[186:189], v170 offset:4096
	ds_read_b128 v[202:205], v170 offset:5120
	ds_read_b128 v[206:209], v170 offset:6144
	ds_read_b128 v[210:213], v170 offset:7168
	global_load_lds_dwordx4 v[168:169], off
	v_lshl_add_u64 v[168:169], s[24:25], 0, v[158:159]
	s_add_i32 m0, s37, 0xe000
	s_nop 0
	global_load_lds_dwordx4 v[168:169], off
	s_waitcnt lgkmcnt(8)
	s_barrier
	s_waitcnt lgkmcnt(0)
	s_setprio 1
	s_waitcnt lgkmcnt(0)
	v_mfma_f32_16x16x32_f16 v[62:65], v[34:37], v[164:167], v[62:65]
	v_mfma_f32_16x16x32_f16 v[138:141], v[50:53], v[164:167], v[138:141]
	v_mfma_f32_16x16x32_f16 v[122:125], v[34:37], v[178:181], v[122:125]
	v_mfma_f32_16x16x32_f16 v[126:129], v[50:53], v[178:181], v[126:129]
	v_mfma_f32_16x16x32_f16 v[106:109], v[34:37], v[186:189], v[106:109]
	v_mfma_f32_16x16x32_f16 v[110:113], v[50:53], v[186:189], v[110:113]
	v_mfma_f32_16x16x32_f16 v[90:93], v[34:37], v[206:209], v[90:93]
	v_mfma_f32_16x16x32_f16 v[94:97], v[50:53], v[206:209], v[94:97]
	v_mfma_f32_16x16x32_f16 v[62:65], v[46:49], v[174:177], v[62:65]
	v_mfma_f32_16x16x32_f16 v[138:141], v[160:163], v[174:177], v[138:141]
	v_mfma_f32_16x16x32_f16 v[122:125], v[46:49], v[182:185], v[122:125]
	v_mfma_f32_16x16x32_f16 v[126:129], v[160:163], v[182:185], v[126:129]
	v_mfma_f32_16x16x32_f16 v[106:109], v[46:49], v[202:205], v[106:109]
	v_mfma_f32_16x16x32_f16 v[110:113], v[160:163], v[202:205], v[110:113]
	v_mfma_f32_16x16x32_f16 v[90:93], v[46:49], v[210:213], v[90:93]
	v_mfma_f32_16x16x32_f16 v[94:97], v[160:163], v[210:213], v[94:97]
	s_setprio 0
	s_barrier
	v_or_b32_e32 v168, 0x14000, v171
	v_add_u32_e32 v169, 0x14400, v171
	ds_read_b128 v[214:217], v168
	ds_read_b128 v[218:221], v169
	v_add_u32_e32 v168, 0x14800, v171
	v_add_u32_e32 v169, 0x14c00, v171
	s_mov_b32 m0, s38
	ds_read_b128 v[222:225], v168
	ds_read_b128 v[226:229], v169
	v_lshl_add_u64 v[168:169], s[26:27], 0, v[0:1]
	global_load_lds_dwordx4 v[168:169], off
	v_lshl_add_u64 v[230:231], s[26:27], 0, v[152:153]
	s_mov_b32 m0, s39
	s_nop 0
	global_load_lds_dwordx4 v[230:231], off
	s_barrier
	s_waitcnt lgkmcnt(0)
	s_setprio 1
	s_waitcnt lgkmcnt(0)
	v_mfma_f32_16x16x32_f16 v[130:133], v[214:217], v[164:167], v[130:133]
	v_mfma_f32_16x16x32_f16 v[134:137], v[222:225], v[164:167], v[134:137]
	v_mfma_f32_16x16x32_f16 v[114:117], v[214:217], v[178:181], v[114:117]
	v_mfma_f32_16x16x32_f16 v[118:121], v[222:225], v[178:181], v[118:121]
	v_mfma_f32_16x16x32_f16 v[98:101], v[214:217], v[186:189], v[98:101]
	v_mfma_f32_16x16x32_f16 v[102:105], v[222:225], v[186:189], v[102:105]
	v_mfma_f32_16x16x32_f16 v[82:85], v[214:217], v[206:209], v[82:85]
	v_mfma_f32_16x16x32_f16 v[86:89], v[222:225], v[206:209], v[86:89]
	v_mfma_f32_16x16x32_f16 v[130:133], v[218:221], v[174:177], v[130:133]
	v_mfma_f32_16x16x32_f16 v[134:137], v[226:229], v[174:177], v[134:137]
	v_mfma_f32_16x16x32_f16 v[114:117], v[218:221], v[182:185], v[114:117]
	v_mfma_f32_16x16x32_f16 v[118:121], v[226:229], v[182:185], v[118:121]
	v_mfma_f32_16x16x32_f16 v[98:101], v[218:221], v[202:205], v[98:101]
	v_mfma_f32_16x16x32_f16 v[102:105], v[226:229], v[202:205], v[102:105]
	v_mfma_f32_16x16x32_f16 v[82:85], v[218:221], v[210:213], v[82:85]
	v_mfma_f32_16x16x32_f16 v[86:89], v[226:229], v[210:213], v[86:89]
	s_setprio 0
	s_mov_b32 m0, s37
	v_lshl_add_u64 v[232:233], s[28:29], 0, v[0:1]
	s_barrier
	ds_read_b128 v[164:167], v170 offset:16384
	ds_read_b128 v[174:177], v170 offset:17408
	ds_read_b128 v[178:181], v170 offset:18432
	ds_read_b128 v[182:185], v170 offset:19456
	ds_read_b128 v[186:189], v170 offset:20480
	ds_read_b128 v[202:205], v170 offset:21504
	ds_read_b128 v[206:209], v170 offset:22528
	ds_read_b128 v[210:213], v170 offset:23552
	global_load_lds_dwordx4 v[232:233], off
	v_lshl_add_u64 v[234:235], s[28:29], 0, v[152:153]
	s_mov_b32 m0, s40
	s_nop 0
	global_load_lds_dwordx4 v[234:235], off
	s_barrier
	s_waitcnt lgkmcnt(0)
	s_setprio 1
	s_waitcnt lgkmcnt(0)
	v_mfma_f32_16x16x32_f16 v[74:77], v[34:37], v[164:167], v[74:77]
	v_mfma_f32_16x16x32_f16 v[78:81], v[50:53], v[164:167], v[78:81]
	v_mfma_f32_16x16x32_f16 v[54:57], v[34:37], v[178:181], v[54:57]
	v_mfma_f32_16x16x32_f16 v[58:61], v[50:53], v[178:181], v[58:61]
	v_mfma_f32_16x16x32_f16 v[26:29], v[34:37], v[186:189], v[26:29]
	v_mfma_f32_16x16x32_f16 v[30:33], v[50:53], v[186:189], v[30:33]
	v_mfma_f32_16x16x32_f16 v[10:13], v[34:37], v[206:209], v[10:13]
	v_mfma_f32_16x16x32_f16 v[14:17], v[50:53], v[206:209], v[14:17]
	v_mfma_f32_16x16x32_f16 v[74:77], v[46:49], v[174:177], v[74:77]
	v_mfma_f32_16x16x32_f16 v[78:81], v[160:163], v[174:177], v[78:81]
	v_mfma_f32_16x16x32_f16 v[54:57], v[46:49], v[182:185], v[54:57]
	v_mfma_f32_16x16x32_f16 v[58:61], v[160:163], v[182:185], v[58:61]
	v_mfma_f32_16x16x32_f16 v[26:29], v[46:49], v[202:205], v[26:29]
	v_mfma_f32_16x16x32_f16 v[30:33], v[160:163], v[202:205], v[30:33]
	v_mfma_f32_16x16x32_f16 v[10:13], v[46:49], v[210:213], v[10:13]
	v_mfma_f32_16x16x32_f16 v[14:17], v[160:163], v[210:213], v[14:17]
	s_setprio 0
	s_barrier
; #define G8_STAGE(bufoff, gbase) do { _Pragma("unroll") for (int _i = 0; _i < 2; ++_i) \
;     __builtin_amdgcn_global_load_lds((const unsigned*)((const char*)(gbase) + voffA[_i]), (LAS unsigned*)(lds + (bufoff) + ldsw + _i * 8192), 16, 0, 0); } while (0)
; #define G8_LDA(dst, b, h) do { _Pragma("unroll") for (int m = 0; m < 4; ++m) _Pragma("unroll") for (int k = 0; k < 2; ++k) dst[m][k] = *(const LAS h16x8*)(lds + G8_SA(b, h) + aoff + m * 2048 + k * 1024); } while (0)
; #define G8_LDB(dst, b, h) do { _Pragma("unroll") for (int n = 0; n < 2; ++n) _Pragma("unroll") for (int k = 0; k < 2; ++k) dst[n][k] = *(const LAS h16x8*)(lds + G8_SB(b, h) + boff + n * 2048 + k * 1024); } while (0)
; #define G8_MMA(ai, bj, At, Bt_) do { __builtin_amdgcn_s_setprio(1); _Pragma("unroll") for (int m = 0; m < 4; ++m) _Pragma("unroll") for (int n = 0; n < 2; ++n) _Pragma("unroll") for (int k = 0; k < 2; ++k) \
;     acc[ai][bj][m][n] = __builtin_amdgcn_mfma_f32_16x16x32_f16(Bt_[n][k], At[m][k], acc[ai][bj][m][n], 0, 0, 0); __builtin_amdgcn_s_setprio(0); } while (0)
; #define G8_WAIT_V(n) asm volatile("s_waitcnt vmcnt(" #n ")" ::: "memory")
; #define G8_WAIT_L(n) asm volatile("s_waitcnt lgkmcnt(" #n ")" ::: "memory")
; #define G8_BAR __builtin_amdgcn_s_barrier()
; #define G8_SCHED __builtin_amdgcn_sched_barrier(0)
; template <class Epi>
; __device__ __forceinline__ void gemm_phase(LAS unsigned char* lds, const h16* A, const h16* Bt, int K, const Order& S, const Epi& E) {
;     ...
;       G8_STAGE(G8_SB(0, 1), b2 + hstep);
;       G8_WAIT_V(6); G8_BAR; G8_MMA(1, 1, At, B1); G8_BAR;
;       G8_LDB(B0, 1, 0); G8_SCHED; G8_LDA(At, 1, 0); G8_STAGE(G8_SA(0, 1), a2 + hstep);
;       G8_WAIT_L(8); G8_BAR; G8_WAIT_L(0); G8_MMA(0, 0, At, B0); G8_BAR; G8_SCHED;
;       G8_LDB(B1, 1, 1); G8_STAGE(G8_SB(1, 0), b3);
;       G8_BAR; G8_WAIT_L(0); G8_MMA(0, 1, At, B1); G8_BAR;
;       G8_LDA(At, 1, 1); G8_STAGE(G8_SA(1, 0), a3);
;       G8_BAR; G8_WAIT_L(0); G8_MMA(1, 0, At, B0); G8_BAR; G8_SCHED;
;       G8_STAGE(G8_SB(1, 1), b3 + hstep);
;       G8_WAIT_V(6); G8_BAR; G8_MMA(1, 1, At, B1); G8_BAR;
	s_add_u32 s56, s26, 0x20000
	s_addc_u32 s57, s27, 0
	s_mov_b32 m0, s41
	v_lshl_add_u64 v[34:35], s[56:57], 0, v[0:1]
	global_load_lds_dwordx4 v[34:35], off
	v_lshl_add_u64 v[34:35], s[56:57], 0, v[152:153]
	s_mov_b32 m0, s42
	s_nop 0
	global_load_lds_dwordx4 v[34:35], off
	s_waitcnt vmcnt(6)
	s_barrier
	s_setprio 1
	v_mfma_f32_16x16x32_f16 v[38:41], v[214:217], v[178:181], v[38:41]
	v_mfma_f32_16x16x32_f16 v[42:45], v[222:225], v[178:181], v[42:45]
	v_mfma_f32_16x16x32_f16 v[18:21], v[214:217], v[186:189], v[18:21]
	v_mfma_f32_16x16x32_f16 v[22:25], v[222:225], v[186:189], v[22:25]
	v_mfma_f32_16x16x32_f16 v[2:5], v[214:217], v[206:209], v[2:5]
	v_mfma_f32_16x16x32_f16 v[6:9], v[222:225], v[206:209], v[6:9]
	v_mfma_f32_16x16x32_f16 v[34:37], v[214:217], v[164:167], v[66:69]
	v_mfma_f32_16x16x32_f16 v[46:49], v[222:225], v[164:167], v[70:73]
	v_mfma_f32_16x16x32_f16 v[38:41], v[218:221], v[182:185], v[38:41]
	v_mfma_f32_16x16x32_f16 v[42:45], v[226:229], v[182:185], v[42:45]
	v_mfma_f32_16x16x32_f16 v[18:21], v[218:221], v[202:205], v[18:21]
	v_mfma_f32_16x16x32_f16 v[22:25], v[226:229], v[202:205], v[22:25]
	v_mfma_f32_16x16x32_f16 v[2:5], v[218:221], v[210:213], v[2:5]
	v_mfma_f32_16x16x32_f16 v[6:9], v[226:229], v[210:213], v[6:9]
	v_mfma_f32_16x16x32_f16 v[34:37], v[218:221], v[174:177], v[34:37]
	v_mfma_f32_16x16x32_f16 v[46:49], v[226:229], v[174:177], v[46:49]
	s_setprio 0
	v_or_b32_e32 v50, 0x18000, v171
	v_add_u32_e32 v66, 0x18400, v171
	v_add_u32_e32 v70, 0x18800, v171
	v_add_u32_e32 v160, 0x18c00, v171
	s_barrier
	ds_read_b128 v[50:53], v50
	ds_read_b128 v[66:69], v66
	ds_read_b128 v[70:73], v70
	ds_read_b128 v[160:163], v160
	s_add_u32 s28, s28, 0x20000
	s_addc_u32 s29, s29, 0
	s_mov_b32 m0, s43
	v_lshl_add_u64 v[214:215], s[28:29], 0, v[0:1]
	ds_read_b128 v[164:167], v170 offset:32768
	ds_read_b128 v[174:177], v170 offset:33792
	ds_read_b128 v[178:181], v170 offset:34816
	ds_read_b128 v[182:185], v170 offset:35840
	ds_read_b128 v[186:189], v170 offset:36864
	ds_read_b128 v[202:205], v170 offset:37888
	ds_read_b128 v[206:209], v170 offset:38912
	ds_read_b128 v[210:213], v170 offset:39936
	global_load_lds_dwordx4 v[214:215], off
	v_lshl_add_u64 v[214:215], s[28:29], 0, v[152:153]
	s_mov_b32 m0, s44
	s_nop 0
	global_load_lds_dwordx4 v[214:215], off
	s_waitcnt lgkmcnt(8)
	s_barrier
	s_waitcnt lgkmcnt(0)
	s_setprio 1
	s_waitcnt lgkmcnt(0)
	v_mfma_f32_16x16x32_f16 v[62:65], v[50:53], v[164:167], v[62:65]
	v_mfma_f32_16x16x32_f16 v[138:141], v[70:73], v[164:167], v[138:141]
	v_mfma_f32_16x16x32_f16 v[122:125], v[50:53], v[178:181], v[122:125]
	v_mfma_f32_16x16x32_f16 v[126:129], v[70:73], v[178:181], v[126:129]
	v_mfma_f32_16x16x32_f16 v[106:109], v[50:53], v[186:189], v[106:109]
	v_mfma_f32_16x16x32_f16 v[110:113], v[70:73], v[186:189], v[110:113]
	v_mfma_f32_16x16x32_f16 v[90:93], v[50:53], v[206:209], v[90:93]
	v_mfma_f32_16x16x32_f16 v[94:97], v[70:73], v[206:209], v[94:97]
	v_mfma_f32_16x16x32_f16 v[62:65], v[66:69], v[174:177], v[62:65]
	v_mfma_f32_16x16x32_f16 v[138:141], v[160:163], v[174:177], v[138:141]
	v_mfma_f32_16x16x32_f16 v[122:125], v[66:69], v[182:185], v[122:125]
	v_mfma_f32_16x16x32_f16 v[126:129], v[160:163], v[182:185], v[126:129]
	v_mfma_f32_16x16x32_f16 v[106:109], v[66:69], v[202:205], v[106:109]
	v_mfma_f32_16x16x32_f16 v[110:113], v[160:163], v[202:205], v[110:113]
	v_mfma_f32_16x16x32_f16 v[90:93], v[66:69], v[210:213], v[90:93]
	v_mfma_f32_16x16x32_f16 v[94:97], v[160:163], v[210:213], v[94:97]
	s_setprio 0
	s_barrier
	v_or_b32_e32 v173, 0x1c000, v171
	s_mov_b32 m0, s46
	v_add_u32_e32 v195, 0x1c400, v171
	ds_read_b128 v[214:217], v173
	ds_read_b128 v[218:221], v195
	v_add_u32_e32 v173, 0x1c800, v171
	v_lshl_add_u64 v[168:169], v[168:169], 0, s[94:95]
	v_add_u32_e32 v195, 0x1cc00, v171
	ds_read_b128 v[222:225], v173
	ds_read_b128 v[226:229], v195
	global_load_lds_dwordx4 v[168:169], off
	v_lshl_add_u64 v[168:169], v[230:231], 0, s[94:95]
	s_mov_b32 m0, s47
	s_nop 0
	global_load_lds_dwordx4 v[168:169], off
	s_barrier
	s_waitcnt lgkmcnt(0)
	s_setprio 1
	s_waitcnt lgkmcnt(0)
	v_mfma_f32_16x16x32_f16 v[130:133], v[214:217], v[164:167], v[130:133]
	v_mfma_f32_16x16x32_f16 v[134:137], v[222:225], v[164:167], v[134:137]
	v_mfma_f32_16x16x32_f16 v[114:117], v[214:217], v[178:181], v[114:117]
	v_mfma_f32_16x16x32_f16 v[118:121], v[222:225], v[178:181], v[118:121]
	v_mfma_f32_16x16x32_f16 v[98:101], v[214:217], v[186:189], v[98:101]
	v_mfma_f32_16x16x32_f16 v[102:105], v[222:225], v[186:189], v[102:105]
	v_mfma_f32_16x16x32_f16 v[82:85], v[214:217], v[206:209], v[82:85]
	v_mfma_f32_16x16x32_f16 v[86:89], v[222:225], v[206:209], v[86:89]
	v_mfma_f32_16x16x32_f16 v[130:133], v[218:221], v[174:177], v[130:133]
	v_mfma_f32_16x16x32_f16 v[134:137], v[226:229], v[174:177], v[134:137]
	v_mfma_f32_16x16x32_f16 v[114:117], v[218:221], v[182:185], v[114:117]
	v_mfma_f32_16x16x32_f16 v[118:121], v[226:229], v[182:185], v[118:121]
	v_mfma_f32_16x16x32_f16 v[98:101], v[218:221], v[202:205], v[98:101]
	v_mfma_f32_16x16x32_f16 v[102:105], v[226:229], v[202:205], v[102:105]
	v_mfma_f32_16x16x32_f16 v[82:85], v[218:221], v[210:213], v[82:85]
	v_mfma_f32_16x16x32_f16 v[86:89], v[226:229], v[210:213], v[86:89]
	s_setprio 0
	s_mov_b32 m0, s48
	v_lshl_add_u64 v[168:169], v[232:233], 0, s[94:95]
	s_barrier
	ds_read_b128 v[164:167], v170 offset:49152
	ds_read_b128 v[174:177], v170 offset:50176
	ds_read_b128 v[178:181], v170 offset:51200
	ds_read_b128 v[182:185], v170 offset:52224
	ds_read_b128 v[186:189], v170 offset:53248
	ds_read_b128 v[202:205], v170 offset:54272
	ds_read_b128 v[206:209], v170 offset:55296
	ds_read_b128 v[210:213], v170 offset:56320
	global_load_lds_dwordx4 v[168:169], off
	v_lshl_add_u64 v[168:169], v[234:235], 0, s[94:95]
	s_mov_b32 m0, s49
	s_nop 0
	global_load_lds_dwordx4 v[168:169], off
	s_barrier
; __device__ __forceinline__ float sigmoidf(float x) { return 1.f / (1.f + __expf(-x)); }
; #define G8_MMA(ai, bj, At, Bt_) do { __builtin_amdgcn_s_setprio(1); _Pragma("unroll") for (int m = 0; m < 4; ++m) _Pragma("unroll") for (int n = 0; n < 2; ++n) _Pragma("unroll") for (int k = 0; k < 2; ++k) \
;     acc[ai][bj][m][n] = __builtin_amdgcn_mfma_f32_16x16x32_f16(Bt_[n][k], At[m][k], acc[ai][bj][m][n], 0, 0, 0); __builtin_amdgcn_s_setprio(0); } while (0)
; #define G8_WAIT_V(n) asm volatile("s_waitcnt vmcnt(" #n ")" ::: "memory")
; #define G8_BAR __builtin_amdgcn_s_barrier()
; template <class Epi>
; __device__ __forceinline__ void gemm_phase(LAS unsigned char* lds, const h16* A, const h16* Bt, int K, const Order& S, const Epi& E) {
;     ...
;       G8_WAIT_V(6); G8_BAR; G8_MMA(1, 1, At, B1); G8_BAR;
;     }
;   __device__ __forceinline__ void operator()(const f32x4 (&acc)[2][2][4][2], const g8::Unit& u, int ui, int wr, int wc, int fr, int fq) const {
;     const int ocb = 128 * u.pn + 16 * wc + 4 * fq;
;     float4 ba[2], bb[2];
; #pragma unroll
;     for (int bj = 0; bj < 2; ++bj) { ba[bj] = *(const float4*)(gb + ocb + 64 * bj); bb[bj] = *(const float4*)(gb + 512 + ocb + 64 * bj); }
; #pragma unroll
;     for (int ai = 0; ai < 2; ++ai)
; #pragma unroll
;       for (int m = 0; m < 4; ++m) {
;         const size_t row = (size_t)u.pm * 256 + 128 * ai + 64 * wr + 16 * m + fr;
;         float ss = 0.f;
; #pragma unroll
;         for (int bj = 0; bj < 2; ++bj) {
;           const f32x4 a = acc[ai][bj][m][0], b = acc[ai][bj][m][1];
;           float o0 = (a[0] + ba[bj].x) * sigmoidf(b[0] + bb[bj].x);
;           float o1 = (a[1] + ba[bj].y) * sigmoidf(b[1] + bb[bj].y);
;           float o2 = (a[2] + ba[bj].z) * sigmoidf(b[2] + bb[bj].z);
;           float o3 = (a[3] + ba[bj].w) * sigmoidf(b[3] + bb[bj].w);
	s_waitcnt lgkmcnt(0)
	s_setprio 1
	s_waitcnt lgkmcnt(0)
	v_mfma_f32_16x16x32_f16 v[74:77], v[50:53], v[164:167], v[74:77]
	v_mfma_f32_16x16x32_f16 v[78:81], v[70:73], v[164:167], v[78:81]
	v_mfma_f32_16x16x32_f16 v[54:57], v[50:53], v[178:181], v[54:57]
	v_mfma_f32_16x16x32_f16 v[58:61], v[70:73], v[178:181], v[58:61]
	v_mfma_f32_16x16x32_f16 v[26:29], v[50:53], v[186:189], v[26:29]
	v_mfma_f32_16x16x32_f16 v[30:33], v[70:73], v[186:189], v[30:33]
	v_mfma_f32_16x16x32_f16 v[10:13], v[50:53], v[206:209], v[10:13]
	v_mfma_f32_16x16x32_f16 v[14:17], v[70:73], v[206:209], v[14:17]
	v_mfma_f32_16x16x32_f16 v[74:77], v[66:69], v[174:177], v[74:77]
	v_mfma_f32_16x16x32_f16 v[78:81], v[160:163], v[174:177], v[78:81]
	v_mfma_f32_16x16x32_f16 v[54:57], v[66:69], v[182:185], v[54:57]
	v_mfma_f32_16x16x32_f16 v[58:61], v[160:163], v[182:185], v[58:61]
	v_mfma_f32_16x16x32_f16 v[26:29], v[66:69], v[202:205], v[26:29]
	v_mfma_f32_16x16x32_f16 v[30:33], v[160:163], v[202:205], v[30:33]
	v_mfma_f32_16x16x32_f16 v[10:13], v[66:69], v[210:213], v[10:13]
	v_mfma_f32_16x16x32_f16 v[14:17], v[160:163], v[210:213], v[14:17]
	s_setprio 0
	s_barrier
	s_add_u32 s26, s26, 0x20080
	s_addc_u32 s27, s27, 0
	s_mov_b32 m0, s50
	v_lshl_add_u64 v[50:51], s[26:27], 0, v[0:1]
	global_load_lds_dwordx4 v[50:51], off
	v_lshl_add_u64 v[50:51], s[26:27], 0, v[152:153]
	s_mov_b32 m0, s51
	s_nop 0
	global_load_lds_dwordx4 v[50:51], off
	s_waitcnt vmcnt(6)
	s_barrier
	s_setprio 1
	v_mfma_f32_16x16x32_f16 v[34:37], v[214:217], v[164:167], v[34:37]
	v_mfma_f32_16x16x32_f16 v[66:69], v[218:221], v[174:177], v[34:37]
	v_mfma_f32_16x16x32_f16 v[34:37], v[222:225], v[164:167], v[46:49]
	v_mfma_f32_16x16x32_f16 v[70:73], v[226:229], v[174:177], v[34:37]
	v_mfma_f32_16x16x32_f16 v[34:37], v[214:217], v[178:181], v[38:41]
	v_mfma_f32_16x16x32_f16 v[38:41], v[218:221], v[182:185], v[34:37]
	v_mfma_f32_16x16x32_f16 v[34:37], v[222:225], v[178:181], v[42:45]
	v_mfma_f32_16x16x32_f16 v[18:21], v[214:217], v[186:189], v[18:21]
	v_mfma_f32_16x16x32_f16 v[22:25], v[222:225], v[186:189], v[22:25]
	v_mfma_f32_16x16x32_f16 v[2:5], v[214:217], v[206:209], v[2:5]
	v_mfma_f32_16x16x32_f16 v[6:9], v[222:225], v[206:209], v[6:9]
	v_mfma_f32_16x16x32_f16 v[42:45], v[226:229], v[182:185], v[34:37]
	v_mfma_f32_16x16x32_f16 v[18:21], v[218:221], v[202:205], v[18:21]
	v_mfma_f32_16x16x32_f16 v[22:25], v[226:229], v[202:205], v[22:25]
	v_mfma_f32_16x16x32_f16 v[2:5], v[218:221], v[210:213], v[2:5]
	v_mfma_f32_16x16x32_f16 v[6:9], v[226:229], v[210:213], v[6:9]
	s_setprio 0
	s_add_i32 s55, s55, 2
	s_add_u32 s24, s24, 0x100
	s_addc_u32 s25, s25, 0
	s_add_u32 s53, s53, 0x100
	s_addc_u32 s54, s54, 0
	s_cmp_gt_u32 s55, 5
	s_barrier
	s_cbranch_scc0 .LBB0_2284
	v_lshl_or_b32 v160, s2, 7, v172
	v_ashrrev_i32_e32 v161, 31, v160
	v_lshl_add_u64 v[166:167], v[160:161], 2, s[12:13]
	global_load_dwordx4 v[46:49], v[166:167], off offset:2048
	global_load_dwordx4 v[34:37], v[166:167], off offset:2304
	v_and_b32_e32 v51, 64, v199
	v_xor_b32_e32 v50, 32, v199
	v_add_u32_e32 v51, 64, v51
	v_cmp_lt_i32_e32 vcc, v50, v51
	s_ashr_i32 s23, s22, 31
	s_lshl_b64 s[22:23], s[22:23], 8
	v_cndmask_b32_e32 v50, v199, v50, vcc
	v_lshlrev_b32_e32 v173, 2, v50
	v_lshl_add_u64 v[162:163], s[22:23], 0, v[154:155]
	s_lshl_b32 s22, s2, 2
	v_lshlrev_b64 v[164:165], 11, v[162:163]
	s_ashr_i32 s23, s22, 31
	s_waitcnt vmcnt(0)
	v_add_f32_e32 v50, v138, v46
	v_mul_f32_e32 v50, 0xbfb8aa3b, v50
	v_exp_f32_e32 v138, v50
	global_load_dwordx4 v[50:53], v[166:167], off
	v_add_f32_e32 v139, v139, v47
	v_mul_f32_e32 v139, 0xbfb8aa3b, v139
	v_exp_f32_e32 v139, v139
	v_add_f32_e32 v140, v140, v48
	v_add_f32_e32 v141, v141, v49
	v_mul_f32_e32 v140, 0xbfb8aa3b, v140
	v_pk_add_f32 v[138:139], v[138:139], 1.0 op_sel_hi:[1,0]
	v_mul_f32_e32 v141, 0xbfb8aa3b, v141
	v_div_scale_f32 v168, s[2:3], v139, v139, 1.0
	v_rcp_f32_e32 v169, v168
	v_exp_f32_e32 v140, v140
	v_exp_f32_e32 v141, v141
	v_add_f32_e32 v135, v135, v35
	v_fma_f32 v174, -v168, v169, 1.0
	v_fmac_f32_e32 v169, v174, v169
	v_div_scale_f32 v174, vcc, 1.0, v139, 1.0
	v_mul_f32_e32 v175, v174, v169
	v_fma_f32 v176, -v168, v175, v174
	v_fmac_f32_e32 v175, v176, v169
	v_fma_f32 v168, -v168, v175, v174
	v_div_fmas_f32 v168, v168, v169, v175
	v_div_fixup_f32 v139, v168, v139, 1.0
	v_div_scale_f32 v168, s[2:3], v138, v138, 1.0
	v_rcp_f32_e32 v169, v168
	v_mul_f32_e32 v135, 0xbfb8aa3b, v135
	v_exp_f32_e32 v135, v135
	v_add_f32_e32 v136, v136, v36
	v_fma_f32 v174, -v168, v169, 1.0
	v_fmac_f32_e32 v169, v174, v169
	v_div_scale_f32 v174, vcc, 1.0, v138, 1.0
	v_mul_f32_e32 v175, v174, v169
	v_fma_f32 v176, -v168, v175, v174
	v_fmac_f32_e32 v175, v176, v169
	v_fma_f32 v168, -v168, v175, v174
	v_div_fmas_f32 v168, v168, v169, v175
	v_div_fixup_f32 v138, v168, v138, 1.0
	v_add_f32_e32 v137, v137, v37
	v_mul_f32_e32 v136, 0xbfb8aa3b, v136
	v_mul_f32_e32 v137, 0xbfb8aa3b, v137
	v_exp_f32_e32 v136, v136
	v_exp_f32_e32 v137, v137
	s_waitcnt vmcnt(0)
; __device__ __forceinline__ float xor16(float v) { return __int_as_float(__builtin_amdgcn_ds_swizzle(__float_as_int(v), 0x401F)); }
; __device__ __forceinline__ float sigmoidf(float x) { return 1.f / (1.f + __expf(-x)); }
;   __device__ __forceinline__ void operator()(const f32x4 (&acc)[2][2][4][2], const g8::Unit& u, int ui, int wr, int wc, int fr, int fq) const {
;     ...
;         for (int bj = 0; bj < 2; ++bj) {
;           const f32x4 a = acc[ai][bj][m][0], b = acc[ai][bj][m][1];
;           float o0 = (a[0] + ba[bj].x) * sigmoidf(b[0] + bb[bj].x);
;           float o1 = (a[1] + ba[bj].y) * sigmoidf(b[1] + bb[bj].y);
;           float o2 = (a[2] + ba[bj].z) * sigmoidf(b[2] + bb[bj].z);
;           float o3 = (a[3] + ba[bj].w) * sigmoidf(b[3] + bb[bj].w);
;           *(h16x4*)(OB + row * 1024 + ocb + 64 * bj) = pack4(o0, o1, o2, o3);
;           ss += o0 * o0 + o1 * o1 + o2 * o2 + o3 * o3;
;         }
;         ss += xor16(ss);
;         ss += __shfl_xor(ss, 32);
;         if (fq == 0) ssqb[row * 16 + u.pn * 4 + wc] = ss;
	v_pk_add_f32 v[62:63], v[62:63], v[50:51]
	s_nop 0
	v_pk_mul_f32 v[62:63], v[62:63], v[138:139]
	v_pk_add_f32 v[138:139], v[140:141], 1.0 op_sel_hi:[1,0]
	v_cvt_pk_f16_f32 v168, v62, v63
	v_div_scale_f32 v140, s[2:3], v139, v139, 1.0
	v_rcp_f32_e32 v141, v140
	v_pk_add_f32 v[64:65], v[64:65], v[52:53]
	v_pk_add_f32 v[136:137], v[136:137], 1.0 op_sel_hi:[1,0]
	v_fma_f32 v169, -v140, v141, 1.0
	v_fmac_f32_e32 v141, v169, v141
	v_div_scale_f32 v169, vcc, 1.0, v139, 1.0
	v_mul_f32_e32 v174, v169, v141
	v_fma_f32 v175, -v140, v174, v169
	v_fmac_f32_e32 v174, v175, v141
	v_fma_f32 v140, -v140, v174, v169
	v_div_fmas_f32 v140, v140, v141, v174
	v_div_fixup_f32 v139, v140, v139, 1.0
	v_div_scale_f32 v140, s[2:3], v138, v138, 1.0
	v_rcp_f32_e32 v141, v140
	s_nop 0
	v_fma_f32 v169, -v140, v141, 1.0
	v_fmac_f32_e32 v141, v169, v141
	v_div_scale_f32 v169, vcc, 1.0, v138, 1.0
	v_mul_f32_e32 v174, v169, v141
	v_fma_f32 v175, -v140, v174, v169
	v_fmac_f32_e32 v174, v175, v141
	v_fma_f32 v140, -v140, v174, v169
	v_div_fmas_f32 v140, v140, v141, v174
	v_div_fixup_f32 v138, v140, v138, 1.0
	v_pk_mul_f32 v[140:141], v[62:63], v[62:63]
	v_add_f32_e32 v62, v134, v34
	v_pk_mul_f32 v[64:65], v[64:65], v[138:139]
	v_lshl_add_u64 v[138:139], s[0:1], 0, v[164:165]
	v_mul_f32_e32 v62, 0xbfb8aa3b, v62
	v_cvt_pk_f16_f32 v169, v64, v65
	v_lshl_add_u64 v[164:165], v[160:161], 1, v[138:139]
	v_pk_mul_f32 v[138:139], v[64:65], v[64:65]
	v_exp_f32_e32 v134, v62
	global_load_dwordx4 v[62:65], v[166:167], off offset:256
	v_pk_add_f32 v[134:135], v[134:135], 1.0 op_sel_hi:[1,0]
	s_nop 0
	v_div_scale_f32 v166, s[2:3], v135, v135, 1.0
	v_rcp_f32_e32 v167, v166
	global_store_dwordx2 v[164:165], v[168:169], off
	v_fma_f32 v168, -v166, v167, 1.0
	v_fmac_f32_e32 v167, v168, v167
	v_div_scale_f32 v168, vcc, 1.0, v135, 1.0
	v_mul_f32_e32 v169, v168, v167
	v_fma_f32 v174, -v166, v169, v168
	v_fmac_f32_e32 v169, v174, v167
	v_fma_f32 v166, -v166, v169, v168
	v_div_fmas_f32 v166, v166, v167, v169
	v_div_fixup_f32 v135, v166, v135, 1.0
	v_div_scale_f32 v166, s[2:3], v134, v134, 1.0
	v_rcp_f32_e32 v167, v166
	s_waitcnt vmcnt(0)
	v_pk_add_f32 v[130:131], v[130:131], v[62:63]
	v_fma_f32 v168, -v166, v167, 1.0
	v_fmac_f32_e32 v167, v168, v167
	v_div_scale_f32 v168, vcc, 1.0, v134, 1.0
	v_mul_f32_e32 v169, v168, v167
	v_fma_f32 v174, -v166, v169, v168
	v_fmac_f32_e32 v169, v174, v167
	v_fma_f32 v166, -v166, v169, v168
	v_div_fmas_f32 v166, v166, v167, v169
	v_div_fixup_f32 v134, v166, v134, 1.0
	v_pk_mul_f32 v[130:131], v[130:131], v[134:135]
	v_div_scale_f32 v135, s[2:3], v137, v137, 1.0
	v_rcp_f32_e32 v166, v135
	v_pk_add_f32 v[132:133], v[132:133], v[64:65]
	v_cvt_pk_f16_f32 v134, v130, v131
	v_pk_mul_f32 v[130:131], v[130:131], v[130:131]
	v_fma_f32 v167, -v135, v166, 1.0
	v_fmac_f32_e32 v166, v167, v166
	v_div_scale_f32 v167, vcc, 1.0, v137, 1.0
	v_mul_f32_e32 v168, v167, v166
	v_fma_f32 v169, -v135, v168, v167
	v_fmac_f32_e32 v168, v169, v166
	v_fma_f32 v135, -v135, v168, v167
	v_div_fmas_f32 v135, v135, v166, v168
	v_div_fixup_f32 v137, v135, v137, 1.0
	v_div_scale_f32 v135, s[2:3], v136, v136, 1.0
	v_rcp_f32_e32 v166, v135
	v_add_f32_e32 v130, v130, v131
	v_add_f32_e32 v131, v140, v141
	v_add_f32_e32 v131, v138, v131
	v_fma_f32 v167, -v135, v166, 1.0
	v_fmac_f32_e32 v166, v167, v166
	v_div_scale_f32 v167, vcc, 1.0, v136, 1.0
	v_mul_f32_e32 v168, v167, v166
	v_fma_f32 v169, -v135, v168, v167
	v_fmac_f32_e32 v168, v169, v166
	v_fma_f32 v135, -v135, v168, v167
	v_div_fmas_f32 v135, v135, v166, v168
	v_div_fixup_f32 v136, v135, v136, 1.0
	v_pk_mul_f32 v[132:133], v[132:133], v[136:137]
	v_add_f32_e32 v131, v139, v131
	v_cvt_pk_f16_f32 v135, v132, v133
	v_pk_mul_f32 v[132:133], v[132:133], v[132:133]
	global_store_dwordx2 v[164:165], v[134:135], off offset:128
	v_add_f32_e32 v130, v132, v130
	v_add_f32_e32 v130, v133, v130
	v_add_f32_e32 v130, v131, v130
	v_mov_b32_e32 v131, v130
	s_nop 1
	v_permlane16_swap_b32_e32 v131, v130
	s_waitcnt lgkmcnt(0)
	v_add_f32_e32 v130, v130, v131
	v_mov_b32_e32 v131, v130
	s_nop 1
	v_permlane32_swap_b32_e32 v131, v130
	s_and_saveexec_b64 s[24:25], s[6:7]
	s_cbranch_execz .LBB0_2287
	s_waitcnt lgkmcnt(0)
	v_add_f32_e32 v132, v130, v131
	v_lshlrev_b64 v[130:131], 6, v[162:163]
	v_lshl_add_u64 v[130:131], s[10:11], 0, v[130:131]
	v_lshl_add_u64 v[130:131], s[22:23], 2, v[130:131]
	s_lshl_b32 s92, s45, 2
	v_lshl_add_u64 v[130:131], v[130:131], 0, s[92:93]
	global_store_dword v[130:131], v132, off
; __device__ __forceinline__ float xor16(float v) { return __int_as_float(__builtin_amdgcn_ds_swizzle(__float_as_int(v), 0x401F)); }
; __device__ __forceinline__ float sigmoidf(float x) { return 1.f / (1.f + __expf(-x)); }
;   __device__ __forceinline__ void operator()(const f32x4 (&acc)[2][2][4][2], const g8::Unit& u, int ui, int wr, int wc, int fr, int fq) const {
;     ...
;         for (int bj = 0; bj < 2; ++bj) {
;           const f32x4 a = acc[ai][bj][m][0], b = acc[ai][bj][m][1];
;           float o0 = (a[0] + ba[bj].x) * sigmoidf(b[0] + bb[bj].x);
;           float o1 = (a[1] + ba[bj].y) * sigmoidf(b[1] + bb[bj].y);
;           float o2 = (a[2] + ba[bj].z) * sigmoidf(b[2] + bb[bj].z);
;           float o3 = (a[3] + ba[bj].w) * sigmoidf(b[3] + bb[bj].w);
;           *(h16x4*)(OB + row * 1024 + ocb + 64 * bj) = pack4(o0, o1, o2, o3);
;           ss += o0 * o0 + o1 * o1 + o2 * o2 + o3 * o3;
;         }
;         ss += xor16(ss);
;         ss += __shfl_xor(ss, 32);
;         if (fq == 0) ssqb[row * 16 + u.pn * 4 + wc] = ss;
.LBB0_2287:
	s_or_b64 exec, exec, s[24:25]
	v_add_f32_e32 v126, v126, v46
	v_add_f32_e32 v127, v127, v47
	v_mul_f32_e32 v126, 0xbfb8aa3b, v126
	v_mul_f32_e32 v127, 0xbfb8aa3b, v127
	v_exp_f32_e32 v126, v126
	v_exp_f32_e32 v127, v127
	v_add_f32_e32 v128, v128, v48
	v_add_f32_e32 v129, v129, v49
	v_mul_f32_e32 v128, 0xbfb8aa3b, v128
	v_pk_add_f32 v[126:127], v[126:127], 1.0 op_sel_hi:[1,0]
	v_mul_f32_e32 v129, 0xbfb8aa3b, v129
	v_div_scale_f32 v134, s[2:3], v127, v127, 1.0
	v_rcp_f32_e32 v135, v134
	v_exp_f32_e32 v128, v128
	v_exp_f32_e32 v129, v129
	v_pk_add_f32 v[122:123], v[122:123], v[50:51]
	v_fma_f32 v136, -v134, v135, 1.0
	v_fmac_f32_e32 v135, v136, v135
	v_div_scale_f32 v136, vcc, 1.0, v127, 1.0
	v_mul_f32_e32 v137, v136, v135
	v_fma_f32 v138, -v134, v137, v136
	v_fmac_f32_e32 v137, v138, v135
	v_fma_f32 v134, -v134, v137, v136
	v_div_fmas_f32 v134, v134, v135, v137
	v_div_fixup_f32 v127, v134, v127, 1.0
	v_div_scale_f32 v134, s[2:3], v126, v126, 1.0
	v_rcp_f32_e32 v135, v134
	v_pk_add_f32 v[128:129], v[128:129], 1.0 op_sel_hi:[1,0]
	v_add_f32_e32 v118, v118, v34
	v_add_f32_e32 v119, v119, v35
	v_fma_f32 v136, -v134, v135, 1.0
	v_fmac_f32_e32 v135, v136, v135
	v_div_scale_f32 v136, vcc, 1.0, v126, 1.0
	v_mul_f32_e32 v137, v136, v135
	v_fma_f32 v138, -v134, v137, v136
	v_fmac_f32_e32 v137, v138, v135
	v_fma_f32 v134, -v134, v137, v136
	v_div_fmas_f32 v134, v134, v135, v137
	v_div_fixup_f32 v126, v134, v126, 1.0
	v_pk_mul_f32 v[122:123], v[122:123], v[126:127]
	v_div_scale_f32 v127, s[2:3], v129, v129, 1.0
	v_rcp_f32_e32 v134, v127
	v_mul_f32_e32 v118, 0xbfb8aa3b, v118
	v_mul_f32_e32 v119, 0xbfb8aa3b, v119
	v_exp_f32_e32 v118, v118
	v_fma_f32 v135, -v127, v134, 1.0
	v_fmac_f32_e32 v134, v135, v134
	v_div_scale_f32 v135, vcc, 1.0, v129, 1.0
	v_mul_f32_e32 v136, v135, v134
	v_fma_f32 v137, -v127, v136, v135
	v_fmac_f32_e32 v136, v137, v134
	v_fma_f32 v127, -v127, v136, v135
	v_div_fmas_f32 v127, v127, v134, v136
	v_div_fixup_f32 v129, v127, v129, 1.0
	v_div_scale_f32 v127, s[2:3], v128, v128, 1.0
	v_rcp_f32_e32 v134, v127
	v_exp_f32_e32 v119, v119
	v_or_b32_e32 v130, 16, v162
	s_waitcnt lgkmcnt(0)
	v_mov_b32_e32 v131, v163
	v_fma_f32 v135, -v127, v134, 1.0
	v_fmac_f32_e32 v134, v135, v134
	v_div_scale_f32 v135, vcc, 1.0, v128, 1.0
	v_mul_f32_e32 v136, v135, v134
	v_fma_f32 v137, -v127, v136, v135
	v_fmac_f32_e32 v136, v137, v134
	v_fma_f32 v127, -v127, v136, v135
	v_div_fmas_f32 v127, v127, v134, v136
	v_lshlrev_b64 v[132:133], 11, v[130:131]
	v_pk_add_f32 v[124:125], v[124:125], v[52:53]
	v_div_fixup_f32 v128, v127, v128, 1.0
	v_pk_mul_f32 v[124:125], v[124:125], v[128:129]
	v_lshl_add_u64 v[128:129], s[0:1], 0, v[132:133]
	v_cvt_pk_f16_f32 v126, v122, v123
	v_cvt_pk_f16_f32 v127, v124, v125
	v_lshl_add_u64 v[128:129], v[160:161], 1, v[128:129]
	v_pk_add_f32 v[118:119], v[118:119], 1.0 op_sel_hi:[1,0]
	global_store_dwordx2 v[128:129], v[126:127], off
	v_div_scale_f32 v126, s[2:3], v119, v119, 1.0
	v_rcp_f32_e32 v127, v126
	v_add_f32_e32 v120, v120, v36
	v_add_f32_e32 v121, v121, v37
	v_mul_f32_e32 v120, 0xbfb8aa3b, v120
	v_fma_f32 v132, -v126, v127, 1.0
	v_fmac_f32_e32 v127, v132, v127
	v_div_scale_f32 v132, vcc, 1.0, v119, 1.0
	v_mul_f32_e32 v133, v132, v127
	v_fma_f32 v134, -v126, v133, v132
	v_fmac_f32_e32 v133, v134, v127
	v_fma_f32 v126, -v126, v133, v132
	v_div_fmas_f32 v126, v126, v127, v133
	v_div_fixup_f32 v119, v126, v119, 1.0
	v_div_scale_f32 v126, s[2:3], v118, v118, 1.0
	v_rcp_f32_e32 v127, v126
	v_mul_f32_e32 v121, 0xbfb8aa3b, v121
	v_exp_f32_e32 v120, v120
	v_exp_f32_e32 v121, v121
	v_fma_f32 v132, -v126, v127, 1.0
	v_fmac_f32_e32 v127, v132, v127
	v_div_scale_f32 v132, vcc, 1.0, v118, 1.0
	v_mul_f32_e32 v133, v132, v127
	v_fma_f32 v134, -v126, v133, v132
	v_fmac_f32_e32 v133, v134, v127
	v_fma_f32 v126, -v126, v133, v132
	v_div_fmas_f32 v126, v126, v127, v133
	v_pk_add_f32 v[114:115], v[114:115], v[62:63]
	v_div_fixup_f32 v118, v126, v118, 1.0
	v_pk_add_f32 v[120:121], v[120:121], 1.0 op_sel_hi:[1,0]
	v_pk_mul_f32 v[114:115], v[114:115], v[118:119]
	v_div_scale_f32 v119, s[2:3], v121, v121, 1.0
	v_rcp_f32_e32 v126, v119
	v_pk_add_f32 v[116:117], v[116:117], v[64:65]
	v_pk_mul_f32 v[122:123], v[122:123], v[122:123]
	v_cvt_pk_f16_f32 v118, v114, v115
	v_fma_f32 v127, -v119, v126, 1.0
	v_fmac_f32_e32 v126, v127, v126
	v_div_scale_f32 v127, vcc, 1.0, v121, 1.0
	v_mul_f32_e32 v132, v127, v126
	v_fma_f32 v133, -v119, v132, v127
	v_fmac_f32_e32 v132, v133, v126
	v_fma_f32 v119, -v119, v132, v127
	v_div_fmas_f32 v119, v119, v126, v132
	v_div_fixup_f32 v121, v119, v121, 1.0
	v_div_scale_f32 v119, s[2:3], v120, v120, 1.0
	v_rcp_f32_e32 v126, v119
	v_pk_mul_f32 v[114:115], v[114:115], v[114:115]
	v_pk_mul_f32 v[124:125], v[124:125], v[124:125]
	v_add_f32_e32 v114, v114, v115
	v_fma_f32 v127, -v119, v126, 1.0
	v_fmac_f32_e32 v126, v127, v126
	v_div_scale_f32 v127, vcc, 1.0, v120, 1.0
	v_mul_f32_e32 v132, v127, v126
	v_fma_f32 v133, -v119, v132, v127
	v_fmac_f32_e32 v132, v133, v126
	v_fma_f32 v119, -v119, v132, v127
	v_div_fmas_f32 v119, v119, v126, v132
	v_div_fixup_f32 v120, v119, v120, 1.0
	v_pk_mul_f32 v[116:117], v[116:117], v[120:121]
	v_add_f32_e32 v115, v122, v123
	v_cvt_pk_f16_f32 v119, v116, v117
	v_pk_mul_f32 v[116:117], v[116:117], v[116:117]
	v_add_f32_e32 v115, v124, v115
	v_add_f32_e32 v114, v116, v114
	v_add_f32_e32 v114, v117, v114
	v_add_f32_e32 v115, v125, v115
	v_add_f32_e32 v114, v115, v114
	v_mov_b32_e32 v115, v114
	s_nop 1
	v_permlane16_swap_b32_e32 v115, v114
	global_store_dwordx2 v[128:129], v[118:119], off offset:128
	s_waitcnt lgkmcnt(0)
	v_add_f32_e32 v114, v114, v115
	v_mov_b32_e32 v115, v114
	s_nop 1
	v_permlane32_swap_b32_e32 v115, v114
	s_and_saveexec_b64 s[24:25], s[6:7]
	s_cbranch_execz .LBB0_2289
	s_waitcnt lgkmcnt(0)
	v_add_f32_e32 v116, v114, v115
	v_lshlrev_b64 v[114:115], 6, v[130:131]
	v_lshl_add_u64 v[114:115], s[10:11], 0, v[114:115]
	v_lshl_add_u64 v[114:115], s[22:23], 2, v[114:115]
	s_lshl_b32 s92, s45, 2
	v_lshl_add_u64 v[114:115], v[114:115], 0, s[92:93]
	global_store_dword v[114:115], v116, off
; __device__ __forceinline__ float xor16(float v) { return __int_as_float(__builtin_amdgcn_ds_swizzle(__float_as_int(v), 0x401F)); }
; __device__ __forceinline__ float sigmoidf(float x) { return 1.f / (1.f + __expf(-x)); }
;   __device__ __forceinline__ void operator()(const f32x4 (&acc)[2][2][4][2], const g8::Unit& u, int ui, int wr, int wc, int fr, int fq) const {
;     ...
;         for (int bj = 0; bj < 2; ++bj) {
;           const f32x4 a = acc[ai][bj][m][0], b = acc[ai][bj][m][1];
;           float o0 = (a[0] + ba[bj].x) * sigmoidf(b[0] + bb[bj].x);
;           float o1 = (a[1] + ba[bj].y) * sigmoidf(b[1] + bb[bj].y);
;           float o2 = (a[2] + ba[bj].z) * sigmoidf(b[2] + bb[bj].z);
;           float o3 = (a[3] + ba[bj].w) * sigmoidf(b[3] + bb[bj].w);
;           *(h16x4*)(OB + row * 1024 + ocb + 64 * bj) = pack4(o0, o1, o2, o3);
;           ss += o0 * o0 + o1 * o1 + o2 * o2 + o3 * o3;
;         }
;         ss += xor16(ss);
;         ss += __shfl_xor(ss, 32);
;         if (fq == 0) ssqb[row * 16 + u.pn * 4 + wc] = ss;
.LBB0_2289:
	s_or_b64 exec, exec, s[24:25]
	v_add_f32_e32 v110, v110, v46
	v_add_f32_e32 v111, v111, v47
	v_mul_f32_e32 v110, 0xbfb8aa3b, v110
	v_mul_f32_e32 v111, 0xbfb8aa3b, v111
	v_exp_f32_e32 v110, v110
	v_exp_f32_e32 v111, v111
	v_add_f32_e32 v112, v112, v48
	v_add_f32_e32 v113, v113, v49
	v_mul_f32_e32 v112, 0xbfb8aa3b, v112
	v_pk_add_f32 v[110:111], v[110:111], 1.0 op_sel_hi:[1,0]
	v_mul_f32_e32 v113, 0xbfb8aa3b, v113
	v_div_scale_f32 v118, s[2:3], v111, v111, 1.0
	v_rcp_f32_e32 v119, v118
	v_exp_f32_e32 v112, v112
	v_exp_f32_e32 v113, v113
	v_pk_add_f32 v[106:107], v[106:107], v[50:51]
	v_fma_f32 v120, -v118, v119, 1.0
	v_fmac_f32_e32 v119, v120, v119
	v_div_scale_f32 v120, vcc, 1.0, v111, 1.0
	v_mul_f32_e32 v121, v120, v119
	v_fma_f32 v122, -v118, v121, v120
	v_fmac_f32_e32 v121, v122, v119
	v_fma_f32 v118, -v118, v121, v120
	v_div_fmas_f32 v118, v118, v119, v121
	v_div_fixup_f32 v111, v118, v111, 1.0
	v_div_scale_f32 v118, s[2:3], v110, v110, 1.0
	v_rcp_f32_e32 v119, v118
	v_pk_add_f32 v[112:113], v[112:113], 1.0 op_sel_hi:[1,0]
	v_add_f32_e32 v102, v102, v34
	v_add_f32_e32 v103, v103, v35
	v_fma_f32 v120, -v118, v119, 1.0
	v_fmac_f32_e32 v119, v120, v119
	v_div_scale_f32 v120, vcc, 1.0, v110, 1.0
	v_mul_f32_e32 v121, v120, v119
	v_fma_f32 v122, -v118, v121, v120
	v_fmac_f32_e32 v121, v122, v119
	v_fma_f32 v118, -v118, v121, v120
	v_div_fmas_f32 v118, v118, v119, v121
	v_div_fixup_f32 v110, v118, v110, 1.0
	v_pk_mul_f32 v[106:107], v[106:107], v[110:111]
	v_div_scale_f32 v111, s[2:3], v113, v113, 1.0
	v_rcp_f32_e32 v118, v111
	v_mul_f32_e32 v102, 0xbfb8aa3b, v102
	v_mul_f32_e32 v103, 0xbfb8aa3b, v103
	v_exp_f32_e32 v102, v102
	v_fma_f32 v119, -v111, v118, 1.0
	v_fmac_f32_e32 v118, v119, v118
	v_div_scale_f32 v119, vcc, 1.0, v113, 1.0
	v_mul_f32_e32 v120, v119, v118
	v_fma_f32 v121, -v111, v120, v119
	v_fmac_f32_e32 v120, v121, v118
	v_fma_f32 v111, -v111, v120, v119
	v_div_fmas_f32 v111, v111, v118, v120
	v_div_fixup_f32 v113, v111, v113, 1.0
	v_div_scale_f32 v111, s[2:3], v112, v112, 1.0
	v_rcp_f32_e32 v118, v111
	v_exp_f32_e32 v103, v103
	v_or_b32_e32 v114, 32, v162
	s_waitcnt lgkmcnt(0)
	v_mov_b32_e32 v115, v163
	v_fma_f32 v119, -v111, v118, 1.0
	v_fmac_f32_e32 v118, v119, v118
	v_div_scale_f32 v119, vcc, 1.0, v112, 1.0
	v_mul_f32_e32 v120, v119, v118
	v_fma_f32 v121, -v111, v120, v119
	v_fmac_f32_e32 v120, v121, v118
	v_fma_f32 v111, -v111, v120, v119
	v_div_fmas_f32 v111, v111, v118, v120
	v_lshlrev_b64 v[116:117], 11, v[114:115]
	v_pk_add_f32 v[108:109], v[108:109], v[52:53]
	v_div_fixup_f32 v112, v111, v112, 1.0
	v_pk_mul_f32 v[108:109], v[108:109], v[112:113]
	v_lshl_add_u64 v[112:113], s[0:1], 0, v[116:117]
	v_cvt_pk_f16_f32 v110, v106, v107
	v_cvt_pk_f16_f32 v111, v108, v109
	v_lshl_add_u64 v[112:113], v[160:161], 1, v[112:113]
	v_pk_add_f32 v[102:103], v[102:103], 1.0 op_sel_hi:[1,0]
	global_store_dwordx2 v[112:113], v[110:111], off
	v_div_scale_f32 v110, s[2:3], v103, v103, 1.0
	v_rcp_f32_e32 v111, v110
	v_add_f32_e32 v104, v104, v36
	v_add_f32_e32 v105, v105, v37
	v_mul_f32_e32 v104, 0xbfb8aa3b, v104
	v_fma_f32 v116, -v110, v111, 1.0
	v_fmac_f32_e32 v111, v116, v111
	v_div_scale_f32 v116, vcc, 1.0, v103, 1.0
	v_mul_f32_e32 v117, v116, v111
	v_fma_f32 v118, -v110, v117, v116
	v_fmac_f32_e32 v117, v118, v111
	v_fma_f32 v110, -v110, v117, v116
	v_div_fmas_f32 v110, v110, v111, v117
	v_div_fixup_f32 v103, v110, v103, 1.0
	v_div_scale_f32 v110, s[2:3], v102, v102, 1.0
	v_rcp_f32_e32 v111, v110
	v_mul_f32_e32 v105, 0xbfb8aa3b, v105
	v_exp_f32_e32 v104, v104
	v_exp_f32_e32 v105, v105
	v_fma_f32 v116, -v110, v111, 1.0
	v_fmac_f32_e32 v111, v116, v111
	v_div_scale_f32 v116, vcc, 1.0, v102, 1.0
	v_mul_f32_e32 v117, v116, v111
	v_fma_f32 v118, -v110, v117, v116
	v_fmac_f32_e32 v117, v118, v111
	v_fma_f32 v110, -v110, v117, v116
	v_div_fmas_f32 v110, v110, v111, v117
	v_pk_add_f32 v[98:99], v[98:99], v[62:63]
	v_div_fixup_f32 v102, v110, v102, 1.0
	v_pk_add_f32 v[104:105], v[104:105], 1.0 op_sel_hi:[1,0]
	v_pk_mul_f32 v[98:99], v[98:99], v[102:103]
	v_div_scale_f32 v103, s[2:3], v105, v105, 1.0
	v_rcp_f32_e32 v110, v103
	v_pk_add_f32 v[100:101], v[100:101], v[64:65]
	v_pk_mul_f32 v[106:107], v[106:107], v[106:107]
	v_cvt_pk_f16_f32 v102, v98, v99
	v_fma_f32 v111, -v103, v110, 1.0
	v_fmac_f32_e32 v110, v111, v110
	v_div_scale_f32 v111, vcc, 1.0, v105, 1.0
	v_mul_f32_e32 v116, v111, v110
	v_fma_f32 v117, -v103, v116, v111
	v_fmac_f32_e32 v116, v117, v110
	v_fma_f32 v103, -v103, v116, v111
	v_div_fmas_f32 v103, v103, v110, v116
	v_div_fixup_f32 v105, v103, v105, 1.0
	v_div_scale_f32 v103, s[2:3], v104, v104, 1.0
	v_rcp_f32_e32 v110, v103
	v_pk_mul_f32 v[98:99], v[98:99], v[98:99]
	v_pk_mul_f32 v[108:109], v[108:109], v[108:109]
	v_add_f32_e32 v98, v98, v99
	v_fma_f32 v111, -v103, v110, 1.0
	v_fmac_f32_e32 v110, v111, v110
	v_div_scale_f32 v111, vcc, 1.0, v104, 1.0
	v_mul_f32_e32 v116, v111, v110
	v_fma_f32 v117, -v103, v116, v111
	v_fmac_f32_e32 v116, v117, v110
	v_fma_f32 v103, -v103, v116, v111
	v_div_fmas_f32 v103, v103, v110, v116
	v_div_fixup_f32 v104, v103, v104, 1.0
	v_pk_mul_f32 v[100:101], v[100:101], v[104:105]
	v_add_f32_e32 v99, v106, v107
	v_cvt_pk_f16_f32 v103, v100, v101
	v_pk_mul_f32 v[100:101], v[100:101], v[100:101]
	v_add_f32_e32 v99, v108, v99
	v_add_f32_e32 v98, v100, v98
	v_add_f32_e32 v98, v101, v98
	v_add_f32_e32 v99, v109, v99
	v_add_f32_e32 v98, v99, v98
	v_mov_b32_e32 v99, v98
	s_nop 1
	v_permlane16_swap_b32_e32 v99, v98
	global_store_dwordx2 v[112:113], v[102:103], off offset:128
	s_waitcnt lgkmcnt(0)
	v_add_f32_e32 v98, v98, v99
	v_mov_b32_e32 v99, v98
	s_nop 1
	v_permlane32_swap_b32_e32 v99, v98
	s_and_saveexec_b64 s[24:25], s[6:7]
	s_cbranch_execz .LBB0_2291
	s_waitcnt lgkmcnt(0)
	v_add_f32_e32 v100, v98, v99
	v_lshlrev_b64 v[98:99], 6, v[114:115]
	v_lshl_add_u64 v[98:99], s[10:11], 0, v[98:99]
	v_lshl_add_u64 v[98:99], s[22:23], 2, v[98:99]
	s_lshl_b32 s92, s45, 2
	v_lshl_add_u64 v[98:99], v[98:99], 0, s[92:93]
	global_store_dword v[98:99], v100, off
; __device__ __forceinline__ float xor16(float v) { return __int_as_float(__builtin_amdgcn_ds_swizzle(__float_as_int(v), 0x401F)); }
; __device__ __forceinline__ float sigmoidf(float x) { return 1.f / (1.f + __expf(-x)); }
;   __device__ __forceinline__ void operator()(const f32x4 (&acc)[2][2][4][2], const g8::Unit& u, int ui, int wr, int wc, int fr, int fq) const {
;     ...
;         for (int bj = 0; bj < 2; ++bj) {
;           const f32x4 a = acc[ai][bj][m][0], b = acc[ai][bj][m][1];
;           float o0 = (a[0] + ba[bj].x) * sigmoidf(b[0] + bb[bj].x);
;           float o1 = (a[1] + ba[bj].y) * sigmoidf(b[1] + bb[bj].y);
;           float o2 = (a[2] + ba[bj].z) * sigmoidf(b[2] + bb[bj].z);
;           float o3 = (a[3] + ba[bj].w) * sigmoidf(b[3] + bb[bj].w);
;           *(h16x4*)(OB + row * 1024 + ocb + 64 * bj) = pack4(o0, o1, o2, o3);
;           ss += o0 * o0 + o1 * o1 + o2 * o2 + o3 * o3;
;         }
;         ss += xor16(ss);
;         ss += __shfl_xor(ss, 32);
;         if (fq == 0) ssqb[row * 16 + u.pn * 4 + wc] = ss;
.LBB0_2291:
	s_or_b64 exec, exec, s[24:25]
	v_add_f32_e32 v94, v94, v46
	v_add_f32_e32 v95, v95, v47
	v_mul_f32_e32 v94, 0xbfb8aa3b, v94
	v_mul_f32_e32 v95, 0xbfb8aa3b, v95
	v_exp_f32_e32 v94, v94
	v_exp_f32_e32 v95, v95
	v_add_f32_e32 v96, v96, v48
	v_add_f32_e32 v97, v97, v49
	v_mul_f32_e32 v96, 0xbfb8aa3b, v96
	v_pk_add_f32 v[94:95], v[94:95], 1.0 op_sel_hi:[1,0]
	v_mul_f32_e32 v97, 0xbfb8aa3b, v97
	v_div_scale_f32 v102, s[2:3], v95, v95, 1.0
	v_rcp_f32_e32 v103, v102
	v_exp_f32_e32 v96, v96
	v_exp_f32_e32 v97, v97
	v_pk_add_f32 v[90:91], v[90:91], v[50:51]
	v_fma_f32 v104, -v102, v103, 1.0
	v_fmac_f32_e32 v103, v104, v103
	v_div_scale_f32 v104, vcc, 1.0, v95, 1.0
	v_mul_f32_e32 v105, v104, v103
	v_fma_f32 v106, -v102, v105, v104
	v_fmac_f32_e32 v105, v106, v103
	v_fma_f32 v102, -v102, v105, v104
	v_div_fmas_f32 v102, v102, v103, v105
	v_div_fixup_f32 v95, v102, v95, 1.0
	v_div_scale_f32 v102, s[2:3], v94, v94, 1.0
	v_rcp_f32_e32 v103, v102
	v_pk_add_f32 v[96:97], v[96:97], 1.0 op_sel_hi:[1,0]
	v_add_f32_e32 v86, v86, v34
	v_add_f32_e32 v87, v87, v35
	v_fma_f32 v104, -v102, v103, 1.0
	v_fmac_f32_e32 v103, v104, v103
	v_div_scale_f32 v104, vcc, 1.0, v94, 1.0
	v_mul_f32_e32 v105, v104, v103
	v_fma_f32 v106, -v102, v105, v104
	v_fmac_f32_e32 v105, v106, v103
	v_fma_f32 v102, -v102, v105, v104
	v_div_fmas_f32 v102, v102, v103, v105
	v_div_fixup_f32 v94, v102, v94, 1.0
	v_pk_mul_f32 v[90:91], v[90:91], v[94:95]
	v_div_scale_f32 v95, s[2:3], v97, v97, 1.0
	v_rcp_f32_e32 v102, v95
	v_mul_f32_e32 v86, 0xbfb8aa3b, v86
	v_mul_f32_e32 v87, 0xbfb8aa3b, v87
	v_exp_f32_e32 v86, v86
	v_fma_f32 v103, -v95, v102, 1.0
	v_fmac_f32_e32 v102, v103, v102
	v_div_scale_f32 v103, vcc, 1.0, v97, 1.0
	v_mul_f32_e32 v104, v103, v102
	v_fma_f32 v105, -v95, v104, v103
	v_fmac_f32_e32 v104, v105, v102
	v_fma_f32 v95, -v95, v104, v103
	v_div_fmas_f32 v95, v95, v102, v104
	v_div_fixup_f32 v97, v95, v97, 1.0
	v_div_scale_f32 v95, s[2:3], v96, v96, 1.0
	v_rcp_f32_e32 v102, v95
	v_exp_f32_e32 v87, v87
	v_or_b32_e32 v98, 48, v162
	s_waitcnt lgkmcnt(0)
	v_mov_b32_e32 v99, v163
	v_fma_f32 v103, -v95, v102, 1.0
	v_fmac_f32_e32 v102, v103, v102
	v_div_scale_f32 v103, vcc, 1.0, v96, 1.0
	v_mul_f32_e32 v104, v103, v102
	v_fma_f32 v105, -v95, v104, v103
	v_fmac_f32_e32 v104, v105, v102
	v_fma_f32 v95, -v95, v104, v103
	v_div_fmas_f32 v95, v95, v102, v104
	v_lshlrev_b64 v[100:101], 11, v[98:99]
	v_pk_add_f32 v[92:93], v[92:93], v[52:53]
	v_div_fixup_f32 v96, v95, v96, 1.0
	v_pk_mul_f32 v[92:93], v[92:93], v[96:97]
	v_lshl_add_u64 v[96:97], s[0:1], 0, v[100:101]
	v_cvt_pk_f16_f32 v94, v90, v91
	v_cvt_pk_f16_f32 v95, v92, v93
	v_lshl_add_u64 v[96:97], v[160:161], 1, v[96:97]
	v_pk_add_f32 v[86:87], v[86:87], 1.0 op_sel_hi:[1,0]
	global_store_dwordx2 v[96:97], v[94:95], off
	v_div_scale_f32 v94, s[2:3], v87, v87, 1.0
	v_rcp_f32_e32 v95, v94
	v_add_f32_e32 v88, v88, v36
	v_add_f32_e32 v89, v89, v37
	v_mul_f32_e32 v88, 0xbfb8aa3b, v88
	v_fma_f32 v100, -v94, v95, 1.0
	v_fmac_f32_e32 v95, v100, v95
	v_div_scale_f32 v100, vcc, 1.0, v87, 1.0
	v_mul_f32_e32 v101, v100, v95
	v_fma_f32 v102, -v94, v101, v100
	v_fmac_f32_e32 v101, v102, v95
	v_fma_f32 v94, -v94, v101, v100
	v_div_fmas_f32 v94, v94, v95, v101
	v_div_fixup_f32 v87, v94, v87, 1.0
	v_div_scale_f32 v94, s[2:3], v86, v86, 1.0
	v_rcp_f32_e32 v95, v94
	v_mul_f32_e32 v89, 0xbfb8aa3b, v89
	v_exp_f32_e32 v88, v88
	v_exp_f32_e32 v89, v89
	v_fma_f32 v100, -v94, v95, 1.0
	v_fmac_f32_e32 v95, v100, v95
	v_div_scale_f32 v100, vcc, 1.0, v86, 1.0
	v_mul_f32_e32 v101, v100, v95
	v_fma_f32 v102, -v94, v101, v100
	v_fmac_f32_e32 v101, v102, v95
	v_fma_f32 v94, -v94, v101, v100
	v_div_fmas_f32 v94, v94, v95, v101
	v_pk_add_f32 v[82:83], v[82:83], v[62:63]
	v_div_fixup_f32 v86, v94, v86, 1.0
	v_pk_add_f32 v[88:89], v[88:89], 1.0 op_sel_hi:[1,0]
	v_pk_mul_f32 v[82:83], v[82:83], v[86:87]
	v_div_scale_f32 v87, s[2:3], v89, v89, 1.0
	v_rcp_f32_e32 v94, v87
	v_pk_add_f32 v[84:85], v[84:85], v[64:65]
	v_pk_mul_f32 v[90:91], v[90:91], v[90:91]
	v_cvt_pk_f16_f32 v86, v82, v83
	v_fma_f32 v95, -v87, v94, 1.0
	v_fmac_f32_e32 v94, v95, v94
	v_div_scale_f32 v95, vcc, 1.0, v89, 1.0
	v_mul_f32_e32 v100, v95, v94
	v_fma_f32 v101, -v87, v100, v95
	v_fmac_f32_e32 v100, v101, v94
	v_fma_f32 v87, -v87, v100, v95
	v_div_fmas_f32 v87, v87, v94, v100
	v_div_fixup_f32 v89, v87, v89, 1.0
	v_div_scale_f32 v87, s[2:3], v88, v88, 1.0
	v_rcp_f32_e32 v94, v87
	v_pk_mul_f32 v[82:83], v[82:83], v[82:83]
	v_pk_mul_f32 v[92:93], v[92:93], v[92:93]
	v_add_f32_e32 v82, v82, v83
	v_fma_f32 v95, -v87, v94, 1.0
	v_fmac_f32_e32 v94, v95, v94
	v_div_scale_f32 v95, vcc, 1.0, v88, 1.0
	v_mul_f32_e32 v100, v95, v94
	v_fma_f32 v101, -v87, v100, v95
	v_fmac_f32_e32 v100, v101, v94
	v_fma_f32 v87, -v87, v100, v95
	v_div_fmas_f32 v87, v87, v94, v100
	v_div_fixup_f32 v88, v87, v88, 1.0
	v_pk_mul_f32 v[84:85], v[84:85], v[88:89]
	v_add_f32_e32 v83, v90, v91
	v_cvt_pk_f16_f32 v87, v84, v85
	v_pk_mul_f32 v[84:85], v[84:85], v[84:85]
	v_add_f32_e32 v83, v92, v83
	v_add_f32_e32 v82, v84, v82
	v_add_f32_e32 v82, v85, v82
	v_add_f32_e32 v83, v93, v83
	v_add_f32_e32 v82, v83, v82
	v_mov_b32_e32 v83, v82
	s_nop 1
	v_permlane16_swap_b32_e32 v83, v82
	global_store_dwordx2 v[96:97], v[86:87], off offset:128
	s_waitcnt lgkmcnt(0)
	v_add_f32_e32 v82, v82, v83
	v_mov_b32_e32 v83, v82
	s_nop 1
	v_permlane32_swap_b32_e32 v83, v82
	s_and_saveexec_b64 s[24:25], s[6:7]
	s_cbranch_execz .LBB0_2293
	s_waitcnt lgkmcnt(0)
	v_add_f32_e32 v84, v82, v83
	v_lshlrev_b64 v[82:83], 6, v[98:99]
	v_lshl_add_u64 v[82:83], s[10:11], 0, v[82:83]
	v_lshl_add_u64 v[82:83], s[22:23], 2, v[82:83]
	s_lshl_b32 s92, s45, 2
	v_lshl_add_u64 v[82:83], v[82:83], 0, s[92:93]
	global_store_dword v[82:83], v84, off
; __device__ __forceinline__ float xor16(float v) { return __int_as_float(__builtin_amdgcn_ds_swizzle(__float_as_int(v), 0x401F)); }
; __device__ __forceinline__ float sigmoidf(float x) { return 1.f / (1.f + __expf(-x)); }
;   __device__ __forceinline__ void operator()(const f32x4 (&acc)[2][2][4][2], const g8::Unit& u, int ui, int wr, int wc, int fr, int fq) const {
;     ...
;         for (int bj = 0; bj < 2; ++bj) {
;           const f32x4 a = acc[ai][bj][m][0], b = acc[ai][bj][m][1];
;           float o0 = (a[0] + ba[bj].x) * sigmoidf(b[0] + bb[bj].x);
;           float o1 = (a[1] + ba[bj].y) * sigmoidf(b[1] + bb[bj].y);
;           float o2 = (a[2] + ba[bj].z) * sigmoidf(b[2] + bb[bj].z);
;           float o3 = (a[3] + ba[bj].w) * sigmoidf(b[3] + bb[bj].w);
;           *(h16x4*)(OB + row * 1024 + ocb + 64 * bj) = pack4(o0, o1, o2, o3);
;           ss += o0 * o0 + o1 * o1 + o2 * o2 + o3 * o3;
;         }
;         ss += xor16(ss);
;         ss += __shfl_xor(ss, 32);
;         if (fq == 0) ssqb[row * 16 + u.pn * 4 + wc] = ss;
.LBB0_2293:
	s_or_b64 exec, exec, s[24:25]
	v_add_f32_e32 v78, v78, v46
	v_add_f32_e32 v79, v79, v47
	v_mul_f32_e32 v78, 0xbfb8aa3b, v78
	v_mul_f32_e32 v79, 0xbfb8aa3b, v79
	v_exp_f32_e32 v78, v78
	v_exp_f32_e32 v79, v79
	v_add_f32_e32 v80, v80, v48
	v_add_f32_e32 v81, v81, v49
	v_mul_f32_e32 v80, 0xbfb8aa3b, v80
	v_pk_add_f32 v[78:79], v[78:79], 1.0 op_sel_hi:[1,0]
	v_mul_f32_e32 v81, 0xbfb8aa3b, v81
	v_div_scale_f32 v86, s[2:3], v79, v79, 1.0
	v_rcp_f32_e32 v87, v86
	v_exp_f32_e32 v80, v80
	v_exp_f32_e32 v81, v81
	v_pk_add_f32 v[74:75], v[74:75], v[50:51]
	v_fma_f32 v88, -v86, v87, 1.0
	v_fmac_f32_e32 v87, v88, v87
	v_div_scale_f32 v88, vcc, 1.0, v79, 1.0
	v_mul_f32_e32 v89, v88, v87
	v_fma_f32 v90, -v86, v89, v88
	v_fmac_f32_e32 v89, v90, v87
	v_fma_f32 v86, -v86, v89, v88
	v_div_fmas_f32 v86, v86, v87, v89
	v_div_fixup_f32 v79, v86, v79, 1.0
	v_div_scale_f32 v86, s[2:3], v78, v78, 1.0
	v_rcp_f32_e32 v87, v86
	v_pk_add_f32 v[80:81], v[80:81], 1.0 op_sel_hi:[1,0]
	v_add_f32_e32 v70, v70, v34
	v_add_f32_e32 v71, v71, v35
	v_fma_f32 v88, -v86, v87, 1.0
	v_fmac_f32_e32 v87, v88, v87
	v_div_scale_f32 v88, vcc, 1.0, v78, 1.0
	v_mul_f32_e32 v89, v88, v87
	v_fma_f32 v90, -v86, v89, v88
	v_fmac_f32_e32 v89, v90, v87
	v_fma_f32 v86, -v86, v89, v88
	v_div_fmas_f32 v86, v86, v87, v89
	v_div_fixup_f32 v78, v86, v78, 1.0
	v_pk_mul_f32 v[74:75], v[74:75], v[78:79]
	v_div_scale_f32 v79, s[2:3], v81, v81, 1.0
	v_rcp_f32_e32 v86, v79
	v_mul_f32_e32 v70, 0xbfb8aa3b, v70
	v_mul_f32_e32 v71, 0xbfb8aa3b, v71
	v_exp_f32_e32 v70, v70
	v_fma_f32 v87, -v79, v86, 1.0
	v_fmac_f32_e32 v86, v87, v86
	v_div_scale_f32 v87, vcc, 1.0, v81, 1.0
	v_mul_f32_e32 v88, v87, v86
	v_fma_f32 v89, -v79, v88, v87
	v_fmac_f32_e32 v88, v89, v86
	v_fma_f32 v79, -v79, v88, v87
	v_div_fmas_f32 v79, v79, v86, v88
	v_div_fixup_f32 v81, v79, v81, 1.0
	v_div_scale_f32 v79, s[2:3], v80, v80, 1.0
	v_rcp_f32_e32 v86, v79
	v_exp_f32_e32 v71, v71
	s_waitcnt lgkmcnt(0)
	v_lshl_add_u64 v[82:83], v[162:163], 0, s[94:95]
	v_lshlrev_b64 v[84:85], 11, v[82:83]
	v_fma_f32 v87, -v79, v86, 1.0
	v_fmac_f32_e32 v86, v87, v86
	v_div_scale_f32 v87, vcc, 1.0, v80, 1.0
	v_mul_f32_e32 v88, v87, v86
	v_fma_f32 v89, -v79, v88, v87
	v_fmac_f32_e32 v88, v89, v86
	v_fma_f32 v79, -v79, v88, v87
	v_div_fmas_f32 v79, v79, v86, v88
	v_pk_add_f32 v[76:77], v[76:77], v[52:53]
	v_div_fixup_f32 v80, v79, v80, 1.0
	v_pk_mul_f32 v[76:77], v[76:77], v[80:81]
	v_lshl_add_u64 v[80:81], s[0:1], 0, v[84:85]
	v_cvt_pk_f16_f32 v78, v74, v75
	v_cvt_pk_f16_f32 v79, v76, v77
	v_lshl_add_u64 v[80:81], v[160:161], 1, v[80:81]
	v_pk_add_f32 v[70:71], v[70:71], 1.0 op_sel_hi:[1,0]
	global_store_dwordx2 v[80:81], v[78:79], off
	v_div_scale_f32 v78, s[2:3], v71, v71, 1.0
	v_rcp_f32_e32 v79, v78
	v_add_f32_e32 v72, v72, v36
	v_add_f32_e32 v73, v73, v37
	v_mul_f32_e32 v72, 0xbfb8aa3b, v72
	v_fma_f32 v84, -v78, v79, 1.0
	v_fmac_f32_e32 v79, v84, v79
	v_div_scale_f32 v84, vcc, 1.0, v71, 1.0
	v_mul_f32_e32 v85, v84, v79
	v_fma_f32 v86, -v78, v85, v84
	v_fmac_f32_e32 v85, v86, v79
	v_fma_f32 v78, -v78, v85, v84
	v_div_fmas_f32 v78, v78, v79, v85
	v_div_fixup_f32 v71, v78, v71, 1.0
	v_div_scale_f32 v78, s[2:3], v70, v70, 1.0
	v_rcp_f32_e32 v79, v78
	v_mul_f32_e32 v73, 0xbfb8aa3b, v73
	v_exp_f32_e32 v72, v72
	v_exp_f32_e32 v73, v73
	v_fma_f32 v84, -v78, v79, 1.0
	v_fmac_f32_e32 v79, v84, v79
	v_div_scale_f32 v84, vcc, 1.0, v70, 1.0
	v_mul_f32_e32 v85, v84, v79
	v_fma_f32 v86, -v78, v85, v84
	v_fmac_f32_e32 v85, v86, v79
	v_fma_f32 v78, -v78, v85, v84
	v_div_fmas_f32 v78, v78, v79, v85
	v_pk_add_f32 v[66:67], v[66:67], v[62:63]
	v_div_fixup_f32 v70, v78, v70, 1.0
	v_pk_add_f32 v[72:73], v[72:73], 1.0 op_sel_hi:[1,0]
	v_pk_mul_f32 v[66:67], v[66:67], v[70:71]
	v_div_scale_f32 v71, s[2:3], v73, v73, 1.0
	v_rcp_f32_e32 v78, v71
	v_pk_add_f32 v[68:69], v[68:69], v[64:65]
	v_pk_mul_f32 v[74:75], v[74:75], v[74:75]
	v_cvt_pk_f16_f32 v70, v66, v67
	v_fma_f32 v79, -v71, v78, 1.0
	v_fmac_f32_e32 v78, v79, v78
	v_div_scale_f32 v79, vcc, 1.0, v73, 1.0
	v_mul_f32_e32 v84, v79, v78
	v_fma_f32 v85, -v71, v84, v79
	v_fmac_f32_e32 v84, v85, v78
	v_fma_f32 v71, -v71, v84, v79
	v_div_fmas_f32 v71, v71, v78, v84
	v_div_fixup_f32 v73, v71, v73, 1.0
	v_div_scale_f32 v71, s[2:3], v72, v72, 1.0
	v_rcp_f32_e32 v78, v71
	v_pk_mul_f32 v[66:67], v[66:67], v[66:67]
	v_pk_mul_f32 v[76:77], v[76:77], v[76:77]
	v_add_f32_e32 v66, v66, v67
	v_fma_f32 v79, -v71, v78, 1.0
	v_fmac_f32_e32 v78, v79, v78
	v_div_scale_f32 v79, vcc, 1.0, v72, 1.0
	v_mul_f32_e32 v84, v79, v78
	v_fma_f32 v85, -v71, v84, v79
	v_fmac_f32_e32 v84, v85, v78
	v_fma_f32 v71, -v71, v84, v79
	v_div_fmas_f32 v71, v71, v78, v84
	v_div_fixup_f32 v72, v71, v72, 1.0
	v_pk_mul_f32 v[68:69], v[68:69], v[72:73]
	v_add_f32_e32 v67, v74, v75
	v_cvt_pk_f16_f32 v71, v68, v69
	v_pk_mul_f32 v[68:69], v[68:69], v[68:69]
	v_add_f32_e32 v67, v76, v67
	v_add_f32_e32 v66, v68, v66
	v_add_f32_e32 v66, v69, v66
	v_add_f32_e32 v67, v77, v67
	v_add_f32_e32 v66, v67, v66
	v_mov_b32_e32 v67, v66
	s_nop 1
	v_permlane16_swap_b32_e32 v67, v66
	global_store_dwordx2 v[80:81], v[70:71], off offset:128
	s_waitcnt lgkmcnt(0)
	v_add_f32_e32 v66, v66, v67
	v_mov_b32_e32 v67, v66
	s_nop 1
	v_permlane32_swap_b32_e32 v67, v66
	s_and_saveexec_b64 s[24:25], s[6:7]
	s_cbranch_execz .LBB0_2295
	s_waitcnt lgkmcnt(0)
	v_add_f32_e32 v68, v66, v67
	v_lshlrev_b64 v[66:67], 6, v[82:83]
	v_lshl_add_u64 v[66:67], s[10:11], 0, v[66:67]
	v_lshl_add_u64 v[66:67], s[22:23], 2, v[66:67]
	s_lshl_b32 s92, s45, 2
	v_lshl_add_u64 v[66:67], v[66:67], 0, s[92:93]
	global_store_dword v[66:67], v68, off
; __device__ __forceinline__ float xor16(float v) { return __int_as_float(__builtin_amdgcn_ds_swizzle(__float_as_int(v), 0x401F)); }
; __device__ __forceinline__ float sigmoidf(float x) { return 1.f / (1.f + __expf(-x)); }
;   __device__ __forceinline__ void operator()(const f32x4 (&acc)[2][2][4][2], const g8::Unit& u, int ui, int wr, int wc, int fr, int fq) const {
;     ...
;         for (int bj = 0; bj < 2; ++bj) {
;           const f32x4 a = acc[ai][bj][m][0], b = acc[ai][bj][m][1];
;           float o0 = (a[0] + ba[bj].x) * sigmoidf(b[0] + bb[bj].x);
;           float o1 = (a[1] + ba[bj].y) * sigmoidf(b[1] + bb[bj].y);
;           float o2 = (a[2] + ba[bj].z) * sigmoidf(b[2] + bb[bj].z);
;           float o3 = (a[3] + ba[bj].w) * sigmoidf(b[3] + bb[bj].w);
;           *(h16x4*)(OB + row * 1024 + ocb + 64 * bj) = pack4(o0, o1, o2, o3);
;           ss += o0 * o0 + o1 * o1 + o2 * o2 + o3 * o3;
;         }
;         ss += xor16(ss);
;         ss += __shfl_xor(ss, 32);
;         if (fq == 0) ssqb[row * 16 + u.pn * 4 + wc] = ss;
.LBB0_2295:
	s_or_b64 exec, exec, s[24:25]
	v_add_f32_e32 v58, v58, v46
	v_add_f32_e32 v59, v59, v47
	v_mul_f32_e32 v58, 0xbfb8aa3b, v58
	v_mul_f32_e32 v59, 0xbfb8aa3b, v59
	v_exp_f32_e32 v58, v58
	v_exp_f32_e32 v59, v59
	s_mov_b64 s[2:3], 0x90
	s_waitcnt lgkmcnt(0)
	v_lshl_add_u64 v[66:67], v[162:163], 0, s[2:3]
	v_add_f32_e32 v60, v60, v48
	v_pk_add_f32 v[58:59], v[58:59], 1.0 op_sel_hi:[1,0]
	v_add_f32_e32 v61, v61, v49
	v_div_scale_f32 v70, s[2:3], v59, v59, 1.0
	v_rcp_f32_e32 v71, v70
	v_mul_f32_e32 v60, 0xbfb8aa3b, v60
	v_mul_f32_e32 v61, 0xbfb8aa3b, v61
	v_exp_f32_e32 v60, v60
	v_fma_f32 v72, -v70, v71, 1.0
	v_fmac_f32_e32 v71, v72, v71
	v_div_scale_f32 v72, vcc, 1.0, v59, 1.0
	v_mul_f32_e32 v73, v72, v71
	v_fma_f32 v74, -v70, v73, v72
	v_fmac_f32_e32 v73, v74, v71
	v_fma_f32 v70, -v70, v73, v72
	v_div_fmas_f32 v70, v70, v71, v73
	v_div_fixup_f32 v59, v70, v59, 1.0
	v_div_scale_f32 v70, s[2:3], v58, v58, 1.0
	v_rcp_f32_e32 v71, v70
	v_exp_f32_e32 v61, v61
	v_pk_add_f32 v[54:55], v[54:55], v[50:51]
	v_add_f32_e32 v42, v42, v34
	v_fma_f32 v72, -v70, v71, 1.0
	v_fmac_f32_e32 v71, v72, v71
	v_div_scale_f32 v72, vcc, 1.0, v58, 1.0
	v_mul_f32_e32 v73, v72, v71
	v_fma_f32 v74, -v70, v73, v72
	v_fmac_f32_e32 v73, v74, v71
	v_fma_f32 v70, -v70, v73, v72
	v_div_fmas_f32 v70, v70, v71, v73
	v_div_fixup_f32 v58, v70, v58, 1.0
	v_pk_add_f32 v[60:61], v[60:61], 1.0 op_sel_hi:[1,0]
	v_pk_mul_f32 v[54:55], v[54:55], v[58:59]
	v_div_scale_f32 v59, s[2:3], v61, v61, 1.0
	v_rcp_f32_e32 v70, v59
	v_add_f32_e32 v43, v43, v35
	v_mul_f32_e32 v42, 0xbfb8aa3b, v42
	v_mul_f32_e32 v43, 0xbfb8aa3b, v43
	v_fma_f32 v71, -v59, v70, 1.0
	v_fmac_f32_e32 v70, v71, v70
	v_div_scale_f32 v71, vcc, 1.0, v61, 1.0
	v_mul_f32_e32 v72, v71, v70
	v_fma_f32 v73, -v59, v72, v71
	v_fmac_f32_e32 v72, v73, v70
	v_fma_f32 v59, -v59, v72, v71
	v_div_fmas_f32 v59, v59, v70, v72
	v_div_fixup_f32 v61, v59, v61, 1.0
	v_div_scale_f32 v59, s[2:3], v60, v60, 1.0
	v_rcp_f32_e32 v70, v59
	v_exp_f32_e32 v42, v42
	v_exp_f32_e32 v43, v43
	v_lshlrev_b64 v[68:69], 11, v[66:67]
	v_fma_f32 v71, -v59, v70, 1.0
	v_fmac_f32_e32 v70, v71, v70
	v_div_scale_f32 v71, vcc, 1.0, v60, 1.0
	v_mul_f32_e32 v72, v71, v70
	v_fma_f32 v73, -v59, v72, v71
	v_fmac_f32_e32 v72, v73, v70
	v_fma_f32 v59, -v59, v72, v71
	v_div_fmas_f32 v59, v59, v70, v72
	v_pk_add_f32 v[56:57], v[56:57], v[52:53]
	v_div_fixup_f32 v60, v59, v60, 1.0
	v_pk_mul_f32 v[56:57], v[56:57], v[60:61]
	v_lshl_add_u64 v[60:61], s[0:1], 0, v[68:69]
	v_cvt_pk_f16_f32 v58, v54, v55
	v_cvt_pk_f16_f32 v59, v56, v57
	v_lshl_add_u64 v[60:61], v[160:161], 1, v[60:61]
	v_pk_add_f32 v[42:43], v[42:43], 1.0 op_sel_hi:[1,0]
	global_store_dwordx2 v[60:61], v[58:59], off
	v_div_scale_f32 v58, s[2:3], v43, v43, 1.0
	v_rcp_f32_e32 v59, v58
	v_add_f32_e32 v44, v44, v36
	v_add_f32_e32 v45, v45, v37
	v_mul_f32_e32 v44, 0xbfb8aa3b, v44
	v_fma_f32 v68, -v58, v59, 1.0
	v_fmac_f32_e32 v59, v68, v59
	v_div_scale_f32 v68, vcc, 1.0, v43, 1.0
	v_mul_f32_e32 v69, v68, v59
	v_fma_f32 v70, -v58, v69, v68
	v_fmac_f32_e32 v69, v70, v59
	v_fma_f32 v58, -v58, v69, v68
	v_div_fmas_f32 v58, v58, v59, v69
	v_div_fixup_f32 v43, v58, v43, 1.0
	v_div_scale_f32 v58, s[2:3], v42, v42, 1.0
	v_rcp_f32_e32 v59, v58
	v_mul_f32_e32 v45, 0xbfb8aa3b, v45
	v_exp_f32_e32 v44, v44
	v_exp_f32_e32 v45, v45
	v_fma_f32 v68, -v58, v59, 1.0
	v_fmac_f32_e32 v59, v68, v59
	v_div_scale_f32 v68, vcc, 1.0, v42, 1.0
	v_mul_f32_e32 v69, v68, v59
	v_fma_f32 v70, -v58, v69, v68
	v_fmac_f32_e32 v69, v70, v59
	v_fma_f32 v58, -v58, v69, v68
	v_div_fmas_f32 v58, v58, v59, v69
	v_pk_add_f32 v[38:39], v[38:39], v[62:63]
	v_div_fixup_f32 v42, v58, v42, 1.0
	v_pk_add_f32 v[44:45], v[44:45], 1.0 op_sel_hi:[1,0]
	v_pk_mul_f32 v[38:39], v[38:39], v[42:43]
	v_div_scale_f32 v43, s[2:3], v45, v45, 1.0
	v_rcp_f32_e32 v58, v43
	v_pk_add_f32 v[40:41], v[40:41], v[64:65]
	v_pk_mul_f32 v[54:55], v[54:55], v[54:55]
	v_cvt_pk_f16_f32 v42, v38, v39
	v_fma_f32 v59, -v43, v58, 1.0
	v_fmac_f32_e32 v58, v59, v58
	v_div_scale_f32 v59, vcc, 1.0, v45, 1.0
	v_mul_f32_e32 v68, v59, v58
	v_fma_f32 v69, -v43, v68, v59
	v_fmac_f32_e32 v68, v69, v58
	v_fma_f32 v43, -v43, v68, v59
	v_div_fmas_f32 v43, v43, v58, v68
	v_div_fixup_f32 v45, v43, v45, 1.0
	v_div_scale_f32 v43, s[2:3], v44, v44, 1.0
	v_rcp_f32_e32 v58, v43
	v_pk_mul_f32 v[38:39], v[38:39], v[38:39]
	v_pk_mul_f32 v[56:57], v[56:57], v[56:57]
	v_add_f32_e32 v38, v38, v39
	v_fma_f32 v59, -v43, v58, 1.0
	v_fmac_f32_e32 v58, v59, v58
	v_div_scale_f32 v59, vcc, 1.0, v44, 1.0
	v_mul_f32_e32 v68, v59, v58
	v_fma_f32 v69, -v43, v68, v59
	v_fmac_f32_e32 v68, v69, v58
	v_fma_f32 v43, -v43, v68, v59
	v_div_fmas_f32 v43, v43, v58, v68
	v_div_fixup_f32 v44, v43, v44, 1.0
	v_pk_mul_f32 v[40:41], v[40:41], v[44:45]
	v_add_f32_e32 v39, v54, v55
	v_cvt_pk_f16_f32 v43, v40, v41
	v_pk_mul_f32 v[40:41], v[40:41], v[40:41]
	v_add_f32_e32 v39, v56, v39
	v_add_f32_e32 v38, v40, v38
	v_add_f32_e32 v38, v41, v38
	v_add_f32_e32 v39, v57, v39
	v_add_f32_e32 v38, v39, v38
	v_mov_b32_e32 v39, v38
	s_nop 1
	v_permlane16_swap_b32_e32 v39, v38
	global_store_dwordx2 v[60:61], v[42:43], off offset:128
	s_waitcnt lgkmcnt(0)
	v_add_f32_e32 v38, v38, v39
	v_mov_b32_e32 v39, v38
	s_nop 1
	v_permlane32_swap_b32_e32 v39, v38
	s_and_saveexec_b64 s[24:25], s[6:7]
	s_cbranch_execz .LBB0_2297
	s_waitcnt lgkmcnt(0)
	v_add_f32_e32 v40, v38, v39
	v_lshlrev_b64 v[38:39], 6, v[66:67]
	v_lshl_add_u64 v[38:39], s[10:11], 0, v[38:39]
	v_lshl_add_u64 v[38:39], s[22:23], 2, v[38:39]
	s_lshl_b32 s92, s45, 2
	v_lshl_add_u64 v[38:39], v[38:39], 0, s[92:93]
	global_store_dword v[38:39], v40, off
; __device__ __forceinline__ float xor16(float v) { return __int_as_float(__builtin_amdgcn_ds_swizzle(__float_as_int(v), 0x401F)); }
; __device__ __forceinline__ float sigmoidf(float x) { return 1.f / (1.f + __expf(-x)); }
;   __device__ __forceinline__ void operator()(const f32x4 (&acc)[2][2][4][2], const g8::Unit& u, int ui, int wr, int wc, int fr, int fq) const {
;     ...
;         for (int bj = 0; bj < 2; ++bj) {
;           const f32x4 a = acc[ai][bj][m][0], b = acc[ai][bj][m][1];
;           float o0 = (a[0] + ba[bj].x) * sigmoidf(b[0] + bb[bj].x);
;           float o1 = (a[1] + ba[bj].y) * sigmoidf(b[1] + bb[bj].y);
;           float o2 = (a[2] + ba[bj].z) * sigmoidf(b[2] + bb[bj].z);
;           float o3 = (a[3] + ba[bj].w) * sigmoidf(b[3] + bb[bj].w);
;           *(h16x4*)(OB + row * 1024 + ocb + 64 * bj) = pack4(o0, o1, o2, o3);
;           ss += o0 * o0 + o1 * o1 + o2 * o2 + o3 * o3;
;         }
;         ss += xor16(ss);
;         ss += __shfl_xor(ss, 32);
;         if (fq == 0) ssqb[row * 16 + u.pn * 4 + wc] = ss;
.LBB0_2297:
	s_or_b64 exec, exec, s[24:25]
	v_add_f32_e32 v30, v30, v46
	v_add_f32_e32 v31, v31, v47
	v_mul_f32_e32 v30, 0xbfb8aa3b, v30
	v_mul_f32_e32 v31, 0xbfb8aa3b, v31
	v_exp_f32_e32 v30, v30
	v_exp_f32_e32 v31, v31
	s_mov_b64 s[2:3], 0xa0
	s_waitcnt lgkmcnt(0)
	v_lshl_add_u64 v[38:39], v[162:163], 0, s[2:3]
	v_add_f32_e32 v32, v32, v48
	v_pk_add_f32 v[30:31], v[30:31], 1.0 op_sel_hi:[1,0]
	v_add_f32_e32 v33, v33, v49
	v_div_scale_f32 v42, s[2:3], v31, v31, 1.0
	v_rcp_f32_e32 v43, v42
	v_mul_f32_e32 v32, 0xbfb8aa3b, v32
	v_mul_f32_e32 v33, 0xbfb8aa3b, v33
	v_exp_f32_e32 v32, v32
	v_fma_f32 v44, -v42, v43, 1.0
	v_fmac_f32_e32 v43, v44, v43
	v_div_scale_f32 v44, vcc, 1.0, v31, 1.0
	v_mul_f32_e32 v45, v44, v43
	v_fma_f32 v54, -v42, v45, v44
	v_fmac_f32_e32 v45, v54, v43
	v_fma_f32 v42, -v42, v45, v44
	v_div_fmas_f32 v42, v42, v43, v45
	v_div_fixup_f32 v31, v42, v31, 1.0
	v_div_scale_f32 v42, s[2:3], v30, v30, 1.0
	v_rcp_f32_e32 v43, v42
	v_exp_f32_e32 v33, v33
	v_pk_add_f32 v[26:27], v[26:27], v[50:51]
	v_add_f32_e32 v22, v22, v34
	v_fma_f32 v44, -v42, v43, 1.0
	v_fmac_f32_e32 v43, v44, v43
	v_div_scale_f32 v44, vcc, 1.0, v30, 1.0
	v_mul_f32_e32 v45, v44, v43
	v_fma_f32 v54, -v42, v45, v44
	v_fmac_f32_e32 v45, v54, v43
	v_fma_f32 v42, -v42, v45, v44
	v_div_fmas_f32 v42, v42, v43, v45
	v_div_fixup_f32 v30, v42, v30, 1.0
	v_pk_add_f32 v[32:33], v[32:33], 1.0 op_sel_hi:[1,0]
	v_pk_mul_f32 v[26:27], v[26:27], v[30:31]
	v_div_scale_f32 v31, s[2:3], v33, v33, 1.0
	v_rcp_f32_e32 v42, v31
	v_add_f32_e32 v23, v23, v35
	v_mul_f32_e32 v22, 0xbfb8aa3b, v22
	v_mul_f32_e32 v23, 0xbfb8aa3b, v23
	v_fma_f32 v43, -v31, v42, 1.0
	v_fmac_f32_e32 v42, v43, v42
	v_div_scale_f32 v43, vcc, 1.0, v33, 1.0
	v_mul_f32_e32 v44, v43, v42
	v_fma_f32 v45, -v31, v44, v43
	v_fmac_f32_e32 v44, v45, v42
	v_fma_f32 v31, -v31, v44, v43
	v_div_fmas_f32 v31, v31, v42, v44
	v_div_fixup_f32 v33, v31, v33, 1.0
	v_div_scale_f32 v31, s[2:3], v32, v32, 1.0
	v_rcp_f32_e32 v42, v31
	v_exp_f32_e32 v22, v22
	v_exp_f32_e32 v23, v23
	v_lshlrev_b64 v[40:41], 11, v[38:39]
	v_fma_f32 v43, -v31, v42, 1.0
	v_fmac_f32_e32 v42, v43, v42
	v_div_scale_f32 v43, vcc, 1.0, v32, 1.0
	v_mul_f32_e32 v44, v43, v42
	v_fma_f32 v45, -v31, v44, v43
	v_fmac_f32_e32 v44, v45, v42
	v_fma_f32 v31, -v31, v44, v43
	v_div_fmas_f32 v31, v31, v42, v44
	v_pk_add_f32 v[28:29], v[28:29], v[52:53]
	v_div_fixup_f32 v32, v31, v32, 1.0
	v_pk_mul_f32 v[28:29], v[28:29], v[32:33]
	v_lshl_add_u64 v[32:33], s[0:1], 0, v[40:41]
	v_cvt_pk_f16_f32 v30, v26, v27
	v_cvt_pk_f16_f32 v31, v28, v29
	v_lshl_add_u64 v[32:33], v[160:161], 1, v[32:33]
	v_pk_add_f32 v[22:23], v[22:23], 1.0 op_sel_hi:[1,0]
	global_store_dwordx2 v[32:33], v[30:31], off
	v_div_scale_f32 v30, s[2:3], v23, v23, 1.0
	v_rcp_f32_e32 v31, v30
	v_add_f32_e32 v24, v24, v36
	v_add_f32_e32 v25, v25, v37
	v_mul_f32_e32 v24, 0xbfb8aa3b, v24
	v_fma_f32 v40, -v30, v31, 1.0
	v_fmac_f32_e32 v31, v40, v31
	v_div_scale_f32 v40, vcc, 1.0, v23, 1.0
	v_mul_f32_e32 v41, v40, v31
	v_fma_f32 v42, -v30, v41, v40
	v_fmac_f32_e32 v41, v42, v31
	v_fma_f32 v30, -v30, v41, v40
	v_div_fmas_f32 v30, v30, v31, v41
	v_div_fixup_f32 v23, v30, v23, 1.0
	v_div_scale_f32 v30, s[2:3], v22, v22, 1.0
	v_rcp_f32_e32 v31, v30
	v_mul_f32_e32 v25, 0xbfb8aa3b, v25
	v_exp_f32_e32 v24, v24
	v_exp_f32_e32 v25, v25
	v_fma_f32 v40, -v30, v31, 1.0
	v_fmac_f32_e32 v31, v40, v31
	v_div_scale_f32 v40, vcc, 1.0, v22, 1.0
	v_mul_f32_e32 v41, v40, v31
	v_fma_f32 v42, -v30, v41, v40
	v_fmac_f32_e32 v41, v42, v31
	v_fma_f32 v30, -v30, v41, v40
	v_div_fmas_f32 v30, v30, v31, v41
	v_pk_add_f32 v[18:19], v[18:19], v[62:63]
	v_div_fixup_f32 v22, v30, v22, 1.0
	v_pk_add_f32 v[24:25], v[24:25], 1.0 op_sel_hi:[1,0]
	v_pk_mul_f32 v[18:19], v[18:19], v[22:23]
	v_div_scale_f32 v23, s[2:3], v25, v25, 1.0
	v_rcp_f32_e32 v30, v23
	v_pk_add_f32 v[20:21], v[20:21], v[64:65]
	v_pk_mul_f32 v[26:27], v[26:27], v[26:27]
	v_cvt_pk_f16_f32 v22, v18, v19
	v_fma_f32 v31, -v23, v30, 1.0
	v_fmac_f32_e32 v30, v31, v30
	v_div_scale_f32 v31, vcc, 1.0, v25, 1.0
	v_mul_f32_e32 v40, v31, v30
	v_fma_f32 v41, -v23, v40, v31
	v_fmac_f32_e32 v40, v41, v30
	v_fma_f32 v23, -v23, v40, v31
	v_div_fmas_f32 v23, v23, v30, v40
	v_div_fixup_f32 v25, v23, v25, 1.0
	v_div_scale_f32 v23, s[2:3], v24, v24, 1.0
	v_rcp_f32_e32 v30, v23
	v_pk_mul_f32 v[18:19], v[18:19], v[18:19]
	v_pk_mul_f32 v[28:29], v[28:29], v[28:29]
	v_add_f32_e32 v18, v18, v19
	v_fma_f32 v31, -v23, v30, 1.0
	v_fmac_f32_e32 v30, v31, v30
	v_div_scale_f32 v31, vcc, 1.0, v24, 1.0
	v_mul_f32_e32 v40, v31, v30
	v_fma_f32 v41, -v23, v40, v31
	v_fmac_f32_e32 v40, v41, v30
	v_fma_f32 v23, -v23, v40, v31
	v_div_fmas_f32 v23, v23, v30, v40
	v_div_fixup_f32 v24, v23, v24, 1.0
	v_pk_mul_f32 v[20:21], v[20:21], v[24:25]
	v_add_f32_e32 v19, v26, v27
	v_cvt_pk_f16_f32 v23, v20, v21
	v_pk_mul_f32 v[20:21], v[20:21], v[20:21]
	v_add_f32_e32 v19, v28, v19
	v_add_f32_e32 v18, v20, v18
	v_add_f32_e32 v18, v21, v18
	v_add_f32_e32 v19, v29, v19
	v_add_f32_e32 v18, v19, v18
	v_mov_b32_e32 v19, v18
	s_nop 1
	v_permlane16_swap_b32_e32 v19, v18
	global_store_dwordx2 v[32:33], v[22:23], off offset:128
	s_waitcnt lgkmcnt(0)
	v_add_f32_e32 v18, v18, v19
	v_mov_b32_e32 v19, v18
	s_nop 1
	v_permlane32_swap_b32_e32 v19, v18
	s_and_saveexec_b64 s[24:25], s[6:7]
	s_cbranch_execz .LBB0_2299
	s_waitcnt lgkmcnt(0)
	v_add_f32_e32 v20, v18, v19
	v_lshlrev_b64 v[18:19], 6, v[38:39]
	v_lshl_add_u64 v[18:19], s[10:11], 0, v[18:19]
	v_lshl_add_u64 v[18:19], s[22:23], 2, v[18:19]
	s_lshl_b32 s92, s45, 2
	v_lshl_add_u64 v[18:19], v[18:19], 0, s[92:93]
	global_store_dword v[18:19], v20, off
; __device__ __forceinline__ float xor16(float v) { return __int_as_float(__builtin_amdgcn_ds_swizzle(__float_as_int(v), 0x401F)); }
; __device__ __forceinline__ float sigmoidf(float x) { return 1.f / (1.f + __expf(-x)); }
; template <class Epi>
; __device__ __forceinline__ void gemm_phase(LAS unsigned char* lds, const h16* A, const h16* Bt, int K, const Order& S, const Epi& E) {
;     ...
;     E(acc, cur, ui, wr, wc, fr, fq);
;     if (!has_next) break;
; #pragma unroll
;     for (int a = 0; a < 2; ++a)
; #pragma unroll
;       for (int b = 0; b < 2; ++b)
; #pragma unroll
;         for (int m = 0; m < 4; ++m)
; #pragma unroll
;           for (int n = 0; n < 2; ++n) acc[a][b][m][n] = (f32x4){0.f, 0.f, 0.f, 0.f};
;     cur = nxt; cA = nA; cB = nB; ++ui;
;   __device__ __forceinline__ void operator()(const f32x4 (&acc)[2][2][4][2], const g8::Unit& u, int ui, int wr, int wc, int fr, int fq) const {
;     ...
;         for (int bj = 0; bj < 2; ++bj) {
;           const f32x4 a = acc[ai][bj][m][0], b = acc[ai][bj][m][1];
;           float o0 = (a[0] + ba[bj].x) * sigmoidf(b[0] + bb[bj].x);
;           float o1 = (a[1] + ba[bj].y) * sigmoidf(b[1] + bb[bj].y);
;           float o2 = (a[2] + ba[bj].z) * sigmoidf(b[2] + bb[bj].z);
;           float o3 = (a[3] + ba[bj].w) * sigmoidf(b[3] + bb[bj].w);
;           *(h16x4*)(OB + row * 1024 + ocb + 64 * bj) = pack4(o0, o1, o2, o3);
;           ss += o0 * o0 + o1 * o1 + o2 * o2 + o3 * o3;
;         }
;         ss += xor16(ss);
;         ss += __shfl_xor(ss, 32);
;         if (fq == 0) ssqb[row * 16 + u.pn * 4 + wc] = ss;
.LBB0_2299:
	s_or_b64 exec, exec, s[24:25]
	v_add_f32_e32 v14, v14, v46
	v_add_f32_e32 v15, v15, v47
	v_mul_f32_e32 v14, 0xbfb8aa3b, v14
	v_mul_f32_e32 v15, 0xbfb8aa3b, v15
	v_exp_f32_e32 v14, v14
	v_exp_f32_e32 v15, v15
	s_mov_b64 s[2:3], 0xb0
	s_waitcnt lgkmcnt(0)
	v_lshl_add_u64 v[18:19], v[162:163], 0, s[2:3]
	v_add_f32_e32 v16, v16, v48
	v_pk_add_f32 v[14:15], v[14:15], 1.0 op_sel_hi:[1,0]
	v_add_f32_e32 v17, v17, v49
	v_div_scale_f32 v22, s[2:3], v15, v15, 1.0
	v_rcp_f32_e32 v23, v22
	v_mul_f32_e32 v16, 0xbfb8aa3b, v16
	v_mul_f32_e32 v17, 0xbfb8aa3b, v17
	v_exp_f32_e32 v16, v16
	v_fma_f32 v24, -v22, v23, 1.0
	v_fmac_f32_e32 v23, v24, v23
	v_div_scale_f32 v24, vcc, 1.0, v15, 1.0
	v_mul_f32_e32 v25, v24, v23
	v_fma_f32 v26, -v22, v25, v24
	v_fmac_f32_e32 v25, v26, v23
	v_fma_f32 v22, -v22, v25, v24
	v_div_fmas_f32 v22, v22, v23, v25
	v_div_fixup_f32 v15, v22, v15, 1.0
	v_div_scale_f32 v22, s[2:3], v14, v14, 1.0
	v_rcp_f32_e32 v23, v22
	v_exp_f32_e32 v17, v17
	v_pk_add_f32 v[10:11], v[10:11], v[50:51]
	v_add_f32_e32 v6, v6, v34
	v_fma_f32 v24, -v22, v23, 1.0
	v_fmac_f32_e32 v23, v24, v23
	v_div_scale_f32 v24, vcc, 1.0, v14, 1.0
	v_mul_f32_e32 v25, v24, v23
	v_fma_f32 v26, -v22, v25, v24
	v_fmac_f32_e32 v25, v26, v23
	v_fma_f32 v22, -v22, v25, v24
	v_div_fmas_f32 v22, v22, v23, v25
	v_div_fixup_f32 v14, v22, v14, 1.0
	v_pk_add_f32 v[16:17], v[16:17], 1.0 op_sel_hi:[1,0]
	v_pk_mul_f32 v[10:11], v[10:11], v[14:15]
	v_div_scale_f32 v15, s[2:3], v17, v17, 1.0
	v_rcp_f32_e32 v22, v15
	v_add_f32_e32 v7, v7, v35
	v_mul_f32_e32 v6, 0xbfb8aa3b, v6
	v_mul_f32_e32 v7, 0xbfb8aa3b, v7
	v_fma_f32 v23, -v15, v22, 1.0
	v_fmac_f32_e32 v22, v23, v22
	v_div_scale_f32 v23, vcc, 1.0, v17, 1.0
	v_mul_f32_e32 v24, v23, v22
	v_fma_f32 v25, -v15, v24, v23
	v_fmac_f32_e32 v24, v25, v22
	v_fma_f32 v15, -v15, v24, v23
	v_div_fmas_f32 v15, v15, v22, v24
	v_div_fixup_f32 v17, v15, v17, 1.0
	v_div_scale_f32 v15, s[2:3], v16, v16, 1.0
	v_rcp_f32_e32 v22, v15
	v_exp_f32_e32 v6, v6
	v_exp_f32_e32 v7, v7
	v_lshlrev_b64 v[20:21], 11, v[18:19]
	v_fma_f32 v23, -v15, v22, 1.0
	v_fmac_f32_e32 v22, v23, v22
	v_div_scale_f32 v23, vcc, 1.0, v16, 1.0
	v_mul_f32_e32 v24, v23, v22
	v_fma_f32 v25, -v15, v24, v23
	v_fmac_f32_e32 v24, v25, v22
	v_fma_f32 v15, -v15, v24, v23
	v_div_fmas_f32 v15, v15, v22, v24
	v_pk_add_f32 v[12:13], v[12:13], v[52:53]
	v_div_fixup_f32 v16, v15, v16, 1.0
	v_pk_mul_f32 v[12:13], v[12:13], v[16:17]
	v_lshl_add_u64 v[16:17], s[0:1], 0, v[20:21]
	v_cvt_pk_f16_f32 v14, v10, v11
	v_cvt_pk_f16_f32 v15, v12, v13
	v_lshl_add_u64 v[16:17], v[160:161], 1, v[16:17]
	v_pk_add_f32 v[6:7], v[6:7], 1.0 op_sel_hi:[1,0]
	global_store_dwordx2 v[16:17], v[14:15], off
	v_div_scale_f32 v14, s[2:3], v7, v7, 1.0
	v_rcp_f32_e32 v15, v14
	v_add_f32_e32 v8, v8, v36
	v_add_f32_e32 v9, v9, v37
	v_mul_f32_e32 v8, 0xbfb8aa3b, v8
	v_fma_f32 v20, -v14, v15, 1.0
	v_fmac_f32_e32 v15, v20, v15
	v_div_scale_f32 v20, vcc, 1.0, v7, 1.0
	v_mul_f32_e32 v21, v20, v15
	v_fma_f32 v22, -v14, v21, v20
	v_fmac_f32_e32 v21, v22, v15
	v_fma_f32 v14, -v14, v21, v20
	v_div_fmas_f32 v14, v14, v15, v21
	v_div_fixup_f32 v7, v14, v7, 1.0
	v_div_scale_f32 v14, s[2:3], v6, v6, 1.0
	v_rcp_f32_e32 v15, v14
	v_mul_f32_e32 v9, 0xbfb8aa3b, v9
	v_exp_f32_e32 v8, v8
	v_exp_f32_e32 v9, v9
	v_fma_f32 v20, -v14, v15, 1.0
	v_fmac_f32_e32 v15, v20, v15
	v_div_scale_f32 v20, vcc, 1.0, v6, 1.0
	v_mul_f32_e32 v21, v20, v15
	v_fma_f32 v22, -v14, v21, v20
	v_fmac_f32_e32 v21, v22, v15
	v_fma_f32 v14, -v14, v21, v20
	v_div_fmas_f32 v14, v14, v15, v21
	v_pk_add_f32 v[2:3], v[2:3], v[62:63]
	v_div_fixup_f32 v6, v14, v6, 1.0
	v_pk_add_f32 v[8:9], v[8:9], 1.0 op_sel_hi:[1,0]
	v_pk_mul_f32 v[2:3], v[2:3], v[6:7]
	v_div_scale_f32 v7, s[2:3], v9, v9, 1.0
	v_rcp_f32_e32 v14, v7
	v_pk_add_f32 v[4:5], v[4:5], v[64:65]
	v_pk_mul_f32 v[10:11], v[10:11], v[10:11]
	v_cvt_pk_f16_f32 v6, v2, v3
	v_fma_f32 v15, -v7, v14, 1.0
	v_fmac_f32_e32 v14, v15, v14
	v_div_scale_f32 v15, vcc, 1.0, v9, 1.0
	v_mul_f32_e32 v20, v15, v14
	v_fma_f32 v21, -v7, v20, v15
	v_fmac_f32_e32 v20, v21, v14
	v_fma_f32 v7, -v7, v20, v15
	v_div_fmas_f32 v7, v7, v14, v20
	v_div_fixup_f32 v9, v7, v9, 1.0
	v_div_scale_f32 v7, s[2:3], v8, v8, 1.0
	v_rcp_f32_e32 v14, v7
	v_pk_mul_f32 v[2:3], v[2:3], v[2:3]
	v_pk_mul_f32 v[12:13], v[12:13], v[12:13]
	v_add_f32_e32 v2, v2, v3
	v_fma_f32 v15, -v7, v14, 1.0
	v_fmac_f32_e32 v14, v15, v14
	v_div_scale_f32 v15, vcc, 1.0, v8, 1.0
	v_mul_f32_e32 v20, v15, v14
	v_fma_f32 v21, -v7, v20, v15
	v_fmac_f32_e32 v20, v21, v14
	v_fma_f32 v7, -v7, v20, v15
	v_div_fmas_f32 v7, v7, v14, v20
	v_div_fixup_f32 v8, v7, v8, 1.0
	v_pk_mul_f32 v[4:5], v[4:5], v[8:9]
	v_add_f32_e32 v3, v10, v11
	v_cvt_pk_f16_f32 v7, v4, v5
	v_pk_mul_f32 v[4:5], v[4:5], v[4:5]
	v_add_f32_e32 v3, v12, v3
	v_add_f32_e32 v2, v4, v2
	v_add_f32_e32 v2, v5, v2
	v_add_f32_e32 v3, v13, v3
	v_add_f32_e32 v2, v3, v2
	v_mov_b32_e32 v3, v2
	s_nop 1
	v_permlane16_swap_b32_e32 v3, v2
	global_store_dwordx2 v[16:17], v[6:7], off offset:128
	s_waitcnt lgkmcnt(0)
	v_add_f32_e32 v2, v2, v3
	v_mov_b32_e32 v3, v2
	s_nop 1
	v_permlane32_swap_b32_e32 v3, v2
	s_and_saveexec_b64 s[24:25], s[6:7]
	s_cbranch_execz .LBB0_2276
	s_waitcnt lgkmcnt(0)
	v_add_f32_e32 v4, v2, v3
	v_lshlrev_b64 v[2:3], 6, v[18:19]
	v_lshl_add_u64 v[2:3], s[10:11], 0, v[2:3]
	v_lshl_add_u64 v[2:3], s[22:23], 2, v[2:3]
	s_lshl_b32 s92, s45, 2
	v_lshl_add_u64 v[2:3], v[2:3], 0, s[92:93]
	global_store_dword v[2:3], v4, off
	s_branch .LBB0_2276

; __device__ __forceinline__ float xor16(float v) { return __int_as_float(__builtin_amdgcn_ds_swizzle(__float_as_int(v), 0x401F)); }
;   __device__ __forceinline__ void operator()(const f32x4 (&acc)[2][2][4][2], const g8::Unit& u, int ui, int wr, int wc, int fr, int fq) const {
; #pragma unroll
;     for (int ai = 0; ai < 2; ++ai)
; #pragma unroll
;       for (int m = 0; m < 4; ++m) {
;         const size_t row = (size_t)u.pm * 256 + 128 * ai + 64 * wr + 16 * m + fr;
;         const size_t base = row * DM + 256 * u.pn + 32 * wc + 8 * fq;
;         float ss = 0.f;
; #pragma unroll
;         for (int bj = 0; bj < 2; ++bj) {
;           const size_t idx = base + 128 * bj;
;           const h16x8 xv = *(const h16x8*)(xb + idx);
;           f32x4 x0 = acc[ai][bj][m][0], x1 = acc[ai][bj][m][1];
; #pragma unroll
;           for (int j = 0; j < 4; ++j) { x0[j] += (float)xv[j]; x1[j] += (float)xv[4 + j]; ss += x0[j] * x0[j] + x1[j] * x1[j]; }
;           if (final_out) {
;             __builtin_nontemporal_store(x0, (f32x4*)(xo + idx));
;             __builtin_nontemporal_store(x1, (f32x4*)(xo + idx + 4));
;           } else {
;             *(h16x8*)(xb + idx) = pack8(x0, x1);
;           }
;         }
;         ss += xor16(ss);
;         ss += __shfl_xor(ss, 32);
;         if (fq == 0) ssq[row * 16 + u.pn * 4 + wc] = ss;
;       }
.LBB0_2381:
	s_ashr_i32 s23, s22, 31
	s_lshl_b64 s[20:21], s[22:23], 8
	v_and_b32_e32 v156, 64, v199
	v_lshl_add_u64 v[2:3], s[20:21], 0, v[136:137]
	s_lshl_b32 s3, s2, 8
	v_xor_b32_e32 v0, 32, v199
	v_add_u32_e32 v156, 64, v156
	s_ashr_i32 s13, s3, 31
	v_cmp_lt_i32_e32 vcc, v0, v156
	v_lshlrev_b64 v[156:157], 11, v[2:3]
	v_mov_b32_e32 v155, s13
	v_or_b32_e32 v154, s3, v138
	v_lshl_add_u64 v[156:157], s[0:1], 0, v[156:157]
	v_lshl_add_u64 v[156:157], v[154:155], 1, v[156:157]
	v_cndmask_b32_e32 v0, v199, v0, vcc
	v_lshlrev_b32_e32 v0, 2, v0
	s_lshl_b32 s20, s2, 2
	s_ashr_i32 s21, s20, 31
	global_load_dwordx4 v[166:169], v[156:157], off
	global_load_dwordx4 v[170:173], v[156:157], off offset:256
	s_mov_b32 s3, 0
	s_mov_b32 s2, 0x8000
	v_lshl_add_u64 v[242:243], v[156:157], 0, s[2:3]
	global_load_dwordx4 v[174:177], v[242:243], off
	global_load_dwordx4 v[178:181], v[242:243], off offset:256
	s_mov_b32 s2, 0x10000
	v_lshl_add_u64 v[244:245], v[156:157], 0, s[2:3]
	global_load_dwordx4 v[182:185], v[244:245], off
	global_load_dwordx4 v[186:189], v[244:245], off offset:256
	s_mov_b32 s2, 0x18000
	v_lshl_add_u64 v[242:243], v[156:157], 0, s[2:3]
	global_load_dwordx4 v[202:205], v[242:243], off
	global_load_dwordx4 v[206:209], v[242:243], off offset:256
	s_mov_b32 s2, 0x40000
	v_lshl_add_u64 v[244:245], v[156:157], 0, s[2:3]
	global_load_dwordx4 v[210:213], v[244:245], off
	global_load_dwordx4 v[214:217], v[244:245], off offset:256
	s_mov_b32 s2, 0x48000
	v_lshl_add_u64 v[242:243], v[156:157], 0, s[2:3]
	global_load_dwordx4 v[218:221], v[242:243], off
	global_load_dwordx4 v[222:225], v[242:243], off offset:256
	s_mov_b32 s2, 0x50000
	v_lshl_add_u64 v[244:245], v[156:157], 0, s[2:3]
	global_load_dwordx4 v[226:229], v[244:245], off
	global_load_dwordx4 v[230:233], v[244:245], off offset:256
	s_mov_b32 s2, 0x58000
	v_lshl_add_u64 v[242:243], v[156:157], 0, s[2:3]
	global_load_dwordx4 v[234:237], v[242:243], off
	global_load_dwordx4 v[238:241], v[242:243], off offset:256
	s_waitcnt vmcnt(15)
	v_cvt_f32_f16_e32 v164, v166
	v_cvt_f32_f16_sdwa v165, v166 dst_sel:DWORD dst_unused:UNUSED_PAD src0_sel:WORD_1
	v_cvt_f32_f16_e32 v160, v167
	v_cvt_f32_f16_sdwa v161, v167 dst_sel:DWORD dst_unused:UNUSED_PAD src0_sel:WORD_1
	v_pk_add_f32 v[164:165], v[128:129], v[164:165]
	s_nop 0
	v_cvt_pk_f16_f32 v128, v164, v165
	v_pk_add_f32 v[160:161], v[130:131], v[160:161]
	v_cvt_f32_f16_e32 v130, v168
	v_cvt_f32_f16_sdwa v131, v168 dst_sel:DWORD dst_unused:UNUSED_PAD src0_sel:WORD_1
	v_cvt_f32_f16_e32 v162, v169
	v_cvt_f32_f16_sdwa v163, v169 dst_sel:DWORD dst_unused:UNUSED_PAD src0_sel:WORD_1
	v_cvt_pk_f16_f32 v129, v160, v161
	v_pk_add_f32 v[130:131], v[124:125], v[130:131]
	v_pk_add_f32 v[162:163], v[126:127], v[162:163]
	v_pk_mul_f32 v[124:125], v[130:131], v[130:131]
	v_cvt_pk_f16_f32 v130, v130, v131
	v_cvt_pk_f16_f32 v131, v162, v163
	global_store_dwordx4 v[156:157], v[128:131], off
	s_nop 0
	v_pk_mul_f32 v[126:127], v[162:163], v[162:163]
	v_pk_fma_f32 v[124:125], v[164:165], v[164:165], v[124:125]
	v_pk_fma_f32 v[126:127], v[160:161], v[160:161], v[126:127]
	s_waitcnt vmcnt(15)
	v_cvt_f32_f16_e32 v160, v170
	v_cvt_f32_f16_sdwa v161, v170 dst_sel:DWORD dst_unused:UNUSED_PAD src0_sel:WORD_1
	v_cvt_f32_f16_e32 v128, v171
	v_cvt_f32_f16_sdwa v129, v171 dst_sel:DWORD dst_unused:UNUSED_PAD src0_sel:WORD_1
	v_pk_add_f32 v[160:161], v[120:121], v[160:161]
	s_nop 0
	v_cvt_pk_f16_f32 v120, v160, v161
	v_pk_add_f32 v[128:129], v[122:123], v[128:129]
	v_cvt_f32_f16_e32 v122, v172
	v_cvt_f32_f16_sdwa v123, v172 dst_sel:DWORD dst_unused:UNUSED_PAD src0_sel:WORD_1
	v_cvt_pk_f16_f32 v121, v128, v129
	v_pk_add_f32 v[116:117], v[116:117], v[122:123]
	s_nop 0
	v_pk_mul_f32 v[122:123], v[116:117], v[116:117]
	s_nop 0
	v_pk_fma_f32 v[160:161], v[160:161], v[160:161], v[122:123]
	v_cvt_pk_f16_f32 v122, v116, v117
	v_cvt_f32_f16_e32 v116, v173
	v_cvt_f32_f16_sdwa v117, v173 dst_sel:DWORD dst_unused:UNUSED_PAD src0_sel:WORD_1
	v_add_f32_e32 v123, v124, v125
	v_add_f32_e32 v123, v126, v123
	v_add_f32_e32 v123, v127, v123
	v_pk_add_f32 v[116:117], v[118:119], v[116:117]
	v_add_f32_e32 v123, v160, v123
	v_pk_mul_f32 v[118:119], v[116:117], v[116:117]
	v_add_f32_e32 v123, v161, v123
	v_pk_fma_f32 v[118:119], v[128:129], v[128:129], v[118:119]
	s_nop 0
	v_add_f32_e32 v118, v118, v123
	v_add_f32_e32 v118, v119, v118
	v_cvt_pk_f16_f32 v123, v116, v117
	v_mov_b32_e32 v116, v118
	s_nop 1
	v_permlane16_swap_b32_e32 v116, v118
	global_store_dwordx4 v[156:157], v[120:123], off offset:256
	s_waitcnt lgkmcnt(0)
	v_add_f32_e32 v116, v118, v116
	v_mov_b32_e32 v117, v116
	s_nop 1
	v_permlane32_swap_b32_e32 v117, v116
	s_and_saveexec_b64 s[22:23], s[6:7]
	s_cbranch_execz .LBB0_2383
	s_waitcnt lgkmcnt(0)
	v_add_f32_e32 v118, v116, v117
	v_lshlrev_b64 v[116:117], 6, v[2:3]
	v_lshl_add_u64 v[116:117], s[10:11], 0, v[116:117]
	v_lshl_add_u64 v[116:117], s[20:21], 2, v[116:117]
	s_lshl_b32 s92, s45, 2
	v_lshl_add_u64 v[116:117], v[116:117], 0, s[92:93]
	global_store_dword v[116:117], v118, off
; __device__ __forceinline__ float xor16(float v) { return __int_as_float(__builtin_amdgcn_ds_swizzle(__float_as_int(v), 0x401F)); }
;   __device__ __forceinline__ void operator()(const f32x4 (&acc)[2][2][4][2], const g8::Unit& u, int ui, int wr, int wc, int fr, int fq) const {
; #pragma unroll
;     for (int ai = 0; ai < 2; ++ai)
; #pragma unroll
;       for (int m = 0; m < 4; ++m) {
;         const size_t row = (size_t)u.pm * 256 + 128 * ai + 64 * wr + 16 * m + fr;
;         const size_t base = row * DM + 256 * u.pn + 32 * wc + 8 * fq;
;         float ss = 0.f;
; #pragma unroll
;         for (int bj = 0; bj < 2; ++bj) {
;           const size_t idx = base + 128 * bj;
;           const h16x8 xv = *(const h16x8*)(xb + idx);
;           f32x4 x0 = acc[ai][bj][m][0], x1 = acc[ai][bj][m][1];
; #pragma unroll
;           for (int j = 0; j < 4; ++j) { x0[j] += (float)xv[j]; x1[j] += (float)xv[4 + j]; ss += x0[j] * x0[j] + x1[j] * x1[j]; }
;           if (final_out) {
;             __builtin_nontemporal_store(x0, (f32x4*)(xo + idx));
;             __builtin_nontemporal_store(x1, (f32x4*)(xo + idx + 4));
;           } else {
;             *(h16x8*)(xb + idx) = pack8(x0, x1);
;           }
;         }
;         ss += xor16(ss);
;         ss += __shfl_xor(ss, 32);
;         if (fq == 0) ssq[row * 16 + u.pn * 4 + wc] = ss;
;       }
.LBB0_2383:
	s_or_b64 exec, exec, s[22:23]
	v_or_b32_e32 v116, 16, v2
	s_waitcnt lgkmcnt(0)
	v_mov_b32_e32 v117, v3
	v_lshlrev_b64 v[118:119], 11, v[116:117]
	v_lshl_add_u64 v[118:119], s[0:1], 0, v[118:119]
	v_lshl_add_u64 v[118:119], v[154:155], 1, v[118:119]
	s_nop 0
	s_waitcnt vmcnt(15)
	v_cvt_f32_f16_e32 v124, v174
	v_cvt_f32_f16_sdwa v125, v174 dst_sel:DWORD dst_unused:UNUSED_PAD src0_sel:WORD_1
	v_cvt_f32_f16_e32 v120, v175
	v_cvt_f32_f16_sdwa v121, v175 dst_sel:DWORD dst_unused:UNUSED_PAD src0_sel:WORD_1
	v_pk_add_f32 v[124:125], v[112:113], v[124:125]
	s_nop 0
	v_cvt_pk_f16_f32 v112, v124, v125
	v_pk_add_f32 v[120:121], v[114:115], v[120:121]
	v_cvt_f32_f16_e32 v114, v176
	v_cvt_f32_f16_sdwa v115, v176 dst_sel:DWORD dst_unused:UNUSED_PAD src0_sel:WORD_1
	v_cvt_f32_f16_e32 v122, v177
	v_cvt_f32_f16_sdwa v123, v177 dst_sel:DWORD dst_unused:UNUSED_PAD src0_sel:WORD_1
	v_cvt_pk_f16_f32 v113, v120, v121
	v_pk_add_f32 v[114:115], v[108:109], v[114:115]
	v_pk_add_f32 v[122:123], v[110:111], v[122:123]
	v_pk_mul_f32 v[108:109], v[114:115], v[114:115]
	v_cvt_pk_f16_f32 v114, v114, v115
	v_cvt_pk_f16_f32 v115, v122, v123
	global_store_dwordx4 v[118:119], v[112:115], off
	s_nop 0
	v_pk_mul_f32 v[110:111], v[122:123], v[122:123]
	v_pk_fma_f32 v[108:109], v[124:125], v[124:125], v[108:109]
	v_pk_fma_f32 v[110:111], v[120:121], v[120:121], v[110:111]
	s_waitcnt vmcnt(15)
	v_cvt_f32_f16_e32 v120, v178
	v_cvt_f32_f16_sdwa v121, v178 dst_sel:DWORD dst_unused:UNUSED_PAD src0_sel:WORD_1
	v_cvt_f32_f16_e32 v112, v179
	v_cvt_f32_f16_sdwa v113, v179 dst_sel:DWORD dst_unused:UNUSED_PAD src0_sel:WORD_1
	v_pk_add_f32 v[120:121], v[104:105], v[120:121]
	s_nop 0
	v_cvt_pk_f16_f32 v104, v120, v121
	v_pk_add_f32 v[112:113], v[106:107], v[112:113]
	v_cvt_f32_f16_e32 v106, v180
	v_cvt_f32_f16_sdwa v107, v180 dst_sel:DWORD dst_unused:UNUSED_PAD src0_sel:WORD_1
	v_cvt_pk_f16_f32 v105, v112, v113
	v_pk_add_f32 v[100:101], v[100:101], v[106:107]
	s_nop 0
	v_pk_mul_f32 v[106:107], v[100:101], v[100:101]
	s_nop 0
	v_pk_fma_f32 v[120:121], v[120:121], v[120:121], v[106:107]
	v_cvt_pk_f16_f32 v106, v100, v101
	v_cvt_f32_f16_e32 v100, v181
	v_cvt_f32_f16_sdwa v101, v181 dst_sel:DWORD dst_unused:UNUSED_PAD src0_sel:WORD_1
	v_add_f32_e32 v107, v108, v109
	v_add_f32_e32 v107, v110, v107
	v_add_f32_e32 v107, v111, v107
	v_pk_add_f32 v[100:101], v[102:103], v[100:101]
	v_add_f32_e32 v107, v120, v107
	v_pk_mul_f32 v[102:103], v[100:101], v[100:101]
	v_add_f32_e32 v107, v121, v107
	v_pk_fma_f32 v[102:103], v[112:113], v[112:113], v[102:103]
	s_nop 0
	v_add_f32_e32 v102, v102, v107
	v_add_f32_e32 v102, v103, v102
	v_cvt_pk_f16_f32 v107, v100, v101
	v_mov_b32_e32 v100, v102
	s_nop 1
	v_permlane16_swap_b32_e32 v100, v102
	global_store_dwordx4 v[118:119], v[104:107], off offset:256
	s_waitcnt lgkmcnt(0)
	v_add_f32_e32 v100, v102, v100
	v_mov_b32_e32 v101, v100
	s_nop 1
	v_permlane32_swap_b32_e32 v101, v100
	s_and_saveexec_b64 s[22:23], s[6:7]
	s_cbranch_execz .LBB0_2385
	s_waitcnt lgkmcnt(0)
	v_add_f32_e32 v102, v100, v101
	v_lshlrev_b64 v[100:101], 6, v[116:117]
	v_lshl_add_u64 v[100:101], s[10:11], 0, v[100:101]
	v_lshl_add_u64 v[100:101], s[20:21], 2, v[100:101]
	s_lshl_b32 s92, s45, 2
	v_lshl_add_u64 v[100:101], v[100:101], 0, s[92:93]
	global_store_dword v[100:101], v102, off
.LBB0_2385:
	s_or_b64 exec, exec, s[22:23]
	v_or_b32_e32 v100, 32, v2
	s_waitcnt lgkmcnt(0)
	v_mov_b32_e32 v101, v3
	v_lshlrev_b64 v[102:103], 11, v[100:101]
	v_lshl_add_u64 v[102:103], s[0:1], 0, v[102:103]
	v_lshl_add_u64 v[102:103], v[154:155], 1, v[102:103]
	s_nop 0
	s_waitcnt vmcnt(15)
	v_cvt_f32_f16_e32 v108, v182
	v_cvt_f32_f16_sdwa v109, v182 dst_sel:DWORD dst_unused:UNUSED_PAD src0_sel:WORD_1
	v_cvt_f32_f16_e32 v104, v183
	v_cvt_f32_f16_sdwa v105, v183 dst_sel:DWORD dst_unused:UNUSED_PAD src0_sel:WORD_1
	v_pk_add_f32 v[108:109], v[96:97], v[108:109]
	s_nop 0
	v_cvt_pk_f16_f32 v96, v108, v109
	v_pk_add_f32 v[104:105], v[98:99], v[104:105]
	v_cvt_f32_f16_e32 v98, v184
	v_cvt_f32_f16_sdwa v99, v184 dst_sel:DWORD dst_unused:UNUSED_PAD src0_sel:WORD_1
	v_cvt_f32_f16_e32 v106, v185
	v_cvt_f32_f16_sdwa v107, v185 dst_sel:DWORD dst_unused:UNUSED_PAD src0_sel:WORD_1
	v_cvt_pk_f16_f32 v97, v104, v105
	v_pk_add_f32 v[98:99], v[92:93], v[98:99]
	v_pk_add_f32 v[106:107], v[94:95], v[106:107]
	v_pk_mul_f32 v[92:93], v[98:99], v[98:99]
	v_cvt_pk_f16_f32 v98, v98, v99
	v_cvt_pk_f16_f32 v99, v106, v107
	global_store_dwordx4 v[102:103], v[96:99], off
	s_nop 0
	v_pk_mul_f32 v[94:95], v[106:107], v[106:107]
	v_pk_fma_f32 v[92:93], v[108:109], v[108:109], v[92:93]
	v_pk_fma_f32 v[94:95], v[104:105], v[104:105], v[94:95]
	s_waitcnt vmcnt(15)
	v_cvt_f32_f16_e32 v104, v186
	v_cvt_f32_f16_sdwa v105, v186 dst_sel:DWORD dst_unused:UNUSED_PAD src0_sel:WORD_1
	v_cvt_f32_f16_e32 v96, v187
	v_cvt_f32_f16_sdwa v97, v187 dst_sel:DWORD dst_unused:UNUSED_PAD src0_sel:WORD_1
	v_pk_add_f32 v[104:105], v[88:89], v[104:105]
	s_nop 0
	v_cvt_pk_f16_f32 v88, v104, v105
	v_pk_add_f32 v[96:97], v[90:91], v[96:97]
	v_cvt_f32_f16_e32 v90, v188
	v_cvt_f32_f16_sdwa v91, v188 dst_sel:DWORD dst_unused:UNUSED_PAD src0_sel:WORD_1
	v_cvt_pk_f16_f32 v89, v96, v97
	v_pk_add_f32 v[84:85], v[84:85], v[90:91]
	s_nop 0
	v_pk_mul_f32 v[90:91], v[84:85], v[84:85]
	s_nop 0
	v_pk_fma_f32 v[104:105], v[104:105], v[104:105], v[90:91]
	v_cvt_pk_f16_f32 v90, v84, v85
	v_cvt_f32_f16_e32 v84, v189
	v_cvt_f32_f16_sdwa v85, v189 dst_sel:DWORD dst_unused:UNUSED_PAD src0_sel:WORD_1
	v_add_f32_e32 v91, v92, v93
	v_add_f32_e32 v91, v94, v91
	v_add_f32_e32 v91, v95, v91
	v_pk_add_f32 v[84:85], v[86:87], v[84:85]
	v_add_f32_e32 v91, v104, v91
	v_pk_mul_f32 v[86:87], v[84:85], v[84:85]
	v_add_f32_e32 v91, v105, v91
	v_pk_fma_f32 v[86:87], v[96:97], v[96:97], v[86:87]
	s_nop 0
	v_add_f32_e32 v86, v86, v91
	v_add_f32_e32 v86, v87, v86
	v_cvt_pk_f16_f32 v91, v84, v85
	v_mov_b32_e32 v84, v86
	s_nop 1
	v_permlane16_swap_b32_e32 v84, v86
	global_store_dwordx4 v[102:103], v[88:91], off offset:256
	s_waitcnt lgkmcnt(0)
	v_add_f32_e32 v84, v86, v84
	v_mov_b32_e32 v85, v84
	s_nop 1
	v_permlane32_swap_b32_e32 v85, v84
	s_and_saveexec_b64 s[22:23], s[6:7]
	s_cbranch_execz .LBB0_2387
	s_waitcnt lgkmcnt(0)
	v_add_f32_e32 v86, v84, v85
	v_lshlrev_b64 v[84:85], 6, v[100:101]
	v_lshl_add_u64 v[84:85], s[10:11], 0, v[84:85]
	v_lshl_add_u64 v[84:85], s[20:21], 2, v[84:85]
	s_lshl_b32 s92, s45, 2
	v_lshl_add_u64 v[84:85], v[84:85], 0, s[92:93]
	global_store_dword v[84:85], v86, off
; __device__ __forceinline__ float xor16(float v) { return __int_as_float(__builtin_amdgcn_ds_swizzle(__float_as_int(v), 0x401F)); }
;   __device__ __forceinline__ void operator()(const f32x4 (&acc)[2][2][4][2], const g8::Unit& u, int ui, int wr, int wc, int fr, int fq) const {
; #pragma unroll
;     for (int ai = 0; ai < 2; ++ai)
; #pragma unroll
;       for (int m = 0; m < 4; ++m) {
;         const size_t row = (size_t)u.pm * 256 + 128 * ai + 64 * wr + 16 * m + fr;
;         const size_t base = row * DM + 256 * u.pn + 32 * wc + 8 * fq;
;         float ss = 0.f;
; #pragma unroll
;         for (int bj = 0; bj < 2; ++bj) {
;           const size_t idx = base + 128 * bj;
;           const h16x8 xv = *(const h16x8*)(xb + idx);
;           f32x4 x0 = acc[ai][bj][m][0], x1 = acc[ai][bj][m][1];
; #pragma unroll
;           for (int j = 0; j < 4; ++j) { x0[j] += (float)xv[j]; x1[j] += (float)xv[4 + j]; ss += x0[j] * x0[j] + x1[j] * x1[j]; }
;           if (final_out) {
;             __builtin_nontemporal_store(x0, (f32x4*)(xo + idx));
;             __builtin_nontemporal_store(x1, (f32x4*)(xo + idx + 4));
;           } else {
;             *(h16x8*)(xb + idx) = pack8(x0, x1);
;           }
;         }
;         ss += xor16(ss);
;         ss += __shfl_xor(ss, 32);
;         if (fq == 0) ssq[row * 16 + u.pn * 4 + wc] = ss;
;       }
.LBB0_2387:
	s_or_b64 exec, exec, s[22:23]
	v_or_b32_e32 v84, 48, v2
	s_waitcnt lgkmcnt(0)
	v_mov_b32_e32 v85, v3
	v_lshlrev_b64 v[86:87], 11, v[84:85]
	v_lshl_add_u64 v[86:87], s[0:1], 0, v[86:87]
	v_lshl_add_u64 v[86:87], v[154:155], 1, v[86:87]
	s_nop 0
	s_waitcnt vmcnt(15)
	v_cvt_f32_f16_e32 v92, v202
	v_cvt_f32_f16_sdwa v93, v202 dst_sel:DWORD dst_unused:UNUSED_PAD src0_sel:WORD_1
	v_cvt_f32_f16_e32 v88, v203
	v_cvt_f32_f16_sdwa v89, v203 dst_sel:DWORD dst_unused:UNUSED_PAD src0_sel:WORD_1
	v_pk_add_f32 v[92:93], v[80:81], v[92:93]
	s_nop 0
	v_cvt_pk_f16_f32 v80, v92, v93
	v_pk_add_f32 v[88:89], v[82:83], v[88:89]
	v_cvt_f32_f16_e32 v82, v204
	v_cvt_f32_f16_sdwa v83, v204 dst_sel:DWORD dst_unused:UNUSED_PAD src0_sel:WORD_1
	v_cvt_f32_f16_e32 v90, v205
	v_cvt_f32_f16_sdwa v91, v205 dst_sel:DWORD dst_unused:UNUSED_PAD src0_sel:WORD_1
	v_cvt_pk_f16_f32 v81, v88, v89
	v_pk_add_f32 v[82:83], v[76:77], v[82:83]
	v_pk_add_f32 v[90:91], v[78:79], v[90:91]
	v_pk_mul_f32 v[76:77], v[82:83], v[82:83]
	v_cvt_pk_f16_f32 v82, v82, v83
	v_cvt_pk_f16_f32 v83, v90, v91
	global_store_dwordx4 v[86:87], v[80:83], off
	s_nop 0
	v_pk_mul_f32 v[78:79], v[90:91], v[90:91]
	v_pk_fma_f32 v[76:77], v[92:93], v[92:93], v[76:77]
	v_pk_fma_f32 v[78:79], v[88:89], v[88:89], v[78:79]
	s_waitcnt vmcnt(15)
	v_cvt_f32_f16_e32 v88, v206
	v_cvt_f32_f16_sdwa v89, v206 dst_sel:DWORD dst_unused:UNUSED_PAD src0_sel:WORD_1
	v_cvt_f32_f16_e32 v80, v207
	v_cvt_f32_f16_sdwa v81, v207 dst_sel:DWORD dst_unused:UNUSED_PAD src0_sel:WORD_1
	v_pk_add_f32 v[88:89], v[72:73], v[88:89]
	s_nop 0
	v_cvt_pk_f16_f32 v72, v88, v89
	v_pk_add_f32 v[80:81], v[74:75], v[80:81]
	v_cvt_f32_f16_e32 v74, v208
	v_cvt_f32_f16_sdwa v75, v208 dst_sel:DWORD dst_unused:UNUSED_PAD src0_sel:WORD_1
	v_cvt_pk_f16_f32 v73, v80, v81
	v_pk_add_f32 v[68:69], v[68:69], v[74:75]
	s_nop 0
	v_pk_mul_f32 v[74:75], v[68:69], v[68:69]
	s_nop 0
	v_pk_fma_f32 v[88:89], v[88:89], v[88:89], v[74:75]
	v_cvt_pk_f16_f32 v74, v68, v69
	v_cvt_f32_f16_e32 v68, v209
	v_cvt_f32_f16_sdwa v69, v209 dst_sel:DWORD dst_unused:UNUSED_PAD src0_sel:WORD_1
	v_add_f32_e32 v75, v76, v77
	v_add_f32_e32 v75, v78, v75
	v_add_f32_e32 v75, v79, v75
	v_pk_add_f32 v[68:69], v[70:71], v[68:69]
	v_add_f32_e32 v75, v88, v75
	v_pk_mul_f32 v[70:71], v[68:69], v[68:69]
	v_add_f32_e32 v75, v89, v75
	v_pk_fma_f32 v[70:71], v[80:81], v[80:81], v[70:71]
	s_nop 0
	v_add_f32_e32 v70, v70, v75
	v_add_f32_e32 v70, v71, v70
	v_cvt_pk_f16_f32 v75, v68, v69
	v_mov_b32_e32 v68, v70
	s_nop 1
	v_permlane16_swap_b32_e32 v68, v70
	global_store_dwordx4 v[86:87], v[72:75], off offset:256
	s_waitcnt lgkmcnt(0)
	v_add_f32_e32 v68, v70, v68
	v_mov_b32_e32 v69, v68
	s_nop 1
	v_permlane32_swap_b32_e32 v69, v68
	s_and_saveexec_b64 s[22:23], s[6:7]
	s_cbranch_execz .LBB0_2389
	s_waitcnt lgkmcnt(0)
	v_add_f32_e32 v70, v68, v69
	v_lshlrev_b64 v[68:69], 6, v[84:85]
	v_lshl_add_u64 v[68:69], s[10:11], 0, v[68:69]
	v_lshl_add_u64 v[68:69], s[20:21], 2, v[68:69]
	s_lshl_b32 s92, s45, 2
	v_lshl_add_u64 v[68:69], v[68:69], 0, s[92:93]
	global_store_dword v[68:69], v70, off
.LBB0_2389:
	s_or_b64 exec, exec, s[22:23]
	s_waitcnt lgkmcnt(0)
	v_lshl_add_u64 v[68:69], v[2:3], 0, s[94:95]
	v_lshlrev_b64 v[70:71], 11, v[68:69]
	v_lshl_add_u64 v[70:71], s[0:1], 0, v[70:71]
	v_lshl_add_u64 v[70:71], v[154:155], 1, v[70:71]
	s_nop 0
	s_waitcnt vmcnt(15)
	v_cvt_f32_f16_e32 v76, v210
	v_cvt_f32_f16_sdwa v77, v210 dst_sel:DWORD dst_unused:UNUSED_PAD src0_sel:WORD_1
	v_cvt_f32_f16_e32 v72, v211
	v_cvt_f32_f16_sdwa v73, v211 dst_sel:DWORD dst_unused:UNUSED_PAD src0_sel:WORD_1
	v_pk_add_f32 v[76:77], v[64:65], v[76:77]
	s_nop 0
	v_cvt_pk_f16_f32 v64, v76, v77
	v_pk_add_f32 v[72:73], v[66:67], v[72:73]
	v_cvt_f32_f16_e32 v66, v212
	v_cvt_f32_f16_sdwa v67, v212 dst_sel:DWORD dst_unused:UNUSED_PAD src0_sel:WORD_1
	v_cvt_f32_f16_e32 v74, v213
	v_cvt_f32_f16_sdwa v75, v213 dst_sel:DWORD dst_unused:UNUSED_PAD src0_sel:WORD_1
	v_cvt_pk_f16_f32 v65, v72, v73
	v_pk_add_f32 v[66:67], v[60:61], v[66:67]
	v_pk_add_f32 v[74:75], v[62:63], v[74:75]
	v_pk_mul_f32 v[60:61], v[66:67], v[66:67]
	v_cvt_pk_f16_f32 v66, v66, v67
	v_cvt_pk_f16_f32 v67, v74, v75
	global_store_dwordx4 v[70:71], v[64:67], off
	s_nop 0
	v_pk_mul_f32 v[62:63], v[74:75], v[74:75]
	v_pk_fma_f32 v[60:61], v[76:77], v[76:77], v[60:61]
	v_pk_fma_f32 v[62:63], v[72:73], v[72:73], v[62:63]
	s_waitcnt vmcnt(15)
	v_cvt_f32_f16_e32 v72, v214
	v_cvt_f32_f16_sdwa v73, v214 dst_sel:DWORD dst_unused:UNUSED_PAD src0_sel:WORD_1
	v_cvt_f32_f16_e32 v64, v215
	v_cvt_f32_f16_sdwa v65, v215 dst_sel:DWORD dst_unused:UNUSED_PAD src0_sel:WORD_1
	v_pk_add_f32 v[72:73], v[56:57], v[72:73]
	s_nop 0
	v_cvt_pk_f16_f32 v56, v72, v73
	v_pk_add_f32 v[64:65], v[58:59], v[64:65]
	v_cvt_f32_f16_e32 v58, v216
	v_cvt_f32_f16_sdwa v59, v216 dst_sel:DWORD dst_unused:UNUSED_PAD src0_sel:WORD_1
	v_cvt_pk_f16_f32 v57, v64, v65
	v_pk_add_f32 v[52:53], v[52:53], v[58:59]
	s_nop 0
	v_pk_mul_f32 v[58:59], v[52:53], v[52:53]
	s_nop 0
	v_pk_fma_f32 v[72:73], v[72:73], v[72:73], v[58:59]
	v_cvt_pk_f16_f32 v58, v52, v53
	v_cvt_f32_f16_e32 v52, v217
	v_cvt_f32_f16_sdwa v53, v217 dst_sel:DWORD dst_unused:UNUSED_PAD src0_sel:WORD_1
	v_add_f32_e32 v59, v60, v61
	v_add_f32_e32 v59, v62, v59
	v_add_f32_e32 v59, v63, v59
	v_pk_add_f32 v[52:53], v[54:55], v[52:53]
	v_add_f32_e32 v59, v72, v59
	v_pk_mul_f32 v[54:55], v[52:53], v[52:53]
	v_add_f32_e32 v59, v73, v59
	v_pk_fma_f32 v[54:55], v[64:65], v[64:65], v[54:55]
	s_nop 0
	v_add_f32_e32 v54, v54, v59
	v_add_f32_e32 v54, v55, v54
	v_cvt_pk_f16_f32 v59, v52, v53
	v_mov_b32_e32 v52, v54
	s_nop 1
	v_permlane16_swap_b32_e32 v52, v54
	global_store_dwordx4 v[70:71], v[56:59], off offset:256
	s_waitcnt lgkmcnt(0)
	v_add_f32_e32 v52, v54, v52
	v_mov_b32_e32 v53, v52
	s_nop 1
	v_permlane32_swap_b32_e32 v53, v52
	s_and_saveexec_b64 s[22:23], s[6:7]
	s_cbranch_execz .LBB0_2391
	s_waitcnt lgkmcnt(0)
	v_add_f32_e32 v54, v52, v53
	v_lshlrev_b64 v[52:53], 6, v[68:69]
	v_lshl_add_u64 v[52:53], s[10:11], 0, v[52:53]
	v_lshl_add_u64 v[52:53], s[20:21], 2, v[52:53]
	s_lshl_b32 s92, s45, 2
	v_lshl_add_u64 v[52:53], v[52:53], 0, s[92:93]
	global_store_dword v[52:53], v54, off
; __device__ __forceinline__ float xor16(float v) { return __int_as_float(__builtin_amdgcn_ds_swizzle(__float_as_int(v), 0x401F)); }
;   __device__ __forceinline__ void operator()(const f32x4 (&acc)[2][2][4][2], const g8::Unit& u, int ui, int wr, int wc, int fr, int fq) const {
; #pragma unroll
;     for (int ai = 0; ai < 2; ++ai)
; #pragma unroll
;       for (int m = 0; m < 4; ++m) {
;         const size_t row = (size_t)u.pm * 256 + 128 * ai + 64 * wr + 16 * m + fr;
;         const size_t base = row * DM + 256 * u.pn + 32 * wc + 8 * fq;
;         float ss = 0.f;
; #pragma unroll
;         for (int bj = 0; bj < 2; ++bj) {
;           const size_t idx = base + 128 * bj;
;           const h16x8 xv = *(const h16x8*)(xb + idx);
;           f32x4 x0 = acc[ai][bj][m][0], x1 = acc[ai][bj][m][1];
; #pragma unroll
;           for (int j = 0; j < 4; ++j) { x0[j] += (float)xv[j]; x1[j] += (float)xv[4 + j]; ss += x0[j] * x0[j] + x1[j] * x1[j]; }
;           if (final_out) {
;             __builtin_nontemporal_store(x0, (f32x4*)(xo + idx));
;             __builtin_nontemporal_store(x1, (f32x4*)(xo + idx + 4));
;           } else {
;             *(h16x8*)(xb + idx) = pack8(x0, x1);
;           }
;         }
;         ss += xor16(ss);
;         ss += __shfl_xor(ss, 32);
;         if (fq == 0) ssq[row * 16 + u.pn * 4 + wc] = ss;
;       }
.LBB0_2391:
	s_or_b64 exec, exec, s[22:23]
	s_mov_b64 s[2:3], 0x90
	s_waitcnt lgkmcnt(0)
	v_lshl_add_u64 v[52:53], v[2:3], 0, s[2:3]
	v_lshlrev_b64 v[54:55], 11, v[52:53]
	v_lshl_add_u64 v[54:55], s[0:1], 0, v[54:55]
	v_lshl_add_u64 v[54:55], v[154:155], 1, v[54:55]
	s_nop 0
	s_waitcnt vmcnt(15)
	v_cvt_f32_f16_e32 v60, v218
	v_cvt_f32_f16_sdwa v61, v218 dst_sel:DWORD dst_unused:UNUSED_PAD src0_sel:WORD_1
	v_cvt_f32_f16_e32 v56, v219
	v_cvt_f32_f16_sdwa v57, v219 dst_sel:DWORD dst_unused:UNUSED_PAD src0_sel:WORD_1
	v_pk_add_f32 v[60:61], v[48:49], v[60:61]
	s_nop 0
	v_cvt_pk_f16_f32 v48, v60, v61
	v_pk_add_f32 v[56:57], v[50:51], v[56:57]
	v_cvt_f32_f16_e32 v50, v220
	v_cvt_f32_f16_sdwa v51, v220 dst_sel:DWORD dst_unused:UNUSED_PAD src0_sel:WORD_1
	v_cvt_f32_f16_e32 v58, v221
	v_cvt_f32_f16_sdwa v59, v221 dst_sel:DWORD dst_unused:UNUSED_PAD src0_sel:WORD_1
	v_cvt_pk_f16_f32 v49, v56, v57
	v_pk_add_f32 v[50:51], v[44:45], v[50:51]
	v_pk_add_f32 v[58:59], v[46:47], v[58:59]
	v_pk_mul_f32 v[44:45], v[50:51], v[50:51]
	v_cvt_pk_f16_f32 v50, v50, v51
	v_cvt_pk_f16_f32 v51, v58, v59
	global_store_dwordx4 v[54:55], v[48:51], off
	s_nop 0
	v_pk_mul_f32 v[46:47], v[58:59], v[58:59]
	v_pk_fma_f32 v[44:45], v[60:61], v[60:61], v[44:45]
	v_pk_fma_f32 v[46:47], v[56:57], v[56:57], v[46:47]
	s_waitcnt vmcnt(15)
	v_cvt_f32_f16_e32 v56, v222
	v_cvt_f32_f16_sdwa v57, v222 dst_sel:DWORD dst_unused:UNUSED_PAD src0_sel:WORD_1
	v_cvt_f32_f16_e32 v48, v223
	v_cvt_f32_f16_sdwa v49, v223 dst_sel:DWORD dst_unused:UNUSED_PAD src0_sel:WORD_1
	v_pk_add_f32 v[56:57], v[40:41], v[56:57]
	s_nop 0
	v_cvt_pk_f16_f32 v40, v56, v57
	v_pk_add_f32 v[48:49], v[42:43], v[48:49]
	v_cvt_f32_f16_e32 v42, v224
	v_cvt_f32_f16_sdwa v43, v224 dst_sel:DWORD dst_unused:UNUSED_PAD src0_sel:WORD_1
	v_cvt_pk_f16_f32 v41, v48, v49
	v_pk_add_f32 v[36:37], v[36:37], v[42:43]
	s_nop 0
	v_pk_mul_f32 v[42:43], v[36:37], v[36:37]
	s_nop 0
	v_pk_fma_f32 v[56:57], v[56:57], v[56:57], v[42:43]
	v_cvt_pk_f16_f32 v42, v36, v37
	v_cvt_f32_f16_e32 v36, v225
	v_cvt_f32_f16_sdwa v37, v225 dst_sel:DWORD dst_unused:UNUSED_PAD src0_sel:WORD_1
	v_add_f32_e32 v43, v44, v45
	v_add_f32_e32 v43, v46, v43
	v_add_f32_e32 v43, v47, v43
	v_pk_add_f32 v[36:37], v[38:39], v[36:37]
	v_add_f32_e32 v43, v56, v43
	v_pk_mul_f32 v[38:39], v[36:37], v[36:37]
	v_add_f32_e32 v43, v57, v43
	v_pk_fma_f32 v[38:39], v[48:49], v[48:49], v[38:39]
	s_nop 0
	v_add_f32_e32 v38, v38, v43
	v_add_f32_e32 v38, v39, v38
	v_cvt_pk_f16_f32 v43, v36, v37
	v_mov_b32_e32 v36, v38
	s_nop 1
	v_permlane16_swap_b32_e32 v36, v38
	global_store_dwordx4 v[54:55], v[40:43], off offset:256
	s_waitcnt lgkmcnt(0)
	v_add_f32_e32 v36, v38, v36
	v_mov_b32_e32 v37, v36
	s_nop 1
	v_permlane32_swap_b32_e32 v37, v36
	s_and_saveexec_b64 s[22:23], s[6:7]
	s_cbranch_execz .LBB0_2393
	s_waitcnt lgkmcnt(0)
	v_add_f32_e32 v38, v36, v37
	v_lshlrev_b64 v[36:37], 6, v[52:53]
	v_lshl_add_u64 v[36:37], s[10:11], 0, v[36:37]
	v_lshl_add_u64 v[36:37], s[20:21], 2, v[36:37]
	s_lshl_b32 s92, s45, 2
	v_lshl_add_u64 v[36:37], v[36:37], 0, s[92:93]
	global_store_dword v[36:37], v38, off
.LBB0_2393:
	s_or_b64 exec, exec, s[22:23]
	s_mov_b64 s[2:3], 0xa0
	s_waitcnt lgkmcnt(0)
	v_lshl_add_u64 v[36:37], v[2:3], 0, s[2:3]
	v_lshlrev_b64 v[38:39], 11, v[36:37]
	v_lshl_add_u64 v[38:39], s[0:1], 0, v[38:39]
	v_lshl_add_u64 v[38:39], v[154:155], 1, v[38:39]
	s_nop 0
	s_waitcnt vmcnt(15)
	v_cvt_f32_f16_e32 v44, v226
	v_cvt_f32_f16_sdwa v45, v226 dst_sel:DWORD dst_unused:UNUSED_PAD src0_sel:WORD_1
	v_cvt_f32_f16_e32 v40, v227
	v_cvt_f32_f16_sdwa v41, v227 dst_sel:DWORD dst_unused:UNUSED_PAD src0_sel:WORD_1
	v_pk_add_f32 v[44:45], v[32:33], v[44:45]
	s_nop 0
	v_cvt_pk_f16_f32 v32, v44, v45
	v_pk_add_f32 v[40:41], v[34:35], v[40:41]
	v_cvt_f32_f16_e32 v34, v228
	v_cvt_f32_f16_sdwa v35, v228 dst_sel:DWORD dst_unused:UNUSED_PAD src0_sel:WORD_1
	v_cvt_f32_f16_e32 v42, v229
	v_cvt_f32_f16_sdwa v43, v229 dst_sel:DWORD dst_unused:UNUSED_PAD src0_sel:WORD_1
	v_cvt_pk_f16_f32 v33, v40, v41
	v_pk_add_f32 v[34:35], v[28:29], v[34:35]
	v_pk_add_f32 v[42:43], v[30:31], v[42:43]
	v_pk_mul_f32 v[28:29], v[34:35], v[34:35]
	v_cvt_pk_f16_f32 v34, v34, v35
	v_cvt_pk_f16_f32 v35, v42, v43
	global_store_dwordx4 v[38:39], v[32:35], off
	s_nop 0
	v_pk_mul_f32 v[30:31], v[42:43], v[42:43]
	v_pk_fma_f32 v[28:29], v[44:45], v[44:45], v[28:29]
	v_pk_fma_f32 v[30:31], v[40:41], v[40:41], v[30:31]
	s_waitcnt vmcnt(15)
	v_cvt_f32_f16_e32 v40, v230
	v_cvt_f32_f16_sdwa v41, v230 dst_sel:DWORD dst_unused:UNUSED_PAD src0_sel:WORD_1
	v_cvt_f32_f16_e32 v32, v231
	v_cvt_f32_f16_sdwa v33, v231 dst_sel:DWORD dst_unused:UNUSED_PAD src0_sel:WORD_1
	v_pk_add_f32 v[40:41], v[24:25], v[40:41]
	s_nop 0
	v_cvt_pk_f16_f32 v24, v40, v41
	v_pk_add_f32 v[32:33], v[26:27], v[32:33]
	v_cvt_f32_f16_e32 v26, v232
	v_cvt_f32_f16_sdwa v27, v232 dst_sel:DWORD dst_unused:UNUSED_PAD src0_sel:WORD_1
	v_cvt_pk_f16_f32 v25, v32, v33
	v_pk_add_f32 v[20:21], v[20:21], v[26:27]
	s_nop 0
	v_pk_mul_f32 v[26:27], v[20:21], v[20:21]
	s_nop 0
	v_pk_fma_f32 v[40:41], v[40:41], v[40:41], v[26:27]
	v_cvt_pk_f16_f32 v26, v20, v21
	v_cvt_f32_f16_e32 v20, v233
	v_cvt_f32_f16_sdwa v21, v233 dst_sel:DWORD dst_unused:UNUSED_PAD src0_sel:WORD_1
	v_add_f32_e32 v27, v28, v29
	v_add_f32_e32 v27, v30, v27
	v_add_f32_e32 v27, v31, v27
	v_pk_add_f32 v[20:21], v[22:23], v[20:21]
	v_add_f32_e32 v27, v40, v27
	v_pk_mul_f32 v[22:23], v[20:21], v[20:21]
	v_add_f32_e32 v27, v41, v27
	v_pk_fma_f32 v[22:23], v[32:33], v[32:33], v[22:23]
	s_nop 0
	v_add_f32_e32 v22, v22, v27
	v_add_f32_e32 v22, v23, v22
	v_cvt_pk_f16_f32 v27, v20, v21
	v_mov_b32_e32 v20, v22
	s_nop 1
	v_permlane16_swap_b32_e32 v20, v22
	global_store_dwordx4 v[38:39], v[24:27], off offset:256
	s_waitcnt lgkmcnt(0)
	v_add_f32_e32 v20, v22, v20
	v_mov_b32_e32 v21, v20
	s_nop 1
	v_permlane32_swap_b32_e32 v21, v20
	s_and_saveexec_b64 s[22:23], s[6:7]
	s_cbranch_execz .LBB0_2395
	s_waitcnt lgkmcnt(0)
	v_add_f32_e32 v22, v20, v21
	v_lshlrev_b64 v[20:21], 6, v[36:37]
	v_lshl_add_u64 v[20:21], s[10:11], 0, v[20:21]
	v_lshl_add_u64 v[20:21], s[20:21], 2, v[20:21]
	s_lshl_b32 s92, s45, 2
	v_lshl_add_u64 v[20:21], v[20:21], 0, s[92:93]
	global_store_dword v[20:21], v22, off

; __device__ __forceinline__ float xor16(float v) { return __int_as_float(__builtin_amdgcn_ds_swizzle(__float_as_int(v), 0x401F)); }
;   __device__ __forceinline__ void operator()(const f32x4 (&acc)[2][2][4][2], const g8::Unit& u, int ui, int wr, int wc, int fr, int fq) const {
;     ...
;           for (int j = 0; j < 4; ++j) { x0[j] += (float)xv[j]; x1[j] += (float)xv[4 + j]; ss += x0[j] * x0[j] + x1[j] * x1[j]; }
;           if (final_out) {
;             __builtin_nontemporal_store(x0, (f32x4*)(xo + idx));
;             __builtin_nontemporal_store(x1, (f32x4*)(xo + idx + 4));
;           } else {
;             *(h16x8*)(xb + idx) = pack8(x0, x1);
;           }
;         }
;         ss += xor16(ss);
;         ss += __shfl_xor(ss, 32);
;         if (fq == 0) ssq[row * 16 + u.pn * 4 + wc] = ss;
.LBB0_2551:
	v_pk_mul_f32 v[122:123], v[122:123], v[122:123]
	v_pk_mul_f32 v[124:125], v[124:125], v[124:125]
	v_pk_fma_f32 v[122:123], v[126:127], v[126:127], v[122:123]
	v_pk_mul_f32 v[114:115], v[114:115], v[114:115]
	v_pk_fma_f32 v[124:125], v[128:129], v[128:129], v[124:125]
	v_pk_fma_f32 v[114:115], v[118:119], v[118:119], v[114:115]
	v_add_f32_e32 v118, v122, v123
	v_add_f32_e32 v118, v124, v118
	v_add_f32_e32 v118, v125, v118
	v_pk_mul_f32 v[116:117], v[116:117], v[116:117]
	v_add_f32_e32 v114, v118, v114
	v_pk_fma_f32 v[116:117], v[120:121], v[120:121], v[116:117]
	v_add_f32_e32 v114, v115, v114
	v_add_f32_e32 v114, v116, v114
	v_add_f32_e32 v114, v117, v114
	v_mov_b32_e32 v117, v114
	s_nop 1
	v_permlane16_swap_b32_e32 v117, v114
	v_and_b32_e32 v116, 64, v199
	v_xor_b32_e32 v115, 32, v199
	v_add_u32_e32 v116, 64, v116
	v_cmp_lt_i32_e32 vcc, v115, v116
	s_waitcnt lgkmcnt(0)
	v_add_f32_e32 v114, v114, v117
	s_lshl_b32 s22, s2, 2
	v_cndmask_b32_e32 v115, v199, v115, vcc
	v_lshlrev_b32_e32 v120, 2, v115
	v_mov_b32_e32 v115, v114
	s_nop 1
	v_permlane32_swap_b32_e32 v115, v114
	s_ashr_i32 s23, s22, 31
	s_and_saveexec_b64 s[24:25], s[4:5]
	s_cbranch_execz .LBB0_2553
	s_waitcnt lgkmcnt(0)
	v_add_f32_e32 v116, v114, v115
	v_lshlrev_b64 v[114:115], 6, v[140:141]
	v_lshl_add_u64 v[114:115], s[12:13], 0, v[114:115]
	v_lshl_add_u64 v[114:115], s[22:23], 2, v[114:115]
	s_lshl_b32 s92, s43, 2
	v_lshl_add_u64 v[114:115], v[114:115], 0, s[92:93]
	global_store_dword v[114:115], v116, off

; __device__ __forceinline__ float xor16(float v) { return __int_as_float(__builtin_amdgcn_ds_swizzle(__float_as_int(v), 0x401F)); }
;   __device__ __forceinline__ void operator()(const f32x4 (&acc)[2][2][4][2], const g8::Unit& u, int ui, int wr, int wc, int fr, int fq) const {
;     ...
;           for (int j = 0; j < 4; ++j) { x0[j] += (float)xv[j]; x1[j] += (float)xv[4 + j]; ss += x0[j] * x0[j] + x1[j] * x1[j]; }
;           if (final_out) {
;             __builtin_nontemporal_store(x0, (f32x4*)(xo + idx));
;             __builtin_nontemporal_store(x1, (f32x4*)(xo + idx + 4));
;           } else {
;             *(h16x8*)(xb + idx) = pack8(x0, x1);
;           }
;         }
;         ss += xor16(ss);
;         ss += __shfl_xor(ss, 32);
;         if (fq == 0) ssq[row * 16 + u.pn * 4 + wc] = ss;
.LBB0_2561:
	v_pk_mul_f32 v[106:107], v[106:107], v[106:107]
	v_pk_mul_f32 v[108:109], v[108:109], v[108:109]
	v_pk_fma_f32 v[106:107], v[110:111], v[110:111], v[106:107]
	v_pk_mul_f32 v[98:99], v[98:99], v[98:99]
	v_pk_fma_f32 v[108:109], v[112:113], v[112:113], v[108:109]
	v_pk_fma_f32 v[98:99], v[102:103], v[102:103], v[98:99]
	v_add_f32_e32 v102, v106, v107
	v_add_f32_e32 v102, v108, v102
	v_add_f32_e32 v102, v109, v102
	v_pk_mul_f32 v[100:101], v[100:101], v[100:101]
	v_add_f32_e32 v98, v102, v98
	v_pk_fma_f32 v[100:101], v[104:105], v[104:105], v[100:101]
	v_add_f32_e32 v98, v99, v98
	v_add_f32_e32 v98, v100, v98
	v_add_f32_e32 v98, v101, v98
	v_mov_b32_e32 v99, v98
	s_nop 1
	v_permlane16_swap_b32_e32 v99, v98
	s_waitcnt lgkmcnt(0)
	v_add_f32_e32 v98, v98, v99
	v_mov_b32_e32 v99, v98
	s_nop 1
	v_permlane32_swap_b32_e32 v99, v98
	s_and_saveexec_b64 s[24:25], s[4:5]
	s_cbranch_execz .LBB0_2563
	s_waitcnt lgkmcnt(0)
	v_add_f32_e32 v100, v98, v99
	v_lshlrev_b64 v[98:99], 6, v[114:115]
	v_lshl_add_u64 v[98:99], s[12:13], 0, v[98:99]
	v_lshl_add_u64 v[98:99], s[22:23], 2, v[98:99]
	s_lshl_b32 s92, s43, 2
	v_lshl_add_u64 v[98:99], v[98:99], 0, s[92:93]
	global_store_dword v[98:99], v100, off

; __device__ __forceinline__ float xor16(float v) { return __int_as_float(__builtin_amdgcn_ds_swizzle(__float_as_int(v), 0x401F)); }
;   __device__ __forceinline__ void operator()(const f32x4 (&acc)[2][2][4][2], const g8::Unit& u, int ui, int wr, int wc, int fr, int fq) const {
;     ...
;           for (int j = 0; j < 4; ++j) { x0[j] += (float)xv[j]; x1[j] += (float)xv[4 + j]; ss += x0[j] * x0[j] + x1[j] * x1[j]; }
;           if (final_out) {
;             __builtin_nontemporal_store(x0, (f32x4*)(xo + idx));
;             __builtin_nontemporal_store(x1, (f32x4*)(xo + idx + 4));
;           } else {
;             *(h16x8*)(xb + idx) = pack8(x0, x1);
;           }
;         }
;         ss += xor16(ss);
;         ss += __shfl_xor(ss, 32);
;         if (fq == 0) ssq[row * 16 + u.pn * 4 + wc] = ss;
.LBB0_2571:
	v_pk_mul_f32 v[90:91], v[90:91], v[90:91]
	v_pk_mul_f32 v[92:93], v[92:93], v[92:93]
	v_pk_fma_f32 v[90:91], v[94:95], v[94:95], v[90:91]
	v_pk_mul_f32 v[82:83], v[82:83], v[82:83]
	v_pk_fma_f32 v[92:93], v[96:97], v[96:97], v[92:93]
	v_pk_fma_f32 v[82:83], v[86:87], v[86:87], v[82:83]
	v_add_f32_e32 v86, v90, v91
	v_add_f32_e32 v86, v92, v86
	v_add_f32_e32 v86, v93, v86
	v_pk_mul_f32 v[84:85], v[84:85], v[84:85]
	v_add_f32_e32 v82, v86, v82
	v_pk_fma_f32 v[84:85], v[88:89], v[88:89], v[84:85]
	v_add_f32_e32 v82, v83, v82
	v_add_f32_e32 v82, v84, v82
	v_add_f32_e32 v82, v85, v82
	v_mov_b32_e32 v83, v82
	s_nop 1
	v_permlane16_swap_b32_e32 v83, v82
	s_waitcnt lgkmcnt(0)
	v_add_f32_e32 v82, v82, v83
	v_mov_b32_e32 v83, v82
	s_nop 1
	v_permlane32_swap_b32_e32 v83, v82
	s_and_saveexec_b64 s[24:25], s[4:5]
	s_cbranch_execz .LBB0_2573
	s_waitcnt lgkmcnt(0)
	v_add_f32_e32 v84, v82, v83
	v_lshlrev_b64 v[82:83], 6, v[98:99]
	v_lshl_add_u64 v[82:83], s[12:13], 0, v[82:83]
	v_lshl_add_u64 v[82:83], s[22:23], 2, v[82:83]
	s_lshl_b32 s92, s43, 2
	v_lshl_add_u64 v[82:83], v[82:83], 0, s[92:93]
	global_store_dword v[82:83], v84, off

; __device__ __forceinline__ float xor16(float v) { return __int_as_float(__builtin_amdgcn_ds_swizzle(__float_as_int(v), 0x401F)); }
;   __device__ __forceinline__ void operator()(const f32x4 (&acc)[2][2][4][2], const g8::Unit& u, int ui, int wr, int wc, int fr, int fq) const {
;     ...
;           for (int j = 0; j < 4; ++j) { x0[j] += (float)xv[j]; x1[j] += (float)xv[4 + j]; ss += x0[j] * x0[j] + x1[j] * x1[j]; }
;           if (final_out) {
;             __builtin_nontemporal_store(x0, (f32x4*)(xo + idx));
;             __builtin_nontemporal_store(x1, (f32x4*)(xo + idx + 4));
;           } else {
;             *(h16x8*)(xb + idx) = pack8(x0, x1);
;           }
;         }
;         ss += xor16(ss);
;         ss += __shfl_xor(ss, 32);
;         if (fq == 0) ssq[row * 16 + u.pn * 4 + wc] = ss;
.LBB0_2581:
	v_pk_mul_f32 v[74:75], v[74:75], v[74:75]
	v_pk_mul_f32 v[76:77], v[76:77], v[76:77]
	v_pk_fma_f32 v[74:75], v[78:79], v[78:79], v[74:75]
	v_pk_mul_f32 v[66:67], v[66:67], v[66:67]
	v_pk_fma_f32 v[76:77], v[80:81], v[80:81], v[76:77]
	v_pk_fma_f32 v[66:67], v[70:71], v[70:71], v[66:67]
	v_add_f32_e32 v70, v74, v75
	v_add_f32_e32 v70, v76, v70
	v_add_f32_e32 v70, v77, v70
	v_pk_mul_f32 v[68:69], v[68:69], v[68:69]
	v_add_f32_e32 v66, v70, v66
	v_pk_fma_f32 v[68:69], v[72:73], v[72:73], v[68:69]
	v_add_f32_e32 v66, v67, v66
	v_add_f32_e32 v66, v68, v66
	v_add_f32_e32 v66, v69, v66
	v_mov_b32_e32 v67, v66
	s_nop 1
	v_permlane16_swap_b32_e32 v67, v66
	s_waitcnt lgkmcnt(0)
	v_add_f32_e32 v66, v66, v67
	v_mov_b32_e32 v67, v66
	s_nop 1
	v_permlane32_swap_b32_e32 v67, v66
	s_and_saveexec_b64 s[24:25], s[4:5]
	s_cbranch_execz .LBB0_2583
	s_waitcnt lgkmcnt(0)
	v_add_f32_e32 v68, v66, v67
	v_lshlrev_b64 v[66:67], 6, v[82:83]
	v_lshl_add_u64 v[66:67], s[12:13], 0, v[66:67]
	v_lshl_add_u64 v[66:67], s[22:23], 2, v[66:67]
	s_lshl_b32 s92, s43, 2
	v_lshl_add_u64 v[66:67], v[66:67], 0, s[92:93]
	global_store_dword v[66:67], v68, off

; __device__ __forceinline__ float xor16(float v) { return __int_as_float(__builtin_amdgcn_ds_swizzle(__float_as_int(v), 0x401F)); }
;   __device__ __forceinline__ void operator()(const f32x4 (&acc)[2][2][4][2], const g8::Unit& u, int ui, int wr, int wc, int fr, int fq) const {
;     ...
;           for (int j = 0; j < 4; ++j) { x0[j] += (float)xv[j]; x1[j] += (float)xv[4 + j]; ss += x0[j] * x0[j] + x1[j] * x1[j]; }
;           if (final_out) {
;             __builtin_nontemporal_store(x0, (f32x4*)(xo + idx));
;             __builtin_nontemporal_store(x1, (f32x4*)(xo + idx + 4));
;           } else {
;             *(h16x8*)(xb + idx) = pack8(x0, x1);
;           }
;         }
;         ss += xor16(ss);
;         ss += __shfl_xor(ss, 32);
;         if (fq == 0) ssq[row * 16 + u.pn * 4 + wc] = ss;
.LBB0_2591:
	v_pk_mul_f32 v[58:59], v[58:59], v[58:59]
	v_pk_mul_f32 v[60:61], v[60:61], v[60:61]
	v_pk_fma_f32 v[58:59], v[62:63], v[62:63], v[58:59]
	v_pk_mul_f32 v[50:51], v[50:51], v[50:51]
	v_pk_fma_f32 v[60:61], v[64:65], v[64:65], v[60:61]
	v_pk_fma_f32 v[50:51], v[54:55], v[54:55], v[50:51]
	v_add_f32_e32 v54, v58, v59
	v_add_f32_e32 v54, v60, v54
	v_add_f32_e32 v54, v61, v54
	v_pk_mul_f32 v[52:53], v[52:53], v[52:53]
	v_add_f32_e32 v50, v54, v50
	v_pk_fma_f32 v[52:53], v[56:57], v[56:57], v[52:53]
	v_add_f32_e32 v50, v51, v50
	v_add_f32_e32 v50, v52, v50
	v_add_f32_e32 v50, v53, v50
	v_mov_b32_e32 v51, v50
	s_nop 1
	v_permlane16_swap_b32_e32 v51, v50
	s_waitcnt lgkmcnt(0)
	v_add_f32_e32 v50, v50, v51
	v_mov_b32_e32 v51, v50
	s_nop 1
	v_permlane32_swap_b32_e32 v51, v50
	s_and_saveexec_b64 s[24:25], s[4:5]
	s_cbranch_execz .LBB0_2593
	s_waitcnt lgkmcnt(0)
	v_add_f32_e32 v52, v50, v51
	v_lshlrev_b64 v[50:51], 6, v[66:67]
	v_lshl_add_u64 v[50:51], s[12:13], 0, v[50:51]
	v_lshl_add_u64 v[50:51], s[22:23], 2, v[50:51]
	s_lshl_b32 s92, s43, 2
	v_lshl_add_u64 v[50:51], v[50:51], 0, s[92:93]
	global_store_dword v[50:51], v52, off

; __device__ __forceinline__ float xor16(float v) { return __int_as_float(__builtin_amdgcn_ds_swizzle(__float_as_int(v), 0x401F)); }
;   __device__ __forceinline__ void operator()(const f32x4 (&acc)[2][2][4][2], const g8::Unit& u, int ui, int wr, int wc, int fr, int fq) const {
;     ...
;           for (int j = 0; j < 4; ++j) { x0[j] += (float)xv[j]; x1[j] += (float)xv[4 + j]; ss += x0[j] * x0[j] + x1[j] * x1[j]; }
;           if (final_out) {
;             __builtin_nontemporal_store(x0, (f32x4*)(xo + idx));
;             __builtin_nontemporal_store(x1, (f32x4*)(xo + idx + 4));
;           } else {
;             *(h16x8*)(xb + idx) = pack8(x0, x1);
;           }
;         }
;         ss += xor16(ss);
;         ss += __shfl_xor(ss, 32);
;         if (fq == 0) ssq[row * 16 + u.pn * 4 + wc] = ss;
.LBB0_2601:
	v_pk_mul_f32 v[42:43], v[42:43], v[42:43]
	v_pk_mul_f32 v[44:45], v[44:45], v[44:45]
	v_pk_fma_f32 v[42:43], v[46:47], v[46:47], v[42:43]
	v_pk_mul_f32 v[34:35], v[34:35], v[34:35]
	v_pk_fma_f32 v[44:45], v[48:49], v[48:49], v[44:45]
	v_pk_fma_f32 v[34:35], v[38:39], v[38:39], v[34:35]
	v_add_f32_e32 v38, v42, v43
	v_add_f32_e32 v38, v44, v38
	v_add_f32_e32 v38, v45, v38
	v_pk_mul_f32 v[36:37], v[36:37], v[36:37]
	v_add_f32_e32 v34, v38, v34
	v_pk_fma_f32 v[36:37], v[40:41], v[40:41], v[36:37]
	v_add_f32_e32 v34, v35, v34
	v_add_f32_e32 v34, v36, v34
	v_add_f32_e32 v34, v37, v34
	v_mov_b32_e32 v35, v34
	s_nop 1
	v_permlane16_swap_b32_e32 v35, v34
	s_waitcnt lgkmcnt(0)
	v_add_f32_e32 v34, v34, v35
	v_mov_b32_e32 v35, v34
	s_nop 1
	v_permlane32_swap_b32_e32 v35, v34
	s_and_saveexec_b64 s[24:25], s[4:5]
	s_cbranch_execz .LBB0_2603
	s_waitcnt lgkmcnt(0)
	v_add_f32_e32 v36, v34, v35
	v_lshlrev_b64 v[34:35], 6, v[50:51]
	v_lshl_add_u64 v[34:35], s[12:13], 0, v[34:35]
	v_lshl_add_u64 v[34:35], s[22:23], 2, v[34:35]
	s_lshl_b32 s92, s43, 2
	v_lshl_add_u64 v[34:35], v[34:35], 0, s[92:93]
	global_store_dword v[34:35], v36, off

; __device__ __forceinline__ float xor16(float v) { return __int_as_float(__builtin_amdgcn_ds_swizzle(__float_as_int(v), 0x401F)); }
;   __device__ __forceinline__ void operator()(const f32x4 (&acc)[2][2][4][2], const g8::Unit& u, int ui, int wr, int wc, int fr, int fq) const {
;     ...
;           for (int j = 0; j < 4; ++j) { x0[j] += (float)xv[j]; x1[j] += (float)xv[4 + j]; ss += x0[j] * x0[j] + x1[j] * x1[j]; }
;           if (final_out) {
;             __builtin_nontemporal_store(x0, (f32x4*)(xo + idx));
;             __builtin_nontemporal_store(x1, (f32x4*)(xo + idx + 4));
;           } else {
;             *(h16x8*)(xb + idx) = pack8(x0, x1);
;           }
;         }
;         ss += xor16(ss);
;         ss += __shfl_xor(ss, 32);
;         if (fq == 0) ssq[row * 16 + u.pn * 4 + wc] = ss;
.LBB0_2611:
	v_pk_mul_f32 v[26:27], v[26:27], v[26:27]
	v_pk_mul_f32 v[28:29], v[28:29], v[28:29]
	v_pk_fma_f32 v[26:27], v[30:31], v[30:31], v[26:27]
	v_pk_mul_f32 v[18:19], v[18:19], v[18:19]
	v_pk_fma_f32 v[28:29], v[32:33], v[32:33], v[28:29]
	v_pk_fma_f32 v[18:19], v[22:23], v[22:23], v[18:19]
	v_add_f32_e32 v22, v26, v27
	v_add_f32_e32 v22, v28, v22
	v_add_f32_e32 v22, v29, v22
	v_pk_mul_f32 v[20:21], v[20:21], v[20:21]
	v_add_f32_e32 v18, v22, v18
	v_pk_fma_f32 v[20:21], v[24:25], v[24:25], v[20:21]
	v_add_f32_e32 v18, v19, v18
	v_add_f32_e32 v18, v20, v18
	v_add_f32_e32 v18, v21, v18
	v_mov_b32_e32 v19, v18
	s_nop 1
	v_permlane16_swap_b32_e32 v19, v18
	s_waitcnt lgkmcnt(0)
	v_add_f32_e32 v18, v18, v19
	v_mov_b32_e32 v19, v18
	s_nop 1
	v_permlane32_swap_b32_e32 v19, v18
	s_and_saveexec_b64 s[24:25], s[4:5]
	s_cbranch_execz .LBB0_2613
	s_waitcnt lgkmcnt(0)
	v_add_f32_e32 v20, v18, v19
	v_lshlrev_b64 v[18:19], 6, v[34:35]
	v_lshl_add_u64 v[18:19], s[12:13], 0, v[18:19]
	v_lshl_add_u64 v[18:19], s[22:23], 2, v[18:19]
	s_lshl_b32 s92, s43, 2
	v_lshl_add_u64 v[18:19], v[18:19], 0, s[92:93]
	global_store_dword v[18:19], v20, off

; __device__ __forceinline__ float xor16(float v) { return __int_as_float(__builtin_amdgcn_ds_swizzle(__float_as_int(v), 0x401F)); }
; template <class Epi>
; __device__ __forceinline__ void gemm_phase(LAS unsigned char* lds, const h16* A, const h16* Bt, int K, const Order& S, const Epi& E) {
;     ...
;     E(acc, cur, ui, wr, wc, fr, fq);
;     if (!has_next) break;
;   __device__ __forceinline__ void operator()(const f32x4 (&acc)[2][2][4][2], const g8::Unit& u, int ui, int wr, int wc, int fr, int fq) const {
;     ...
;           for (int j = 0; j < 4; ++j) { x0[j] += (float)xv[j]; x1[j] += (float)xv[4 + j]; ss += x0[j] * x0[j] + x1[j] * x1[j]; }
;           if (final_out) {
;             __builtin_nontemporal_store(x0, (f32x4*)(xo + idx));
;             __builtin_nontemporal_store(x1, (f32x4*)(xo + idx + 4));
;           } else {
;             *(h16x8*)(xb + idx) = pack8(x0, x1);
;           }
;         }
;         ss += xor16(ss);
;         ss += __shfl_xor(ss, 32);
;         if (fq == 0) ssq[row * 16 + u.pn * 4 + wc] = ss;
.LBB0_2621:
	v_pk_mul_f32 v[10:11], v[10:11], v[10:11]
	v_pk_mul_f32 v[12:13], v[12:13], v[12:13]
	v_pk_fma_f32 v[10:11], v[14:15], v[14:15], v[10:11]
	v_pk_mul_f32 v[2:3], v[2:3], v[2:3]
	v_pk_fma_f32 v[12:13], v[16:17], v[16:17], v[12:13]
	v_pk_fma_f32 v[2:3], v[6:7], v[6:7], v[2:3]
	v_add_f32_e32 v6, v10, v11
	v_add_f32_e32 v6, v12, v6
	v_add_f32_e32 v6, v13, v6
	v_pk_mul_f32 v[4:5], v[4:5], v[4:5]
	v_add_f32_e32 v2, v6, v2
	v_pk_fma_f32 v[4:5], v[8:9], v[8:9], v[4:5]
	v_add_f32_e32 v2, v3, v2
	v_add_f32_e32 v2, v4, v2
	v_add_f32_e32 v2, v5, v2
	v_mov_b32_e32 v3, v2
	s_nop 1
	v_permlane16_swap_b32_e32 v3, v2
	s_waitcnt lgkmcnt(0)
	v_add_f32_e32 v2, v2, v3
	v_mov_b32_e32 v3, v2
	s_nop 1
	v_permlane32_swap_b32_e32 v3, v2
	s_and_saveexec_b64 s[8:9], s[4:5]
	s_cbranch_execz .LBB0_2534
	s_waitcnt lgkmcnt(0)
	v_add_f32_e32 v4, v2, v3
	v_lshlrev_b64 v[2:3], 6, v[18:19]
	v_lshl_add_u64 v[2:3], s[12:13], 0, v[2:3]
	v_lshl_add_u64 v[2:3], s[22:23], 2, v[2:3]
	s_lshl_b32 s92, s43, 2
	v_lshl_add_u64 v[2:3], v[2:3], 0, s[92:93]
	global_store_dword v[2:3], v4, off
	s_branch .LBB0_2534
